# GEMM phases: first K-loop trip peeled with epilogue-store-aware counted vmcnt waits (6 of 9 GEMMs)
# baseline (speedup 1.0000x reference)
; #define PG8_STAGE(bufoff, gbase, voff) do { _Pragma("unroll") for (int _i = 0; _i < 2; ++_i) \
;         __builtin_amdgcn_global_load_lds((const unsigned*)((const char*)(gbase) + (voff)[_i]), (PG8_LAS unsigned*)(lds + (bufoff) + ldsw + _i * 8192), 16, 0, 0); } while (0)
; #define PG8_LDA(dst, b, h) do { _Pragma("unroll") for (int m = 0; m < 4; ++m) _Pragma("unroll") for (int k = 0; k < 2; ++k) dst[m][k] = *(const PG8_LAS bf16x8*)(lds + PG8_SA(b, h) + aoff + m * 2048 + k * 1024); } while (0)
; #define PG8_LDB(dst, b, h) do { _Pragma("unroll") for (int n = 0; n < 2; ++n) _Pragma("unroll") for (int k = 0; k < 2; ++k) dst[n][k] = *(const PG8_LAS bf16x8*)(lds + PG8_SB(b, h) + boff + n * 2048 + k * 1024); } while (0)
; #define PG8_SCHED __builtin_amdgcn_sched_barrier(0)
; template <class Epi, class Sched, bool ALIGN_EPI = false, bool SP2 = false>
; __device__ __forceinline__ void gemm_phase(PG8_LAS unsigned char* lds, const Gemm g, const Sched& S, const Epi& E) {
;     ...
;         const bool has_next = S.next(ui + 1, nxt);
;         const char* nA = has_next ? (const char*)g.A + (size_t)nxt.pm * tstep : cA; const char* nB = has_next ? (const char*)g.Bt + (size_t)nxt.pn * tstep : cB;
; #pragma nounroll
;         for (int t = 0; t < nt; t += 2) {
;             const bool last = (t == nt - 2);
;             const char* a1 = cA + (size_t)(t + 1) * kstep;
;             const char* a2 = last ? nA : cA + (size_t)(t + 2) * kstep; const char* b2 = last ? nB : cB + (size_t)(t + 2) * kstep;
;             const char* a3 = a2 + kstep; const char* b3 = b2 + kstep;
;             if (last && has_next) S.a_ready(nxt);
;             if constexpr (SP2) {
;             PG8_LDB(B0, 0, 0); PG8_LDB(B1, 0, 1); PG8_SCHED; PG8_LDA(At, 0, 0); PG8_STAGE(PG8_SA(1, 1), a1 + hstep, voffA);
;     ...
; #pragma unroll
;         for (int a = 0; a < 2; ++a)
; #pragma unroll
;             for (int b = 0; b < 2; ++b)
; #pragma unroll
;                 for (int m = 0; m < 4; ++m)
; #pragma unroll
;                     for (int n = 0; n < 2; ++n) acc[a][b][m][n] = (f32x4){0.f, 0.f, 0.f, 0.f};
.LBB0_490:
	s_ashr_i32 s11, s10, 31
	s_lshl_b64 s[12:13], s[10:11], 19
	s_add_u32 s12, s24, s12
	s_addc_u32 s13, s25, s13
	s_and_b64 s[14:15], s[2:3], exec
	s_cselect_b32 s11, s13, s19
	s_cselect_b32 s52, s12, s18
	s_ashr_i32 s9, s8, 31
	s_lshl_b64 s[14:15], s[8:9], 19
	s_add_u32 s14, s26, s14
	s_addc_u32 s15, s27, s15
	s_and_b64 s[22:23], s[2:3], exec
	s_cselect_b32 s9, s15, s21
	s_cselect_b32 s53, s14, s20
	s_add_u32 s18, s18, 0x40080
	s_addc_u32 s19, s19, 0
	s_add_u32 s56, s20, 0x100
	v_mov_b32_e32 v2, 0
	s_addc_u32 s57, s21, 0
	s_mov_b32 s60, -2
	v_mov_b32_e32 v3, v2
	v_mov_b32_e32 v4, v2
	v_mov_b32_e32 v5, v2
	v_mov_b32_e32 v6, v2
	v_mov_b32_e32 v7, v2
	v_mov_b32_e32 v8, v2
	v_mov_b32_e32 v9, v2
	v_mov_b32_e32 v14, v2
	v_mov_b32_e32 v15, v2
	v_mov_b32_e32 v16, v2
	v_mov_b32_e32 v17, v2
	v_mov_b32_e32 v22, v2
	v_mov_b32_e32 v23, v2
	v_mov_b32_e32 v24, v2
	v_mov_b32_e32 v25, v2
	v_mov_b32_e32 v30, v2
	v_mov_b32_e32 v31, v2
	v_mov_b32_e32 v32, v2
	v_mov_b32_e32 v33, v2
	v_mov_b32_e32 v38, v2
	v_mov_b32_e32 v39, v2
	v_mov_b32_e32 v40, v2
	v_mov_b32_e32 v41, v2
	v_mov_b32_e32 v46, v2
	v_mov_b32_e32 v47, v2
	v_mov_b32_e32 v48, v2
	v_mov_b32_e32 v49, v2
	v_mov_b32_e32 v54, v2
	v_mov_b32_e32 v55, v2
	v_mov_b32_e32 v56, v2
	v_mov_b32_e32 v57, v2
	v_mov_b32_e32 v10, v2
	v_mov_b32_e32 v11, v2
	v_mov_b32_e32 v12, v2
	v_mov_b32_e32 v13, v2
	v_mov_b32_e32 v18, v2
	v_mov_b32_e32 v19, v2
	v_mov_b32_e32 v20, v2
	v_mov_b32_e32 v21, v2
	v_mov_b32_e32 v26, v2
	v_mov_b32_e32 v27, v2
	v_mov_b32_e32 v28, v2
	v_mov_b32_e32 v29, v2
	v_mov_b32_e32 v34, v2
	v_mov_b32_e32 v35, v2
	v_mov_b32_e32 v36, v2
	v_mov_b32_e32 v37, v2
	v_mov_b32_e32 v42, v2
	v_mov_b32_e32 v43, v2
	v_mov_b32_e32 v44, v2
	v_mov_b32_e32 v45, v2
	v_mov_b32_e32 v50, v2
	v_mov_b32_e32 v51, v2
	v_mov_b32_e32 v52, v2
	v_mov_b32_e32 v53, v2
	v_mov_b32_e32 v58, v2
	v_mov_b32_e32 v59, v2
	v_mov_b32_e32 v60, v2
	v_mov_b32_e32 v61, v2
	v_mov_b32_e32 v62, v2
	v_mov_b32_e32 v63, v2
	v_mov_b32_e32 v64, v2
	v_mov_b32_e32 v65, v2
	v_mov_b32_e32 v66, v2
	v_mov_b32_e32 v67, v2
	v_mov_b32_e32 v68, v2
	v_mov_b32_e32 v69, v2
	v_mov_b32_e32 v70, v2
	v_mov_b32_e32 v71, v2
	v_mov_b32_e32 v72, v2
	v_mov_b32_e32 v73, v2
	v_mov_b32_e32 v78, v2
	v_mov_b32_e32 v79, v2
	v_mov_b32_e32 v80, v2
	v_mov_b32_e32 v81, v2
	v_mov_b32_e32 v86, v2
	v_mov_b32_e32 v87, v2
	v_mov_b32_e32 v88, v2
	v_mov_b32_e32 v89, v2
	v_mov_b32_e32 v94, v2
	v_mov_b32_e32 v95, v2
	v_mov_b32_e32 v96, v2
	v_mov_b32_e32 v97, v2
	v_mov_b32_e32 v102, v2
	v_mov_b32_e32 v103, v2
	v_mov_b32_e32 v104, v2
	v_mov_b32_e32 v105, v2
	v_mov_b32_e32 v110, v2
	v_mov_b32_e32 v111, v2
	v_mov_b32_e32 v112, v2
	v_mov_b32_e32 v113, v2
	v_mov_b32_e32 v118, v2
	v_mov_b32_e32 v119, v2
	v_mov_b32_e32 v120, v2
	v_mov_b32_e32 v121, v2
	v_mov_b32_e32 v74, v2
	v_mov_b32_e32 v75, v2
	v_mov_b32_e32 v76, v2
	v_mov_b32_e32 v77, v2
	v_mov_b32_e32 v82, v2
	v_mov_b32_e32 v83, v2
	v_mov_b32_e32 v84, v2
	v_mov_b32_e32 v85, v2
	v_mov_b32_e32 v90, v2
	v_mov_b32_e32 v91, v2
	v_mov_b32_e32 v92, v2
	v_mov_b32_e32 v93, v2
	v_mov_b32_e32 v98, v2
	v_mov_b32_e32 v99, v2
	v_mov_b32_e32 v100, v2
	v_mov_b32_e32 v101, v2
	v_mov_b32_e32 v106, v2
	v_mov_b32_e32 v107, v2
	v_mov_b32_e32 v108, v2
	v_mov_b32_e32 v109, v2
	v_mov_b32_e32 v114, v2
	v_mov_b32_e32 v115, v2
	v_mov_b32_e32 v116, v2
	v_mov_b32_e32 v117, v2
	v_mov_b32_e32 v122, v2
	v_mov_b32_e32 v123, v2
	v_mov_b32_e32 v124, v2
	v_mov_b32_e32 v125, v2
	v_mov_b32_e32 v126, v2
	v_mov_b32_e32 v127, v2
	v_mov_b32_e32 v128, v2
	v_mov_b32_e32 v129, v2
	ds_read_b128 v[156:159], v151
	ds_read_b128 v[160:163], v151 offset:1024
	ds_read_b128 v[164:167], v151 offset:2048
	ds_read_b128 v[168:171], v151 offset:3072
	ds_read_b128 v[174:177], v152
	ds_read_b128 v[178:181], v152 offset:1024
	ds_read_b128 v[182:185], v152 offset:2048
	ds_read_b128 v[186:189], v152 offset:3072
	s_add_u32 s20, s18, 0xfffc0080
	s_addc_u32 s21, s19, -1
	s_cmp_eq_u32 s60, 12
	s_cselect_b32 s23, s11, s21
	s_cselect_b32 s22, s52, s20
	s_cselect_b32 s21, s9, s57
	s_cselect_b32 s20, s53, s56

; #define PG8_STAGE(bufoff, gbase, voff) do { _Pragma("unroll") for (int _i = 0; _i < 2; ++_i) \
;         __builtin_amdgcn_global_load_lds((const unsigned*)((const char*)(gbase) + (voff)[_i]), (PG8_LAS unsigned*)(lds + (bufoff) + ldsw + _i * 8192), 16, 0, 0); } while (0)
; #define PG8_LDA(dst, b, h) do { _Pragma("unroll") for (int m = 0; m < 4; ++m) _Pragma("unroll") for (int k = 0; k < 2; ++k) dst[m][k] = *(const PG8_LAS bf16x8*)(lds + PG8_SA(b, h) + aoff + m * 2048 + k * 1024); } while (0)
; #define PG8_LDB(dst, b, h) do { _Pragma("unroll") for (int n = 0; n < 2; ++n) _Pragma("unroll") for (int k = 0; k < 2; ++k) dst[n][k] = *(const PG8_LAS bf16x8*)(lds + PG8_SB(b, h) + boff + n * 2048 + k * 1024); } while (0)
; #define PG8_MMA(ai, bj, At, Bt) do { __builtin_amdgcn_s_setprio(1); _Pragma("unroll") for (int m = 0; m < 4; ++m) _Pragma("unroll") for (int n = 0; n < 2; ++n) _Pragma("unroll") for (int k = 0; k < 2; ++k) \
;         acc[ai][bj][m][n] = __builtin_amdgcn_mfma_f32_16x16x32_bf16(Bt[n][k], At[m][k], acc[ai][bj][m][n], 0, 0, 0); __builtin_amdgcn_s_setprio(0); } while (0)
; #define PG8_WAIT_V(n) asm volatile("s_waitcnt vmcnt(" #n ")" ::: "memory")
; #define PG8_WAIT_L(n) asm volatile("s_waitcnt lgkmcnt(" #n ")" ::: "memory")
; #define PG8_BAR __builtin_amdgcn_s_barrier()
; #define PG8_SCHED __builtin_amdgcn_sched_barrier(0)
; template <class Epi, class Sched, bool ALIGN_EPI = false, bool SP2 = false>
; __device__ __forceinline__ void gemm_phase(PG8_LAS unsigned char* lds, const Gemm g, const Sched& S, const Epi& E) {
;     ...
;             PG8_LDB(B0, 0, 0); PG8_LDB(B1, 0, 1); PG8_SCHED; PG8_LDA(At, 0, 0); PG8_STAGE(PG8_SA(1, 1), a1 + hstep, voffA);
;             PG8_WAIT_V(8); PG8_WAIT_L(0); PG8_BAR; PG8_MMA(0, 0, At, B0); PG8_MMA(0, 1, At, B1); PG8_BAR; PG8_SCHED;
	v_lshl_add_u64 v[222:223], s[18:19], 0, v[142:143]
	s_add_i32 m0, s31, 0xc000
	ds_read_b128 v[190:193], v153
	ds_read_b128 v[194:197], v153 offset:1024
	ds_read_b128 v[198:201], v153 offset:2048
	ds_read_b128 v[202:205], v153 offset:3072
	ds_read_b128 v[206:209], v153 offset:4096
	ds_read_b128 v[210:213], v153 offset:5120
	ds_read_b128 v[214:217], v153 offset:6144
	ds_read_b128 v[218:221], v153 offset:7168
	global_load_lds_dwordx4 v[222:223], off
	v_lshl_add_u64 v[222:223], s[18:19], 0, v[144:145]
	s_add_i32 m0, s31, 0xe000
	s_nop 0
	global_load_lds_dwordx4 v[222:223], off
	s_waitcnt vmcnt(24)
	s_waitcnt lgkmcnt(0)
	s_barrier
	s_setprio 1
	s_waitcnt lgkmcnt(0)
	v_mfma_f32_16x16x32_bf16 v[126:129], v[156:159], v[190:193], v[126:129]
	v_mfma_f32_16x16x32_bf16 v[122:125], v[164:167], v[190:193], v[122:125]
	v_mfma_f32_16x16x32_bf16 v[114:117], v[156:159], v[198:201], v[114:117]
	v_mfma_f32_16x16x32_bf16 v[106:109], v[164:167], v[198:201], v[106:109]
	v_mfma_f32_16x16x32_bf16 v[98:101], v[156:159], v[206:209], v[98:101]
	v_mfma_f32_16x16x32_bf16 v[90:93], v[164:167], v[206:209], v[90:93]
	v_mfma_f32_16x16x32_bf16 v[82:85], v[156:159], v[214:217], v[82:85]
	v_mfma_f32_16x16x32_bf16 v[74:77], v[164:167], v[214:217], v[74:77]
	v_mfma_f32_16x16x32_bf16 v[126:129], v[160:163], v[194:197], v[126:129]
	v_mfma_f32_16x16x32_bf16 v[122:125], v[168:171], v[194:197], v[122:125]
	v_mfma_f32_16x16x32_bf16 v[114:117], v[160:163], v[202:205], v[114:117]
	v_mfma_f32_16x16x32_bf16 v[106:109], v[168:171], v[202:205], v[106:109]
	v_mfma_f32_16x16x32_bf16 v[98:101], v[160:163], v[210:213], v[98:101]
	v_mfma_f32_16x16x32_bf16 v[90:93], v[168:171], v[210:213], v[90:93]
	v_mfma_f32_16x16x32_bf16 v[82:85], v[160:163], v[218:221], v[82:85]
	v_mfma_f32_16x16x32_bf16 v[74:77], v[168:171], v[218:221], v[74:77]
	s_setprio 0
	s_setprio 1
	v_mfma_f32_16x16x32_bf16 v[118:121], v[174:177], v[190:193], v[118:121]
	v_mfma_f32_16x16x32_bf16 v[110:113], v[182:185], v[190:193], v[110:113]
	v_mfma_f32_16x16x32_bf16 v[102:105], v[174:177], v[198:201], v[102:105]
	v_mfma_f32_16x16x32_bf16 v[94:97], v[182:185], v[198:201], v[94:97]
	v_mfma_f32_16x16x32_bf16 v[86:89], v[174:177], v[206:209], v[86:89]
	v_mfma_f32_16x16x32_bf16 v[78:81], v[182:185], v[206:209], v[78:81]
	v_mfma_f32_16x16x32_bf16 v[70:73], v[174:177], v[214:217], v[70:73]
	v_mfma_f32_16x16x32_bf16 v[66:69], v[182:185], v[214:217], v[66:69]
	v_mfma_f32_16x16x32_bf16 v[118:121], v[178:181], v[194:197], v[118:121]
	v_mfma_f32_16x16x32_bf16 v[110:113], v[186:189], v[194:197], v[110:113]
	v_mfma_f32_16x16x32_bf16 v[102:105], v[178:181], v[202:205], v[102:105]
	v_mfma_f32_16x16x32_bf16 v[94:97], v[186:189], v[202:205], v[94:97]
	v_mfma_f32_16x16x32_bf16 v[86:89], v[178:181], v[210:213], v[86:89]
	v_mfma_f32_16x16x32_bf16 v[78:81], v[186:189], v[210:213], v[78:81]
	v_mfma_f32_16x16x32_bf16 v[70:73], v[178:181], v[218:221], v[70:73]
	v_mfma_f32_16x16x32_bf16 v[66:69], v[186:189], v[218:221], v[66:69]
	s_setprio 0
	s_barrier

; #define PG8_STAGE(bufoff, gbase, voff) do { _Pragma("unroll") for (int _i = 0; _i < 2; ++_i) \
;         __builtin_amdgcn_global_load_lds((const unsigned*)((const char*)(gbase) + (voff)[_i]), (PG8_LAS unsigned*)(lds + (bufoff) + ldsw + _i * 8192), 16, 0, 0); } while (0)
; #define PG8_LDA(dst, b, h) do { _Pragma("unroll") for (int m = 0; m < 4; ++m) _Pragma("unroll") for (int k = 0; k < 2; ++k) dst[m][k] = *(const PG8_LAS bf16x8*)(lds + PG8_SA(b, h) + aoff + m * 2048 + k * 1024); } while (0)
; #define PG8_MMA(ai, bj, At, Bt) do { __builtin_amdgcn_s_setprio(1); _Pragma("unroll") for (int m = 0; m < 4; ++m) _Pragma("unroll") for (int n = 0; n < 2; ++n) _Pragma("unroll") for (int k = 0; k < 2; ++k) \
;         acc[ai][bj][m][n] = __builtin_amdgcn_mfma_f32_16x16x32_bf16(Bt[n][k], At[m][k], acc[ai][bj][m][n], 0, 0, 0); __builtin_amdgcn_s_setprio(0); } while (0)
; #define PG8_WAIT_V(n) asm volatile("s_waitcnt vmcnt(" #n ")" ::: "memory")
; #define PG8_WAIT_L(n) asm volatile("s_waitcnt lgkmcnt(" #n ")" ::: "memory")
; #define PG8_BAR __builtin_amdgcn_s_barrier()
; #define PG8_SCHED __builtin_amdgcn_sched_barrier(0)
; template <class Epi, class Sched, bool ALIGN_EPI = false, bool SP2 = false>
; __device__ __forceinline__ void gemm_phase(PG8_LAS unsigned char* lds, const Gemm g, const Sched& S, const Epi& E) {
;     ...
;             PG8_LDA(At, 0, 1); PG8_STAGE(PG8_SB(0, 0), b2, voffB); PG8_STAGE(PG8_SB(0, 1), b2 + hstep, voffB); PG8_STAGE(PG8_SA(0, 0), a2, voffA);
;             PG8_WAIT_V(8); PG8_WAIT_L(0); PG8_BAR; PG8_MMA(1, 0, At, B0); PG8_MMA(1, 1, At, B1); PG8_BAR; PG8_SCHED;
	s_add_i32 s61, s44, s28
	v_lshl_add_u64 v[222:223], s[20:21], 0, v[134:135]
	s_mov_b32 m0, s61
	ds_read_b128 v[190:193], v153 offset:16384
	ds_read_b128 v[194:197], v153 offset:17408
	ds_read_b128 v[198:201], v153 offset:18432
	ds_read_b128 v[202:205], v153 offset:19456
	ds_read_b128 v[206:209], v153 offset:20480
	ds_read_b128 v[210:213], v153 offset:21504
	ds_read_b128 v[214:217], v153 offset:22528
	ds_read_b128 v[218:221], v153 offset:23552
	global_load_lds_dwordx4 v[222:223], off
	s_add_i32 m0, s61, 0x2000
	s_add_u32 s62, s20, 0x40000
	v_lshl_add_u64 v[224:225], s[20:21], 0, v[130:131]
	s_addc_u32 s63, s21, 0
	s_add_i32 s61, s45, s28
	global_load_lds_dwordx4 v[224:225], off
	v_lshl_add_u64 v[226:227], s[62:63], 0, v[134:135]
	s_mov_b32 m0, s61
	v_lshl_add_u64 v[228:229], s[22:23], 0, v[132:133]
	global_load_lds_dwordx4 v[226:227], off
	v_lshl_add_u64 v[226:227], s[62:63], 0, v[130:131]
	s_add_i32 m0, s61, 0x2000
	s_nop 0
	global_load_lds_dwordx4 v[226:227], off
	v_lshl_add_u64 v[226:227], s[22:23], 0, v[136:137]
	s_mov_b32 m0, s31
	s_nop 0
	global_load_lds_dwordx4 v[226:227], off
	s_mov_b32 m0, s33
	s_nop 0
	global_load_lds_dwordx4 v[228:229], off
	s_waitcnt vmcnt(24)
	s_waitcnt lgkmcnt(0)
	s_barrier
	s_setprio 1
	s_waitcnt lgkmcnt(0)
	v_mfma_f32_16x16x32_bf16 v[62:65], v[156:159], v[190:193], v[62:65]
	v_mfma_f32_16x16x32_bf16 v[58:61], v[164:167], v[190:193], v[58:61]
	v_mfma_f32_16x16x32_bf16 v[50:53], v[156:159], v[198:201], v[50:53]
	v_mfma_f32_16x16x32_bf16 v[42:45], v[164:167], v[198:201], v[42:45]
	v_mfma_f32_16x16x32_bf16 v[34:37], v[156:159], v[206:209], v[34:37]
	v_mfma_f32_16x16x32_bf16 v[26:29], v[164:167], v[206:209], v[26:29]
	v_mfma_f32_16x16x32_bf16 v[18:21], v[156:159], v[214:217], v[18:21]
	v_mfma_f32_16x16x32_bf16 v[10:13], v[164:167], v[214:217], v[10:13]
	v_mfma_f32_16x16x32_bf16 v[62:65], v[160:163], v[194:197], v[62:65]
	v_mfma_f32_16x16x32_bf16 v[58:61], v[168:171], v[194:197], v[58:61]
	v_mfma_f32_16x16x32_bf16 v[50:53], v[160:163], v[202:205], v[50:53]
	v_mfma_f32_16x16x32_bf16 v[42:45], v[168:171], v[202:205], v[42:45]
	v_mfma_f32_16x16x32_bf16 v[34:37], v[160:163], v[210:213], v[34:37]
	v_mfma_f32_16x16x32_bf16 v[26:29], v[168:171], v[210:213], v[26:29]
	v_mfma_f32_16x16x32_bf16 v[18:21], v[160:163], v[218:221], v[18:21]
	v_mfma_f32_16x16x32_bf16 v[10:13], v[168:171], v[218:221], v[10:13]
	s_setprio 0
	s_setprio 1
	v_mfma_f32_16x16x32_bf16 v[54:57], v[174:177], v[190:193], v[54:57]
	v_mfma_f32_16x16x32_bf16 v[46:49], v[182:185], v[190:193], v[46:49]
	v_mfma_f32_16x16x32_bf16 v[38:41], v[174:177], v[198:201], v[38:41]
	v_mfma_f32_16x16x32_bf16 v[30:33], v[182:185], v[198:201], v[30:33]
	v_mfma_f32_16x16x32_bf16 v[22:25], v[174:177], v[206:209], v[22:25]
	v_mfma_f32_16x16x32_bf16 v[14:17], v[182:185], v[206:209], v[14:17]
	v_mfma_f32_16x16x32_bf16 v[6:9], v[174:177], v[214:217], v[6:9]
	v_mfma_f32_16x16x32_bf16 v[2:5], v[182:185], v[214:217], v[2:5]
	v_mfma_f32_16x16x32_bf16 v[54:57], v[178:181], v[194:197], v[54:57]
	v_mfma_f32_16x16x32_bf16 v[46:49], v[186:189], v[194:197], v[46:49]
	v_mfma_f32_16x16x32_bf16 v[38:41], v[178:181], v[202:205], v[38:41]
	v_mfma_f32_16x16x32_bf16 v[30:33], v[186:189], v[202:205], v[30:33]
	v_mfma_f32_16x16x32_bf16 v[22:25], v[178:181], v[210:213], v[22:25]
	v_mfma_f32_16x16x32_bf16 v[14:17], v[186:189], v[210:213], v[14:17]
	v_mfma_f32_16x16x32_bf16 v[6:9], v[178:181], v[218:221], v[6:9]
	v_mfma_f32_16x16x32_bf16 v[2:5], v[186:189], v[218:221], v[2:5]
	s_setprio 0
	s_barrier

; #define PG8_STAGE(bufoff, gbase, voff) do { _Pragma("unroll") for (int _i = 0; _i < 2; ++_i) \
;         __builtin_amdgcn_global_load_lds((const unsigned*)((const char*)(gbase) + (voff)[_i]), (PG8_LAS unsigned*)(lds + (bufoff) + ldsw + _i * 8192), 16, 0, 0); } while (0)
; #define PG8_LDA(dst, b, h) do { _Pragma("unroll") for (int m = 0; m < 4; ++m) _Pragma("unroll") for (int k = 0; k < 2; ++k) dst[m][k] = *(const PG8_LAS bf16x8*)(lds + PG8_SA(b, h) + aoff + m * 2048 + k * 1024); } while (0)
; #define PG8_LDB(dst, b, h) do { _Pragma("unroll") for (int n = 0; n < 2; ++n) _Pragma("unroll") for (int k = 0; k < 2; ++k) dst[n][k] = *(const PG8_LAS bf16x8*)(lds + PG8_SB(b, h) + boff + n * 2048 + k * 1024); } while (0)
; #define PG8_SCHED __builtin_amdgcn_sched_barrier(0)
; template <class Epi, class Sched, bool ALIGN_EPI = false, bool SP2 = false>
; __device__ __forceinline__ void gemm_phase(PG8_LAS unsigned char* lds, const Gemm g, const Sched& S, const Epi& E) {
;     ...
;             PG8_LDB(B0, 1, 0); PG8_LDB(B1, 1, 1); PG8_SCHED; PG8_LDA(At, 1, 0); PG8_STAGE(PG8_SA(0, 1), a2 + hstep, voffA);
	s_add_i32 s61, 0, 0x18000
	v_add_u32_e32 v138, s61, v150
	s_add_i32 s62, 0, 0x1c000
	ds_read_b128 v[156:159], v138
	ds_read_b128 v[160:163], v138 offset:1024
	ds_read_b128 v[164:167], v138 offset:2048
	ds_read_b128 v[168:171], v138 offset:3072
	v_add_u32_e32 v138, s62, v150
	ds_read_b128 v[174:177], v138
	ds_read_b128 v[178:181], v138 offset:1024
	ds_read_b128 v[182:185], v138 offset:2048
	ds_read_b128 v[186:189], v138 offset:3072

; #define PG8_STAGE(bufoff, gbase, voff) do { _Pragma("unroll") for (int _i = 0; _i < 2; ++_i) \
;         __builtin_amdgcn_global_load_lds((const unsigned*)((const char*)(gbase) + (voff)[_i]), (PG8_LAS unsigned*)(lds + (bufoff) + ldsw + _i * 8192), 16, 0, 0); } while (0)
; #define PG8_LDA(dst, b, h) do { _Pragma("unroll") for (int m = 0; m < 4; ++m) _Pragma("unroll") for (int k = 0; k < 2; ++k) dst[m][k] = *(const PG8_LAS bf16x8*)(lds + PG8_SA(b, h) + aoff + m * 2048 + k * 1024); } while (0)
; #define PG8_LDB(dst, b, h) do { _Pragma("unroll") for (int n = 0; n < 2; ++n) _Pragma("unroll") for (int k = 0; k < 2; ++k) dst[n][k] = *(const PG8_LAS bf16x8*)(lds + PG8_SB(b, h) + boff + n * 2048 + k * 1024); } while (0)
; #define PG8_MMA(ai, bj, At, Bt) do { __builtin_amdgcn_s_setprio(1); _Pragma("unroll") for (int m = 0; m < 4; ++m) _Pragma("unroll") for (int n = 0; n < 2; ++n) _Pragma("unroll") for (int k = 0; k < 2; ++k) \
;         acc[ai][bj][m][n] = __builtin_amdgcn_mfma_f32_16x16x32_bf16(Bt[n][k], At[m][k], acc[ai][bj][m][n], 0, 0, 0); __builtin_amdgcn_s_setprio(0); } while (0)
; #define PG8_WAIT_V(n) asm volatile("s_waitcnt vmcnt(" #n ")" ::: "memory")
; #define PG8_WAIT_L(n) asm volatile("s_waitcnt lgkmcnt(" #n ")" ::: "memory")
; #define PG8_BAR __builtin_amdgcn_s_barrier()
; #define PG8_SCHED __builtin_amdgcn_sched_barrier(0)
; template <class Epi, class Sched, bool ALIGN_EPI = false, bool SP2 = false>
; __device__ __forceinline__ void gemm_phase(PG8_LAS unsigned char* lds, const Gemm g, const Sched& S, const Epi& E) {
;     ...
;             PG8_LDB(B0, 1, 0); PG8_LDB(B1, 1, 1); PG8_SCHED; PG8_LDA(At, 1, 0); PG8_STAGE(PG8_SA(0, 1), a2 + hstep, voffA);
;             PG8_WAIT_V(8); PG8_WAIT_L(0); PG8_BAR; PG8_MMA(0, 0, At, B0); PG8_MMA(0, 1, At, B1); PG8_BAR; PG8_SCHED;
	s_add_u32 s22, s22, 0x40000
	s_addc_u32 s23, s23, 0
	s_mov_b32 m0, s34
	v_lshl_add_u64 v[230:231], s[22:23], 0, v[136:137]
	ds_read_b128 v[190:193], v153 offset:32768
	ds_read_b128 v[194:197], v153 offset:33792
	ds_read_b128 v[198:201], v153 offset:34816
	ds_read_b128 v[202:205], v153 offset:35840
	ds_read_b128 v[206:209], v153 offset:36864
	ds_read_b128 v[210:213], v153 offset:37888
	ds_read_b128 v[214:217], v153 offset:38912
	ds_read_b128 v[218:221], v153 offset:39936
	global_load_lds_dwordx4 v[230:231], off
	v_lshl_add_u64 v[230:231], s[22:23], 0, v[132:133]
	s_mov_b32 m0, s35
	s_nop 0
	global_load_lds_dwordx4 v[230:231], off
	s_waitcnt vmcnt(8)
	s_waitcnt lgkmcnt(0)
	s_barrier
	s_setprio 1
	s_waitcnt lgkmcnt(0)
	v_mfma_f32_16x16x32_bf16 v[126:129], v[156:159], v[190:193], v[126:129]
	v_mfma_f32_16x16x32_bf16 v[122:125], v[164:167], v[190:193], v[122:125]
	v_mfma_f32_16x16x32_bf16 v[114:117], v[156:159], v[198:201], v[114:117]
	v_mfma_f32_16x16x32_bf16 v[106:109], v[164:167], v[198:201], v[106:109]
	v_mfma_f32_16x16x32_bf16 v[98:101], v[156:159], v[206:209], v[98:101]
	v_mfma_f32_16x16x32_bf16 v[90:93], v[164:167], v[206:209], v[90:93]
	v_mfma_f32_16x16x32_bf16 v[82:85], v[156:159], v[214:217], v[82:85]
	v_mfma_f32_16x16x32_bf16 v[74:77], v[164:167], v[214:217], v[74:77]
	v_mfma_f32_16x16x32_bf16 v[126:129], v[160:163], v[194:197], v[126:129]
	v_mfma_f32_16x16x32_bf16 v[122:125], v[168:171], v[194:197], v[122:125]
	v_mfma_f32_16x16x32_bf16 v[114:117], v[160:163], v[202:205], v[114:117]
	v_mfma_f32_16x16x32_bf16 v[106:109], v[168:171], v[202:205], v[106:109]
	v_mfma_f32_16x16x32_bf16 v[98:101], v[160:163], v[210:213], v[98:101]
	v_mfma_f32_16x16x32_bf16 v[90:93], v[168:171], v[210:213], v[90:93]
	v_mfma_f32_16x16x32_bf16 v[82:85], v[160:163], v[218:221], v[82:85]
	v_mfma_f32_16x16x32_bf16 v[74:77], v[168:171], v[218:221], v[74:77]
	s_setprio 0
	s_setprio 1
	v_mfma_f32_16x16x32_bf16 v[118:121], v[174:177], v[190:193], v[118:121]
	v_mfma_f32_16x16x32_bf16 v[110:113], v[182:185], v[190:193], v[110:113]
	v_mfma_f32_16x16x32_bf16 v[102:105], v[174:177], v[198:201], v[102:105]
	v_mfma_f32_16x16x32_bf16 v[94:97], v[182:185], v[198:201], v[94:97]
	v_mfma_f32_16x16x32_bf16 v[86:89], v[174:177], v[206:209], v[86:89]
	v_mfma_f32_16x16x32_bf16 v[78:81], v[182:185], v[206:209], v[78:81]
	v_mfma_f32_16x16x32_bf16 v[70:73], v[174:177], v[214:217], v[70:73]
	v_mfma_f32_16x16x32_bf16 v[66:69], v[182:185], v[214:217], v[66:69]
	v_mfma_f32_16x16x32_bf16 v[118:121], v[178:181], v[194:197], v[118:121]
	v_mfma_f32_16x16x32_bf16 v[110:113], v[186:189], v[194:197], v[110:113]
	v_mfma_f32_16x16x32_bf16 v[102:105], v[178:181], v[202:205], v[102:105]
	v_mfma_f32_16x16x32_bf16 v[94:97], v[186:189], v[202:205], v[94:97]
	v_mfma_f32_16x16x32_bf16 v[86:89], v[178:181], v[210:213], v[86:89]
	v_mfma_f32_16x16x32_bf16 v[78:81], v[186:189], v[210:213], v[78:81]
	v_mfma_f32_16x16x32_bf16 v[70:73], v[178:181], v[218:221], v[70:73]
	v_mfma_f32_16x16x32_bf16 v[66:69], v[186:189], v[218:221], v[66:69]
	s_setprio 0
	s_barrier

; #define PG8_STAGE(bufoff, gbase, voff) do { _Pragma("unroll") for (int _i = 0; _i < 2; ++_i) \
;         __builtin_amdgcn_global_load_lds((const unsigned*)((const char*)(gbase) + (voff)[_i]), (PG8_LAS unsigned*)(lds + (bufoff) + ldsw + _i * 8192), 16, 0, 0); } while (0)
; #define PG8_LDA(dst, b, h) do { _Pragma("unroll") for (int m = 0; m < 4; ++m) _Pragma("unroll") for (int k = 0; k < 2; ++k) dst[m][k] = *(const PG8_LAS bf16x8*)(lds + PG8_SA(b, h) + aoff + m * 2048 + k * 1024); } while (0)
; #define PG8_MMA(ai, bj, At, Bt) do { __builtin_amdgcn_s_setprio(1); _Pragma("unroll") for (int m = 0; m < 4; ++m) _Pragma("unroll") for (int n = 0; n < 2; ++n) _Pragma("unroll") for (int k = 0; k < 2; ++k) \
;         acc[ai][bj][m][n] = __builtin_amdgcn_mfma_f32_16x16x32_bf16(Bt[n][k], At[m][k], acc[ai][bj][m][n], 0, 0, 0); __builtin_amdgcn_s_setprio(0); } while (0)
; #define PG8_WAIT_V(n) asm volatile("s_waitcnt vmcnt(" #n ")" ::: "memory")
; #define PG8_WAIT_L(n) asm volatile("s_waitcnt lgkmcnt(" #n ")" ::: "memory")
; #define PG8_BAR __builtin_amdgcn_s_barrier()
; #define PG8_SCHED __builtin_amdgcn_sched_barrier(0)
; template <class Epi, class Sched, bool ALIGN_EPI = false, bool SP2 = false>
; __device__ __forceinline__ void gemm_phase(PG8_LAS unsigned char* lds, const Gemm g, const Sched& S, const Epi& E) {
;     ...
;             PG8_LDA(At, 1, 1); PG8_STAGE(PG8_SB(1, 0), b3, voffB); PG8_STAGE(PG8_SB(1, 1), b3 + hstep, voffB); PG8_STAGE(PG8_SA(1, 0), a3, voffA);
;             PG8_WAIT_V(8); PG8_WAIT_L(0); PG8_BAR; PG8_MMA(1, 0, At, B0); PG8_MMA(1, 1, At, B1); PG8_BAR; PG8_SCHED;
	s_add_i32 s22, s61, s28
	v_lshl_add_u64 v[222:223], v[222:223], 0, s[4:5]
	s_mov_b32 m0, s22
	ds_read_b128 v[190:193], v153 offset:49152
	ds_read_b128 v[194:197], v153 offset:50176
	ds_read_b128 v[198:201], v153 offset:51200
	ds_read_b128 v[202:205], v153 offset:52224
	ds_read_b128 v[206:209], v153 offset:53248
	ds_read_b128 v[210:213], v153 offset:54272
	ds_read_b128 v[214:217], v153 offset:55296
	ds_read_b128 v[218:221], v153 offset:56320
	global_load_lds_dwordx4 v[222:223], off
	s_add_i32 m0, s22, 0x2000
	s_add_u32 s20, s20, 0x40080
	v_lshl_add_u64 v[222:223], v[224:225], 0, s[4:5]
	s_addc_u32 s21, s21, 0
	s_add_i32 s22, s62, s28
	global_load_lds_dwordx4 v[222:223], off
	v_lshl_add_u64 v[222:223], s[20:21], 0, v[134:135]
	s_mov_b32 m0, s22
	s_nop 0
	global_load_lds_dwordx4 v[222:223], off
	v_lshl_add_u64 v[222:223], s[20:21], 0, v[130:131]
	s_add_i32 m0, s22, 0x2000
	s_nop 0
	global_load_lds_dwordx4 v[222:223], off
	v_lshl_add_u64 v[222:223], v[226:227], 0, s[4:5]
	s_mov_b32 m0, s39
	s_nop 0
	global_load_lds_dwordx4 v[222:223], off
	v_lshl_add_u64 v[222:223], v[228:229], 0, s[4:5]
	s_mov_b32 m0, s40
	s_nop 0
	global_load_lds_dwordx4 v[222:223], off
	s_waitcnt vmcnt(8)
	s_waitcnt lgkmcnt(0)
	s_barrier
	s_setprio 1
	s_waitcnt lgkmcnt(0)
	v_mfma_f32_16x16x32_bf16 v[62:65], v[156:159], v[190:193], v[62:65]
	v_mfma_f32_16x16x32_bf16 v[58:61], v[164:167], v[190:193], v[58:61]
	v_mfma_f32_16x16x32_bf16 v[50:53], v[156:159], v[198:201], v[50:53]
	v_mfma_f32_16x16x32_bf16 v[42:45], v[164:167], v[198:201], v[42:45]
	v_mfma_f32_16x16x32_bf16 v[34:37], v[156:159], v[206:209], v[34:37]
	v_mfma_f32_16x16x32_bf16 v[26:29], v[164:167], v[206:209], v[26:29]
	v_mfma_f32_16x16x32_bf16 v[18:21], v[156:159], v[214:217], v[18:21]
	v_mfma_f32_16x16x32_bf16 v[10:13], v[164:167], v[214:217], v[10:13]
	v_mfma_f32_16x16x32_bf16 v[62:65], v[160:163], v[194:197], v[62:65]
	v_mfma_f32_16x16x32_bf16 v[58:61], v[168:171], v[194:197], v[58:61]
	v_mfma_f32_16x16x32_bf16 v[50:53], v[160:163], v[202:205], v[50:53]
	v_mfma_f32_16x16x32_bf16 v[42:45], v[168:171], v[202:205], v[42:45]
	v_mfma_f32_16x16x32_bf16 v[34:37], v[160:163], v[210:213], v[34:37]
	v_mfma_f32_16x16x32_bf16 v[26:29], v[168:171], v[210:213], v[26:29]
	v_mfma_f32_16x16x32_bf16 v[18:21], v[160:163], v[218:221], v[18:21]
	v_mfma_f32_16x16x32_bf16 v[10:13], v[168:171], v[218:221], v[10:13]
	s_setprio 0
	s_setprio 1
	v_mfma_f32_16x16x32_bf16 v[54:57], v[174:177], v[190:193], v[54:57]
	v_mfma_f32_16x16x32_bf16 v[46:49], v[182:185], v[190:193], v[46:49]
	v_mfma_f32_16x16x32_bf16 v[38:41], v[174:177], v[198:201], v[38:41]
	v_mfma_f32_16x16x32_bf16 v[30:33], v[182:185], v[198:201], v[30:33]
	v_mfma_f32_16x16x32_bf16 v[22:25], v[174:177], v[206:209], v[22:25]
	v_mfma_f32_16x16x32_bf16 v[14:17], v[182:185], v[206:209], v[14:17]
	v_mfma_f32_16x16x32_bf16 v[6:9], v[174:177], v[214:217], v[6:9]
	v_mfma_f32_16x16x32_bf16 v[2:5], v[182:185], v[214:217], v[2:5]
	v_mfma_f32_16x16x32_bf16 v[54:57], v[178:181], v[194:197], v[54:57]
	v_mfma_f32_16x16x32_bf16 v[46:49], v[186:189], v[194:197], v[46:49]
	v_mfma_f32_16x16x32_bf16 v[38:41], v[178:181], v[202:205], v[38:41]
	v_mfma_f32_16x16x32_bf16 v[30:33], v[186:189], v[202:205], v[30:33]
	v_mfma_f32_16x16x32_bf16 v[22:25], v[178:181], v[210:213], v[22:25]
	v_mfma_f32_16x16x32_bf16 v[14:17], v[186:189], v[210:213], v[14:17]
	v_mfma_f32_16x16x32_bf16 v[6:9], v[178:181], v[218:221], v[6:9]
	v_mfma_f32_16x16x32_bf16 v[2:5], v[186:189], v[218:221], v[2:5]
	s_setprio 0
	s_barrier

; template <class Epi, class Sched, bool ALIGN_EPI = false, bool SP2 = false>
; __device__ __forceinline__ void gemm_phase(PG8_LAS unsigned char* lds, const Gemm g, const Sched& S, const Epi& E) {
;     ...
;         for (int t = 0; t < nt; t += 2) {
;             const bool last = (t == nt - 2);
;             const char* a1 = cA + (size_t)(t + 1) * kstep;
;             const char* a2 = last ? nA : cA + (size_t)(t + 2) * kstep; const char* b2 = last ? nB : cB + (size_t)(t + 2) * kstep;
;             const char* a3 = a2 + kstep; const char* b3 = b2 + kstep;
	s_add_i32 s60, s60, 2
	s_add_u32 s18, s18, 0x100
	s_addc_u32 s19, s19, 0
	s_add_u32 s56, s56, 0x100
	s_addc_u32 s57, s57, 0

; #define PG8_STAGE(bufoff, gbase, voff) do { _Pragma("unroll") for (int _i = 0; _i < 2; ++_i) \
;         __builtin_amdgcn_global_load_lds((const unsigned*)((const char*)(gbase) + (voff)[_i]), (PG8_LAS unsigned*)(lds + (bufoff) + ldsw + _i * 8192), 16, 0, 0); } while (0)
; #define PG8_LDA(dst, b, h) do { _Pragma("unroll") for (int m = 0; m < 4; ++m) _Pragma("unroll") for (int k = 0; k < 2; ++k) dst[m][k] = *(const PG8_LAS bf16x8*)(lds + PG8_SA(b, h) + aoff + m * 2048 + k * 1024); } while (0)
; #define PG8_LDB(dst, b, h) do { _Pragma("unroll") for (int n = 0; n < 2; ++n) _Pragma("unroll") for (int k = 0; k < 2; ++k) dst[n][k] = *(const PG8_LAS bf16x8*)(lds + PG8_SB(b, h) + boff + n * 2048 + k * 1024); } while (0)
; #define PG8_SCHED __builtin_amdgcn_sched_barrier(0)
; template <class Epi, class Sched, bool ALIGN_EPI = false, bool SP2 = false>
; __device__ __forceinline__ void gemm_phase(PG8_LAS unsigned char* lds, const Gemm g, const Sched& S, const Epi& E) {
;     ...
;         const bool has_next = S.next(ui + 1, nxt);
;         const char* nA = has_next ? (const char*)g.A + (size_t)nxt.pm * tstep : cA; const char* nB = has_next ? (const char*)g.Bt + (size_t)nxt.pn * tstep : cB;
; #pragma nounroll
;         for (int t = 0; t < nt; t += 2) {
;             const bool last = (t == nt - 2);
;             const char* a1 = cA + (size_t)(t + 1) * kstep;
;             const char* a2 = last ? nA : cA + (size_t)(t + 2) * kstep; const char* b2 = last ? nB : cB + (size_t)(t + 2) * kstep;
;             const char* a3 = a2 + kstep; const char* b3 = b2 + kstep;
;             if (last && has_next) S.a_ready(nxt);
;             if constexpr (SP2) {
;             PG8_LDB(B0, 0, 0); PG8_LDB(B1, 0, 1); PG8_SCHED; PG8_LDA(At, 0, 0); PG8_STAGE(PG8_SA(1, 1), a1 + hstep, voffA);
;     ...
; #pragma unroll
;         for (int a = 0; a < 2; ++a)
; #pragma unroll
;             for (int b = 0; b < 2; ++b)
; #pragma unroll
;                 for (int m = 0; m < 4; ++m)
; #pragma unroll
;                     for (int n = 0; n < 2; ++n) acc[a][b][m][n] = (f32x4){0.f, 0.f, 0.f, 0.f};
.LBB0_688:
	s_ashr_i32 s23, s22, 31
	s_lshl_b64 s[24:25], s[22:23], 19
	s_add_u32 s24, s33, s24
	s_addc_u32 s25, s38, s25
	s_and_b64 s[26:27], s[2:3], exec
	s_cselect_b32 s23, s25, s29
	s_cselect_b32 s70, s24, s28
	s_ashr_i32 s21, s20, 31
	s_lshl_b64 s[26:27], s[20:21], 19
	s_add_u32 s26, s39, s26
	s_addc_u32 s27, s40, s27
	s_and_b64 s[34:35], s[2:3], exec
	s_cselect_b32 s21, s27, s31
	s_cselect_b32 s71, s26, s30
	s_add_u32 s28, s28, 0x40080
	s_addc_u32 s29, s29, 0
	s_add_u32 s72, s30, 0x100
	v_mov_b32_e32 v2, 0
	s_addc_u32 s73, s31, 0
	s_mov_b32 s74, -2
	v_mov_b32_e32 v3, v2
	v_mov_b32_e32 v4, v2
	v_mov_b32_e32 v5, v2
	v_mov_b32_e32 v6, v2
	v_mov_b32_e32 v7, v2
	v_mov_b32_e32 v8, v2
	v_mov_b32_e32 v9, v2
	v_mov_b32_e32 v14, v2
	v_mov_b32_e32 v15, v2
	v_mov_b32_e32 v16, v2
	v_mov_b32_e32 v17, v2
	v_mov_b32_e32 v22, v2
	v_mov_b32_e32 v23, v2
	v_mov_b32_e32 v24, v2
	v_mov_b32_e32 v25, v2
	v_mov_b32_e32 v30, v2
	v_mov_b32_e32 v31, v2
	v_mov_b32_e32 v32, v2
	v_mov_b32_e32 v33, v2
	v_mov_b32_e32 v38, v2
	v_mov_b32_e32 v39, v2
	v_mov_b32_e32 v40, v2
	v_mov_b32_e32 v41, v2
	v_mov_b32_e32 v46, v2
	v_mov_b32_e32 v47, v2
	v_mov_b32_e32 v48, v2
	v_mov_b32_e32 v49, v2
	v_mov_b32_e32 v54, v2
	v_mov_b32_e32 v55, v2
	v_mov_b32_e32 v56, v2
	v_mov_b32_e32 v57, v2
	v_mov_b32_e32 v10, v2
	v_mov_b32_e32 v11, v2
	v_mov_b32_e32 v12, v2
	v_mov_b32_e32 v13, v2
	v_mov_b32_e32 v18, v2
	v_mov_b32_e32 v19, v2
	v_mov_b32_e32 v20, v2
	v_mov_b32_e32 v21, v2
	v_mov_b32_e32 v26, v2
	v_mov_b32_e32 v27, v2
	v_mov_b32_e32 v28, v2
	v_mov_b32_e32 v29, v2
	v_mov_b32_e32 v34, v2
	v_mov_b32_e32 v35, v2
	v_mov_b32_e32 v36, v2
	v_mov_b32_e32 v37, v2
	v_mov_b32_e32 v42, v2
	v_mov_b32_e32 v43, v2
	v_mov_b32_e32 v44, v2
	v_mov_b32_e32 v45, v2
	v_mov_b32_e32 v50, v2
	v_mov_b32_e32 v51, v2
	v_mov_b32_e32 v52, v2
	v_mov_b32_e32 v53, v2
	v_mov_b32_e32 v58, v2
	v_mov_b32_e32 v59, v2
	v_mov_b32_e32 v60, v2
	v_mov_b32_e32 v61, v2
	v_mov_b32_e32 v62, v2
	v_mov_b32_e32 v63, v2
	v_mov_b32_e32 v64, v2
	v_mov_b32_e32 v65, v2
	v_mov_b32_e32 v66, v2
	v_mov_b32_e32 v67, v2
	v_mov_b32_e32 v68, v2
	v_mov_b32_e32 v69, v2
	v_mov_b32_e32 v70, v2
	v_mov_b32_e32 v71, v2
	v_mov_b32_e32 v72, v2
	v_mov_b32_e32 v73, v2
	v_mov_b32_e32 v78, v2
	v_mov_b32_e32 v79, v2
	v_mov_b32_e32 v80, v2
	v_mov_b32_e32 v81, v2
	v_mov_b32_e32 v86, v2
	v_mov_b32_e32 v87, v2
	v_mov_b32_e32 v88, v2
	v_mov_b32_e32 v89, v2
	v_mov_b32_e32 v94, v2
	v_mov_b32_e32 v95, v2
	v_mov_b32_e32 v96, v2
	v_mov_b32_e32 v97, v2
	v_mov_b32_e32 v102, v2
	v_mov_b32_e32 v103, v2
	v_mov_b32_e32 v104, v2
	v_mov_b32_e32 v105, v2
	v_mov_b32_e32 v110, v2
	v_mov_b32_e32 v111, v2
	v_mov_b32_e32 v112, v2
	v_mov_b32_e32 v113, v2
	v_mov_b32_e32 v118, v2
	v_mov_b32_e32 v119, v2
	v_mov_b32_e32 v120, v2
	v_mov_b32_e32 v121, v2
	v_mov_b32_e32 v74, v2
	v_mov_b32_e32 v75, v2
	v_mov_b32_e32 v76, v2
	v_mov_b32_e32 v77, v2
	v_mov_b32_e32 v82, v2
	v_mov_b32_e32 v83, v2
	v_mov_b32_e32 v84, v2
	v_mov_b32_e32 v85, v2
	v_mov_b32_e32 v90, v2
	v_mov_b32_e32 v91, v2
	v_mov_b32_e32 v92, v2
	v_mov_b32_e32 v93, v2
	v_mov_b32_e32 v98, v2
	v_mov_b32_e32 v99, v2
	v_mov_b32_e32 v100, v2
	v_mov_b32_e32 v101, v2
	v_mov_b32_e32 v106, v2
	v_mov_b32_e32 v107, v2
	v_mov_b32_e32 v108, v2
	v_mov_b32_e32 v109, v2
	v_mov_b32_e32 v114, v2
	v_mov_b32_e32 v115, v2
	v_mov_b32_e32 v116, v2
	v_mov_b32_e32 v117, v2
	v_mov_b32_e32 v122, v2
	v_mov_b32_e32 v123, v2
	v_mov_b32_e32 v124, v2
	v_mov_b32_e32 v125, v2
	v_mov_b32_e32 v126, v2
	v_mov_b32_e32 v127, v2
	v_mov_b32_e32 v128, v2
	v_mov_b32_e32 v129, v2
	ds_read_b128 v[148:151], v157
	ds_read_b128 v[152:155], v157 offset:1024
	ds_read_b128 v[160:163], v157 offset:2048
	ds_read_b128 v[164:167], v157 offset:3072
	ds_read_b128 v[168:171], v158
	ds_read_b128 v[174:177], v158 offset:1024
	ds_read_b128 v[178:181], v158 offset:2048
	ds_read_b128 v[182:185], v158 offset:3072
	s_add_u32 s30, s28, 0xfffc0080
	s_addc_u32 s31, s29, -1
	s_cmp_eq_u32 s74, 12
	s_cselect_b32 s35, s23, s31
	s_cselect_b32 s34, s70, s30
	s_cselect_b32 s31, s21, s73
	s_cselect_b32 s30, s71, s72

; #define PG8_STAGE(bufoff, gbase, voff) do { _Pragma("unroll") for (int _i = 0; _i < 2; ++_i) \
;         __builtin_amdgcn_global_load_lds((const unsigned*)((const char*)(gbase) + (voff)[_i]), (PG8_LAS unsigned*)(lds + (bufoff) + ldsw + _i * 8192), 16, 0, 0); } while (0)
; #define PG8_LDA(dst, b, h) do { _Pragma("unroll") for (int m = 0; m < 4; ++m) _Pragma("unroll") for (int k = 0; k < 2; ++k) dst[m][k] = *(const PG8_LAS bf16x8*)(lds + PG8_SA(b, h) + aoff + m * 2048 + k * 1024); } while (0)
; #define PG8_LDB(dst, b, h) do { _Pragma("unroll") for (int n = 0; n < 2; ++n) _Pragma("unroll") for (int k = 0; k < 2; ++k) dst[n][k] = *(const PG8_LAS bf16x8*)(lds + PG8_SB(b, h) + boff + n * 2048 + k * 1024); } while (0)
; #define PG8_MMA(ai, bj, At, Bt) do { __builtin_amdgcn_s_setprio(1); _Pragma("unroll") for (int m = 0; m < 4; ++m) _Pragma("unroll") for (int n = 0; n < 2; ++n) _Pragma("unroll") for (int k = 0; k < 2; ++k) \
;         acc[ai][bj][m][n] = __builtin_amdgcn_mfma_f32_16x16x32_bf16(Bt[n][k], At[m][k], acc[ai][bj][m][n], 0, 0, 0); __builtin_amdgcn_s_setprio(0); } while (0)
; #define PG8_WAIT_V(n) asm volatile("s_waitcnt vmcnt(" #n ")" ::: "memory")
; #define PG8_WAIT_L(n) asm volatile("s_waitcnt lgkmcnt(" #n ")" ::: "memory")
; #define PG8_BAR __builtin_amdgcn_s_barrier()
; #define PG8_SCHED __builtin_amdgcn_sched_barrier(0)
; template <class Epi, class Sched, bool ALIGN_EPI = false, bool SP2 = false>
; __device__ __forceinline__ void gemm_phase(PG8_LAS unsigned char* lds, const Gemm g, const Sched& S, const Epi& E) {
;     ...
;             PG8_LDB(B0, 0, 0); PG8_LDB(B1, 0, 1); PG8_SCHED; PG8_LDA(At, 0, 0); PG8_STAGE(PG8_SA(1, 1), a1 + hstep, voffA);
;             PG8_WAIT_V(8); PG8_WAIT_L(0); PG8_BAR; PG8_MMA(0, 0, At, B0); PG8_MMA(0, 1, At, B1); PG8_BAR; PG8_SCHED;
	v_lshl_add_u64 v[218:219], s[28:29], 0, v[140:141]
	s_add_i32 m0, s44, 0xc000
	ds_read_b128 v[186:189], v159
	ds_read_b128 v[190:193], v159 offset:1024
	ds_read_b128 v[194:197], v159 offset:2048
	ds_read_b128 v[198:201], v159 offset:3072
	ds_read_b128 v[202:205], v159 offset:4096
	ds_read_b128 v[206:209], v159 offset:5120
	ds_read_b128 v[210:213], v159 offset:6144
	ds_read_b128 v[214:217], v159 offset:7168
	global_load_lds_dwordx4 v[218:219], off
	v_lshl_add_u64 v[218:219], s[28:29], 0, v[142:143]
	s_add_i32 m0, s44, 0xe000
	s_nop 0
	global_load_lds_dwordx4 v[218:219], off
	s_waitcnt vmcnt(24)
	s_waitcnt lgkmcnt(0)
	s_barrier
	s_setprio 1
	s_waitcnt lgkmcnt(0)
	v_mfma_f32_16x16x32_bf16 v[126:129], v[148:151], v[186:189], v[126:129]
	v_mfma_f32_16x16x32_bf16 v[122:125], v[160:163], v[186:189], v[122:125]
	v_mfma_f32_16x16x32_bf16 v[114:117], v[148:151], v[194:197], v[114:117]
	v_mfma_f32_16x16x32_bf16 v[106:109], v[160:163], v[194:197], v[106:109]
	v_mfma_f32_16x16x32_bf16 v[98:101], v[148:151], v[202:205], v[98:101]
	v_mfma_f32_16x16x32_bf16 v[90:93], v[160:163], v[202:205], v[90:93]
	v_mfma_f32_16x16x32_bf16 v[82:85], v[148:151], v[210:213], v[82:85]
	v_mfma_f32_16x16x32_bf16 v[74:77], v[160:163], v[210:213], v[74:77]
	v_mfma_f32_16x16x32_bf16 v[126:129], v[152:155], v[190:193], v[126:129]
	v_mfma_f32_16x16x32_bf16 v[122:125], v[164:167], v[190:193], v[122:125]
	v_mfma_f32_16x16x32_bf16 v[114:117], v[152:155], v[198:201], v[114:117]
	v_mfma_f32_16x16x32_bf16 v[106:109], v[164:167], v[198:201], v[106:109]
	v_mfma_f32_16x16x32_bf16 v[98:101], v[152:155], v[206:209], v[98:101]
	v_mfma_f32_16x16x32_bf16 v[90:93], v[164:167], v[206:209], v[90:93]
	v_mfma_f32_16x16x32_bf16 v[82:85], v[152:155], v[214:217], v[82:85]
	v_mfma_f32_16x16x32_bf16 v[74:77], v[164:167], v[214:217], v[74:77]
	s_setprio 0
	s_setprio 1
	v_mfma_f32_16x16x32_bf16 v[118:121], v[168:171], v[186:189], v[118:121]
	v_mfma_f32_16x16x32_bf16 v[110:113], v[178:181], v[186:189], v[110:113]
	v_mfma_f32_16x16x32_bf16 v[102:105], v[168:171], v[194:197], v[102:105]
	v_mfma_f32_16x16x32_bf16 v[94:97], v[178:181], v[194:197], v[94:97]
	v_mfma_f32_16x16x32_bf16 v[86:89], v[168:171], v[202:205], v[86:89]
	v_mfma_f32_16x16x32_bf16 v[78:81], v[178:181], v[202:205], v[78:81]
	v_mfma_f32_16x16x32_bf16 v[70:73], v[168:171], v[210:213], v[70:73]
	v_mfma_f32_16x16x32_bf16 v[66:69], v[178:181], v[210:213], v[66:69]
	v_mfma_f32_16x16x32_bf16 v[118:121], v[174:177], v[190:193], v[118:121]
	v_mfma_f32_16x16x32_bf16 v[110:113], v[182:185], v[190:193], v[110:113]
	v_mfma_f32_16x16x32_bf16 v[102:105], v[174:177], v[198:201], v[102:105]
	v_mfma_f32_16x16x32_bf16 v[94:97], v[182:185], v[198:201], v[94:97]
	v_mfma_f32_16x16x32_bf16 v[86:89], v[174:177], v[206:209], v[86:89]
	v_mfma_f32_16x16x32_bf16 v[78:81], v[182:185], v[206:209], v[78:81]
	v_mfma_f32_16x16x32_bf16 v[70:73], v[174:177], v[214:217], v[70:73]
	v_mfma_f32_16x16x32_bf16 v[66:69], v[182:185], v[214:217], v[66:69]
	s_setprio 0
	s_barrier

; #define PG8_STAGE(bufoff, gbase, voff) do { _Pragma("unroll") for (int _i = 0; _i < 2; ++_i) \
;         __builtin_amdgcn_global_load_lds((const unsigned*)((const char*)(gbase) + (voff)[_i]), (PG8_LAS unsigned*)(lds + (bufoff) + ldsw + _i * 8192), 16, 0, 0); } while (0)
; #define PG8_LDA(dst, b, h) do { _Pragma("unroll") for (int m = 0; m < 4; ++m) _Pragma("unroll") for (int k = 0; k < 2; ++k) dst[m][k] = *(const PG8_LAS bf16x8*)(lds + PG8_SA(b, h) + aoff + m * 2048 + k * 1024); } while (0)
; #define PG8_MMA(ai, bj, At, Bt) do { __builtin_amdgcn_s_setprio(1); _Pragma("unroll") for (int m = 0; m < 4; ++m) _Pragma("unroll") for (int n = 0; n < 2; ++n) _Pragma("unroll") for (int k = 0; k < 2; ++k) \
;         acc[ai][bj][m][n] = __builtin_amdgcn_mfma_f32_16x16x32_bf16(Bt[n][k], At[m][k], acc[ai][bj][m][n], 0, 0, 0); __builtin_amdgcn_s_setprio(0); } while (0)
; #define PG8_WAIT_V(n) asm volatile("s_waitcnt vmcnt(" #n ")" ::: "memory")
; #define PG8_WAIT_L(n) asm volatile("s_waitcnt lgkmcnt(" #n ")" ::: "memory")
; #define PG8_BAR __builtin_amdgcn_s_barrier()
; #define PG8_SCHED __builtin_amdgcn_sched_barrier(0)
; template <class Epi, class Sched, bool ALIGN_EPI = false, bool SP2 = false>
; __device__ __forceinline__ void gemm_phase(PG8_LAS unsigned char* lds, const Gemm g, const Sched& S, const Epi& E) {
;     ...
;             PG8_LDA(At, 0, 1); PG8_STAGE(PG8_SB(0, 0), b2, voffB); PG8_STAGE(PG8_SB(0, 1), b2 + hstep, voffB); PG8_STAGE(PG8_SA(0, 0), a2, voffA);
;             PG8_WAIT_V(8); PG8_WAIT_L(0); PG8_BAR; PG8_MMA(1, 0, At, B0); PG8_MMA(1, 1, At, B1); PG8_BAR; PG8_SCHED;
	s_add_i32 s75, s63, s41
	v_lshl_add_u64 v[218:219], s[30:31], 0, v[136:137]
	s_mov_b32 m0, s75
	ds_read_b128 v[186:189], v159 offset:16384
	ds_read_b128 v[190:193], v159 offset:17408
	ds_read_b128 v[194:197], v159 offset:18432
	ds_read_b128 v[198:201], v159 offset:19456
	ds_read_b128 v[202:205], v159 offset:20480
	ds_read_b128 v[206:209], v159 offset:21504
	ds_read_b128 v[210:213], v159 offset:22528
	ds_read_b128 v[214:217], v159 offset:23552
	global_load_lds_dwordx4 v[218:219], off
	s_add_i32 m0, s75, 0x2000
	s_add_u32 s76, s30, 0x40000
	v_lshl_add_u64 v[220:221], s[30:31], 0, v[132:133]
	s_addc_u32 s77, s31, 0
	s_add_i32 s75, s66, s41
	global_load_lds_dwordx4 v[220:221], off
	v_lshl_add_u64 v[222:223], s[76:77], 0, v[136:137]
	s_mov_b32 m0, s75
	v_lshl_add_u64 v[224:225], s[34:35], 0, v[134:135]
	global_load_lds_dwordx4 v[222:223], off
	v_lshl_add_u64 v[222:223], s[76:77], 0, v[132:133]
	s_add_i32 m0, s75, 0x2000
	s_nop 0
	global_load_lds_dwordx4 v[222:223], off
	v_lshl_add_u64 v[222:223], s[34:35], 0, v[138:139]
	s_mov_b32 m0, s44
	s_nop 0
	global_load_lds_dwordx4 v[222:223], off
	s_mov_b32 m0, s45
	s_nop 0
	global_load_lds_dwordx4 v[224:225], off
	s_waitcnt vmcnt(24)
	s_waitcnt lgkmcnt(0)
	s_barrier
	s_setprio 1
	s_waitcnt lgkmcnt(0)
	v_mfma_f32_16x16x32_bf16 v[62:65], v[148:151], v[186:189], v[62:65]
	v_mfma_f32_16x16x32_bf16 v[58:61], v[160:163], v[186:189], v[58:61]
	v_mfma_f32_16x16x32_bf16 v[50:53], v[148:151], v[194:197], v[50:53]
	v_mfma_f32_16x16x32_bf16 v[42:45], v[160:163], v[194:197], v[42:45]
	v_mfma_f32_16x16x32_bf16 v[34:37], v[148:151], v[202:205], v[34:37]
	v_mfma_f32_16x16x32_bf16 v[26:29], v[160:163], v[202:205], v[26:29]
	v_mfma_f32_16x16x32_bf16 v[18:21], v[148:151], v[210:213], v[18:21]
	v_mfma_f32_16x16x32_bf16 v[10:13], v[160:163], v[210:213], v[10:13]
	v_mfma_f32_16x16x32_bf16 v[62:65], v[152:155], v[190:193], v[62:65]
	v_mfma_f32_16x16x32_bf16 v[58:61], v[164:167], v[190:193], v[58:61]
	v_mfma_f32_16x16x32_bf16 v[50:53], v[152:155], v[198:201], v[50:53]
	v_mfma_f32_16x16x32_bf16 v[42:45], v[164:167], v[198:201], v[42:45]
	v_mfma_f32_16x16x32_bf16 v[34:37], v[152:155], v[206:209], v[34:37]
	v_mfma_f32_16x16x32_bf16 v[26:29], v[164:167], v[206:209], v[26:29]
	v_mfma_f32_16x16x32_bf16 v[18:21], v[152:155], v[214:217], v[18:21]
	v_mfma_f32_16x16x32_bf16 v[10:13], v[164:167], v[214:217], v[10:13]
	s_setprio 0
	s_setprio 1
	v_mfma_f32_16x16x32_bf16 v[54:57], v[168:171], v[186:189], v[54:57]
	v_mfma_f32_16x16x32_bf16 v[46:49], v[178:181], v[186:189], v[46:49]
	v_mfma_f32_16x16x32_bf16 v[38:41], v[168:171], v[194:197], v[38:41]
	v_mfma_f32_16x16x32_bf16 v[30:33], v[178:181], v[194:197], v[30:33]
	v_mfma_f32_16x16x32_bf16 v[22:25], v[168:171], v[202:205], v[22:25]
	v_mfma_f32_16x16x32_bf16 v[14:17], v[178:181], v[202:205], v[14:17]
	v_mfma_f32_16x16x32_bf16 v[6:9], v[168:171], v[210:213], v[6:9]
	v_mfma_f32_16x16x32_bf16 v[2:5], v[178:181], v[210:213], v[2:5]
	v_mfma_f32_16x16x32_bf16 v[54:57], v[174:177], v[190:193], v[54:57]
	v_mfma_f32_16x16x32_bf16 v[46:49], v[182:185], v[190:193], v[46:49]
	v_mfma_f32_16x16x32_bf16 v[38:41], v[174:177], v[198:201], v[38:41]
	v_mfma_f32_16x16x32_bf16 v[30:33], v[182:185], v[198:201], v[30:33]
	v_mfma_f32_16x16x32_bf16 v[22:25], v[174:177], v[206:209], v[22:25]
	v_mfma_f32_16x16x32_bf16 v[14:17], v[182:185], v[206:209], v[14:17]
	v_mfma_f32_16x16x32_bf16 v[6:9], v[174:177], v[214:217], v[6:9]
	v_mfma_f32_16x16x32_bf16 v[2:5], v[182:185], v[214:217], v[2:5]
	s_setprio 0
	s_barrier

; #define PG8_STAGE(bufoff, gbase, voff) do { _Pragma("unroll") for (int _i = 0; _i < 2; ++_i) \
;         __builtin_amdgcn_global_load_lds((const unsigned*)((const char*)(gbase) + (voff)[_i]), (PG8_LAS unsigned*)(lds + (bufoff) + ldsw + _i * 8192), 16, 0, 0); } while (0)
; #define PG8_LDA(dst, b, h) do { _Pragma("unroll") for (int m = 0; m < 4; ++m) _Pragma("unroll") for (int k = 0; k < 2; ++k) dst[m][k] = *(const PG8_LAS bf16x8*)(lds + PG8_SA(b, h) + aoff + m * 2048 + k * 1024); } while (0)
; #define PG8_LDB(dst, b, h) do { _Pragma("unroll") for (int n = 0; n < 2; ++n) _Pragma("unroll") for (int k = 0; k < 2; ++k) dst[n][k] = *(const PG8_LAS bf16x8*)(lds + PG8_SB(b, h) + boff + n * 2048 + k * 1024); } while (0)
; #define PG8_SCHED __builtin_amdgcn_sched_barrier(0)
; template <class Epi, class Sched, bool ALIGN_EPI = false, bool SP2 = false>
; __device__ __forceinline__ void gemm_phase(PG8_LAS unsigned char* lds, const Gemm g, const Sched& S, const Epi& E) {
;     ...
;             PG8_LDB(B0, 1, 0); PG8_LDB(B1, 1, 1); PG8_SCHED; PG8_LDA(At, 1, 0); PG8_STAGE(PG8_SA(0, 1), a2 + hstep, voffA);
	s_add_i32 s75, 0, 0x18000
	s_add_i32 s76, 0, 0x1c000
	v_add_u32_e32 v164, s75, v131
	v_add_u32_e32 v182, s76, v131
	ds_read_b128 v[148:151], v164
	ds_read_b128 v[152:155], v164 offset:1024
	ds_read_b128 v[160:163], v164 offset:2048
	ds_read_b128 v[164:167], v164 offset:3072
	ds_read_b128 v[168:171], v182
	ds_read_b128 v[174:177], v182 offset:1024
	ds_read_b128 v[178:181], v182 offset:2048
	ds_read_b128 v[182:185], v182 offset:3072

; #define PG8_STAGE(bufoff, gbase, voff) do { _Pragma("unroll") for (int _i = 0; _i < 2; ++_i) \
;         __builtin_amdgcn_global_load_lds((const unsigned*)((const char*)(gbase) + (voff)[_i]), (PG8_LAS unsigned*)(lds + (bufoff) + ldsw + _i * 8192), 16, 0, 0); } while (0)
; #define PG8_LDA(dst, b, h) do { _Pragma("unroll") for (int m = 0; m < 4; ++m) _Pragma("unroll") for (int k = 0; k < 2; ++k) dst[m][k] = *(const PG8_LAS bf16x8*)(lds + PG8_SA(b, h) + aoff + m * 2048 + k * 1024); } while (0)
; #define PG8_LDB(dst, b, h) do { _Pragma("unroll") for (int n = 0; n < 2; ++n) _Pragma("unroll") for (int k = 0; k < 2; ++k) dst[n][k] = *(const PG8_LAS bf16x8*)(lds + PG8_SB(b, h) + boff + n * 2048 + k * 1024); } while (0)
; #define PG8_MMA(ai, bj, At, Bt) do { __builtin_amdgcn_s_setprio(1); _Pragma("unroll") for (int m = 0; m < 4; ++m) _Pragma("unroll") for (int n = 0; n < 2; ++n) _Pragma("unroll") for (int k = 0; k < 2; ++k) \
;         acc[ai][bj][m][n] = __builtin_amdgcn_mfma_f32_16x16x32_bf16(Bt[n][k], At[m][k], acc[ai][bj][m][n], 0, 0, 0); __builtin_amdgcn_s_setprio(0); } while (0)
; #define PG8_WAIT_V(n) asm volatile("s_waitcnt vmcnt(" #n ")" ::: "memory")
; #define PG8_WAIT_L(n) asm volatile("s_waitcnt lgkmcnt(" #n ")" ::: "memory")
; #define PG8_BAR __builtin_amdgcn_s_barrier()
; #define PG8_SCHED __builtin_amdgcn_sched_barrier(0)
; template <class Epi, class Sched, bool ALIGN_EPI = false, bool SP2 = false>
; __device__ __forceinline__ void gemm_phase(PG8_LAS unsigned char* lds, const Gemm g, const Sched& S, const Epi& E) {
;     ...
;             PG8_LDB(B0, 1, 0); PG8_LDB(B1, 1, 1); PG8_SCHED; PG8_LDA(At, 1, 0); PG8_STAGE(PG8_SA(0, 1), a2 + hstep, voffA);
;             PG8_WAIT_V(8); PG8_WAIT_L(0); PG8_BAR; PG8_MMA(0, 0, At, B0); PG8_MMA(0, 1, At, B1); PG8_BAR; PG8_SCHED;
	s_add_u32 s34, s34, 0x40000
	s_addc_u32 s35, s35, 0
	s_mov_b32 m0, s52
	v_lshl_add_u64 v[226:227], s[34:35], 0, v[138:139]
	ds_read_b128 v[186:189], v159 offset:32768
	ds_read_b128 v[190:193], v159 offset:33792
	ds_read_b128 v[194:197], v159 offset:34816
	ds_read_b128 v[198:201], v159 offset:35840
	ds_read_b128 v[202:205], v159 offset:36864
	ds_read_b128 v[206:209], v159 offset:37888
	ds_read_b128 v[210:213], v159 offset:38912
	ds_read_b128 v[214:217], v159 offset:39936
	global_load_lds_dwordx4 v[226:227], off
	v_lshl_add_u64 v[226:227], s[34:35], 0, v[134:135]
	s_mov_b32 m0, s53
	s_nop 0
	global_load_lds_dwordx4 v[226:227], off
	s_waitcnt vmcnt(8)
	s_waitcnt lgkmcnt(0)
	s_barrier
	s_setprio 1
	s_waitcnt lgkmcnt(0)
	v_mfma_f32_16x16x32_bf16 v[126:129], v[148:151], v[186:189], v[126:129]
	v_mfma_f32_16x16x32_bf16 v[122:125], v[160:163], v[186:189], v[122:125]
	v_mfma_f32_16x16x32_bf16 v[114:117], v[148:151], v[194:197], v[114:117]
	v_mfma_f32_16x16x32_bf16 v[106:109], v[160:163], v[194:197], v[106:109]
	v_mfma_f32_16x16x32_bf16 v[98:101], v[148:151], v[202:205], v[98:101]
	v_mfma_f32_16x16x32_bf16 v[90:93], v[160:163], v[202:205], v[90:93]
	v_mfma_f32_16x16x32_bf16 v[82:85], v[148:151], v[210:213], v[82:85]
	v_mfma_f32_16x16x32_bf16 v[74:77], v[160:163], v[210:213], v[74:77]
	v_mfma_f32_16x16x32_bf16 v[126:129], v[152:155], v[190:193], v[126:129]
	v_mfma_f32_16x16x32_bf16 v[122:125], v[164:167], v[190:193], v[122:125]
	v_mfma_f32_16x16x32_bf16 v[114:117], v[152:155], v[198:201], v[114:117]
	v_mfma_f32_16x16x32_bf16 v[106:109], v[164:167], v[198:201], v[106:109]
	v_mfma_f32_16x16x32_bf16 v[98:101], v[152:155], v[206:209], v[98:101]
	v_mfma_f32_16x16x32_bf16 v[90:93], v[164:167], v[206:209], v[90:93]
	v_mfma_f32_16x16x32_bf16 v[82:85], v[152:155], v[214:217], v[82:85]
	v_mfma_f32_16x16x32_bf16 v[74:77], v[164:167], v[214:217], v[74:77]
	s_setprio 0
	s_setprio 1
	v_mfma_f32_16x16x32_bf16 v[118:121], v[168:171], v[186:189], v[118:121]
	v_mfma_f32_16x16x32_bf16 v[110:113], v[178:181], v[186:189], v[110:113]
	v_mfma_f32_16x16x32_bf16 v[102:105], v[168:171], v[194:197], v[102:105]
	v_mfma_f32_16x16x32_bf16 v[94:97], v[178:181], v[194:197], v[94:97]
	v_mfma_f32_16x16x32_bf16 v[86:89], v[168:171], v[202:205], v[86:89]
	v_mfma_f32_16x16x32_bf16 v[78:81], v[178:181], v[202:205], v[78:81]
	v_mfma_f32_16x16x32_bf16 v[70:73], v[168:171], v[210:213], v[70:73]
	v_mfma_f32_16x16x32_bf16 v[66:69], v[178:181], v[210:213], v[66:69]
	v_mfma_f32_16x16x32_bf16 v[118:121], v[174:177], v[190:193], v[118:121]
	v_mfma_f32_16x16x32_bf16 v[110:113], v[182:185], v[190:193], v[110:113]
	v_mfma_f32_16x16x32_bf16 v[102:105], v[174:177], v[198:201], v[102:105]
	v_mfma_f32_16x16x32_bf16 v[94:97], v[182:185], v[198:201], v[94:97]
	v_mfma_f32_16x16x32_bf16 v[86:89], v[174:177], v[206:209], v[86:89]
	v_mfma_f32_16x16x32_bf16 v[78:81], v[182:185], v[206:209], v[78:81]
	v_mfma_f32_16x16x32_bf16 v[70:73], v[174:177], v[214:217], v[70:73]
	v_mfma_f32_16x16x32_bf16 v[66:69], v[182:185], v[214:217], v[66:69]
	s_setprio 0
	s_barrier

; #define PG8_STAGE(bufoff, gbase, voff) do { _Pragma("unroll") for (int _i = 0; _i < 2; ++_i) \
;         __builtin_amdgcn_global_load_lds((const unsigned*)((const char*)(gbase) + (voff)[_i]), (PG8_LAS unsigned*)(lds + (bufoff) + ldsw + _i * 8192), 16, 0, 0); } while (0)
; #define PG8_LDA(dst, b, h) do { _Pragma("unroll") for (int m = 0; m < 4; ++m) _Pragma("unroll") for (int k = 0; k < 2; ++k) dst[m][k] = *(const PG8_LAS bf16x8*)(lds + PG8_SA(b, h) + aoff + m * 2048 + k * 1024); } while (0)
; #define PG8_MMA(ai, bj, At, Bt) do { __builtin_amdgcn_s_setprio(1); _Pragma("unroll") for (int m = 0; m < 4; ++m) _Pragma("unroll") for (int n = 0; n < 2; ++n) _Pragma("unroll") for (int k = 0; k < 2; ++k) \
;         acc[ai][bj][m][n] = __builtin_amdgcn_mfma_f32_16x16x32_bf16(Bt[n][k], At[m][k], acc[ai][bj][m][n], 0, 0, 0); __builtin_amdgcn_s_setprio(0); } while (0)
; #define PG8_WAIT_V(n) asm volatile("s_waitcnt vmcnt(" #n ")" ::: "memory")
; #define PG8_WAIT_L(n) asm volatile("s_waitcnt lgkmcnt(" #n ")" ::: "memory")
; #define PG8_BAR __builtin_amdgcn_s_barrier()
; #define PG8_SCHED __builtin_amdgcn_sched_barrier(0)
; template <class Epi, class Sched, bool ALIGN_EPI = false, bool SP2 = false>
; __device__ __forceinline__ void gemm_phase(PG8_LAS unsigned char* lds, const Gemm g, const Sched& S, const Epi& E) {
;     ...
;             PG8_LDA(At, 1, 1); PG8_STAGE(PG8_SB(1, 0), b3, voffB); PG8_STAGE(PG8_SB(1, 1), b3 + hstep, voffB); PG8_STAGE(PG8_SA(1, 0), a3, voffA);
;             PG8_WAIT_V(8); PG8_WAIT_L(0); PG8_BAR; PG8_MMA(1, 0, At, B0); PG8_MMA(1, 1, At, B1); PG8_BAR; PG8_SCHED;
	s_add_i32 s34, s75, s41
	v_lshl_add_u64 v[218:219], v[218:219], 0, s[10:11]
	s_mov_b32 m0, s34
	ds_read_b128 v[186:189], v159 offset:49152
	ds_read_b128 v[190:193], v159 offset:50176
	ds_read_b128 v[194:197], v159 offset:51200
	ds_read_b128 v[198:201], v159 offset:52224
	ds_read_b128 v[202:205], v159 offset:53248
	ds_read_b128 v[206:209], v159 offset:54272
	ds_read_b128 v[210:213], v159 offset:55296
	ds_read_b128 v[214:217], v159 offset:56320
	global_load_lds_dwordx4 v[218:219], off
	s_add_i32 m0, s34, 0x2000
	s_add_u32 s30, s30, 0x40080
	v_lshl_add_u64 v[218:219], v[220:221], 0, s[10:11]
	s_addc_u32 s31, s31, 0
	s_add_i32 s34, s76, s41
	global_load_lds_dwordx4 v[218:219], off
	v_lshl_add_u64 v[218:219], s[30:31], 0, v[136:137]
	s_mov_b32 m0, s34
	s_nop 0
	global_load_lds_dwordx4 v[218:219], off
	v_lshl_add_u64 v[218:219], s[30:31], 0, v[132:133]
	s_add_i32 m0, s34, 0x2000
	s_nop 0
	global_load_lds_dwordx4 v[218:219], off
	v_lshl_add_u64 v[218:219], v[222:223], 0, s[10:11]
	s_mov_b32 m0, s57
	s_nop 0
	global_load_lds_dwordx4 v[218:219], off
	v_lshl_add_u64 v[218:219], v[224:225], 0, s[10:11]
	s_mov_b32 m0, s60
	s_nop 0
	global_load_lds_dwordx4 v[218:219], off
	s_waitcnt vmcnt(8)
	s_waitcnt lgkmcnt(0)
	s_barrier
	s_setprio 1
	s_waitcnt lgkmcnt(0)
	v_mfma_f32_16x16x32_bf16 v[62:65], v[148:151], v[186:189], v[62:65]
	v_mfma_f32_16x16x32_bf16 v[58:61], v[160:163], v[186:189], v[58:61]
	v_mfma_f32_16x16x32_bf16 v[50:53], v[148:151], v[194:197], v[50:53]
	v_mfma_f32_16x16x32_bf16 v[42:45], v[160:163], v[194:197], v[42:45]
	v_mfma_f32_16x16x32_bf16 v[34:37], v[148:151], v[202:205], v[34:37]
	v_mfma_f32_16x16x32_bf16 v[26:29], v[160:163], v[202:205], v[26:29]
	v_mfma_f32_16x16x32_bf16 v[18:21], v[148:151], v[210:213], v[18:21]
	v_mfma_f32_16x16x32_bf16 v[10:13], v[160:163], v[210:213], v[10:13]
	v_mfma_f32_16x16x32_bf16 v[62:65], v[152:155], v[190:193], v[62:65]
	v_mfma_f32_16x16x32_bf16 v[58:61], v[164:167], v[190:193], v[58:61]
	v_mfma_f32_16x16x32_bf16 v[50:53], v[152:155], v[198:201], v[50:53]
	v_mfma_f32_16x16x32_bf16 v[42:45], v[164:167], v[198:201], v[42:45]
	v_mfma_f32_16x16x32_bf16 v[34:37], v[152:155], v[206:209], v[34:37]
	v_mfma_f32_16x16x32_bf16 v[26:29], v[164:167], v[206:209], v[26:29]
	v_mfma_f32_16x16x32_bf16 v[18:21], v[152:155], v[214:217], v[18:21]
	v_mfma_f32_16x16x32_bf16 v[10:13], v[164:167], v[214:217], v[10:13]
	s_setprio 0
	s_setprio 1
	v_mfma_f32_16x16x32_bf16 v[54:57], v[168:171], v[186:189], v[54:57]
	v_mfma_f32_16x16x32_bf16 v[46:49], v[178:181], v[186:189], v[46:49]
	v_mfma_f32_16x16x32_bf16 v[38:41], v[168:171], v[194:197], v[38:41]
	v_mfma_f32_16x16x32_bf16 v[30:33], v[178:181], v[194:197], v[30:33]
	v_mfma_f32_16x16x32_bf16 v[22:25], v[168:171], v[202:205], v[22:25]
	v_mfma_f32_16x16x32_bf16 v[14:17], v[178:181], v[202:205], v[14:17]
	v_mfma_f32_16x16x32_bf16 v[6:9], v[168:171], v[210:213], v[6:9]
	v_mfma_f32_16x16x32_bf16 v[2:5], v[178:181], v[210:213], v[2:5]
	v_mfma_f32_16x16x32_bf16 v[54:57], v[174:177], v[190:193], v[54:57]
	v_mfma_f32_16x16x32_bf16 v[46:49], v[182:185], v[190:193], v[46:49]
	v_mfma_f32_16x16x32_bf16 v[38:41], v[174:177], v[198:201], v[38:41]
	v_mfma_f32_16x16x32_bf16 v[30:33], v[182:185], v[198:201], v[30:33]
	v_mfma_f32_16x16x32_bf16 v[22:25], v[174:177], v[206:209], v[22:25]
	v_mfma_f32_16x16x32_bf16 v[14:17], v[182:185], v[206:209], v[14:17]
	v_mfma_f32_16x16x32_bf16 v[6:9], v[174:177], v[214:217], v[6:9]
	v_mfma_f32_16x16x32_bf16 v[2:5], v[182:185], v[214:217], v[2:5]
	s_setprio 0
	s_barrier

; template <class Epi, class Sched, bool ALIGN_EPI = false, bool SP2 = false>
; __device__ __forceinline__ void gemm_phase(PG8_LAS unsigned char* lds, const Gemm g, const Sched& S, const Epi& E) {
;     ...
;         for (int t = 0; t < nt; t += 2) {
;             const bool last = (t == nt - 2);
;             const char* a1 = cA + (size_t)(t + 1) * kstep;
;             const char* a2 = last ? nA : cA + (size_t)(t + 2) * kstep; const char* b2 = last ? nB : cB + (size_t)(t + 2) * kstep;
;             const char* a3 = a2 + kstep; const char* b3 = b2 + kstep;
	s_add_i32 s74, s74, 2
	s_add_u32 s28, s28, 0x100
	s_addc_u32 s29, s29, 0
	s_add_u32 s72, s72, 0x100
	s_addc_u32 s73, s73, 0

; #define PG8_STAGE(bufoff, gbase, voff) do { _Pragma("unroll") for (int _i = 0; _i < 2; ++_i) \
;         __builtin_amdgcn_global_load_lds((const unsigned*)((const char*)(gbase) + (voff)[_i]), (PG8_LAS unsigned*)(lds + (bufoff) + ldsw + _i * 8192), 16, 0, 0); } while (0)
; #define PG8_LDA(dst, b, h) do { _Pragma("unroll") for (int m = 0; m < 4; ++m) _Pragma("unroll") for (int k = 0; k < 2; ++k) dst[m][k] = *(const PG8_LAS bf16x8*)(lds + PG8_SA(b, h) + aoff + m * 2048 + k * 1024); } while (0)
; #define PG8_LDB(dst, b, h) do { _Pragma("unroll") for (int n = 0; n < 2; ++n) _Pragma("unroll") for (int k = 0; k < 2; ++k) dst[n][k] = *(const PG8_LAS bf16x8*)(lds + PG8_SB(b, h) + boff + n * 2048 + k * 1024); } while (0)
; #define PG8_SCHED __builtin_amdgcn_sched_barrier(0)
; template <class Epi, class Sched, bool ALIGN_EPI = false, bool SP2 = false>
; __device__ __forceinline__ void gemm_phase(PG8_LAS unsigned char* lds, const Gemm g, const Sched& S, const Epi& E) {
;     ...
;         const bool has_next = S.next(ui + 1, nxt);
;         const char* nA = has_next ? (const char*)g.A + (size_t)nxt.pm * tstep : cA; const char* nB = has_next ? (const char*)g.Bt + (size_t)nxt.pn * tstep : cB;
; #pragma nounroll
;         for (int t = 0; t < nt; t += 2) {
;             const bool last = (t == nt - 2);
;             const char* a1 = cA + (size_t)(t + 1) * kstep;
;             const char* a2 = last ? nA : cA + (size_t)(t + 2) * kstep; const char* b2 = last ? nB : cB + (size_t)(t + 2) * kstep;
;             const char* a3 = a2 + kstep; const char* b3 = b2 + kstep;
;             if (last && has_next) S.a_ready(nxt);
;             if constexpr (SP2) {
;             PG8_LDB(B0, 0, 0); PG8_LDB(B1, 0, 1); PG8_SCHED; PG8_LDA(At, 0, 0); PG8_STAGE(PG8_SA(1, 1), a1 + hstep, voffA);
;     ...
; #pragma unroll
;         for (int a = 0; a < 2; ++a)
; #pragma unroll
;             for (int b = 0; b < 2; ++b)
; #pragma unroll
;                 for (int m = 0; m < 4; ++m)
; #pragma unroll
;                     for (int n = 0; n < 2; ++n) acc[a][b][m][n] = (f32x4){0.f, 0.f, 0.f, 0.f};
.LBB0_1220:
	s_ashr_i32 s29, s28, 31
	s_lshl_b64 s[30:31], s[28:29], 19
	s_add_u32 s30, s44, s30
	s_addc_u32 s31, s45, s31
	s_and_b64 s[34:35], s[2:3], exec
	s_cselect_b32 s29, s31, s39
	s_cselect_b32 s67, s30, s38
	s_ashr_i32 s27, s26, 31
	s_lshl_b64 s[34:35], s[26:27], 19
	s_add_u32 s34, s52, s34
	s_addc_u32 s35, s53, s35
	s_and_b64 s[42:43], s[2:3], exec
	s_cselect_b32 s27, s35, s41
	s_cselect_b32 s68, s34, s40
	s_add_u32 s38, s38, 0x40080
	s_addc_u32 s39, s39, 0
	s_add_u32 s69, s40, 0x100
	v_mov_b32_e32 v2, 0
	s_addc_u32 s70, s41, 0
	s_mov_b32 s71, -2
	v_mov_b32_e32 v3, v2
	v_mov_b32_e32 v4, v2
	v_mov_b32_e32 v5, v2
	v_mov_b32_e32 v6, v2
	v_mov_b32_e32 v7, v2
	v_mov_b32_e32 v8, v2
	v_mov_b32_e32 v9, v2
	v_mov_b32_e32 v18, v2
	v_mov_b32_e32 v19, v2
	v_mov_b32_e32 v20, v2
	v_mov_b32_e32 v21, v2
	v_mov_b32_e32 v22, v2
	v_mov_b32_e32 v23, v2
	v_mov_b32_e32 v24, v2
	v_mov_b32_e32 v25, v2
	v_mov_b32_e32 v34, v2
	v_mov_b32_e32 v35, v2
	v_mov_b32_e32 v36, v2
	v_mov_b32_e32 v37, v2
	v_mov_b32_e32 v38, v2
	v_mov_b32_e32 v39, v2
	v_mov_b32_e32 v40, v2
	v_mov_b32_e32 v41, v2
	v_mov_b32_e32 v50, v2
	v_mov_b32_e32 v51, v2
	v_mov_b32_e32 v52, v2
	v_mov_b32_e32 v53, v2
	v_mov_b32_e32 v54, v2
	v_mov_b32_e32 v55, v2
	v_mov_b32_e32 v56, v2
	v_mov_b32_e32 v57, v2
	v_mov_b32_e32 v10, v2
	v_mov_b32_e32 v11, v2
	v_mov_b32_e32 v12, v2
	v_mov_b32_e32 v13, v2
	v_mov_b32_e32 v14, v2
	v_mov_b32_e32 v15, v2
	v_mov_b32_e32 v16, v2
	v_mov_b32_e32 v17, v2
	v_mov_b32_e32 v26, v2
	v_mov_b32_e32 v27, v2
	v_mov_b32_e32 v28, v2
	v_mov_b32_e32 v29, v2
	v_mov_b32_e32 v30, v2
	v_mov_b32_e32 v31, v2
	v_mov_b32_e32 v32, v2
	v_mov_b32_e32 v33, v2
	v_mov_b32_e32 v42, v2
	v_mov_b32_e32 v43, v2
	v_mov_b32_e32 v44, v2
	v_mov_b32_e32 v45, v2
	v_mov_b32_e32 v46, v2
	v_mov_b32_e32 v47, v2
	v_mov_b32_e32 v48, v2
	v_mov_b32_e32 v49, v2
	v_mov_b32_e32 v58, v2
	v_mov_b32_e32 v59, v2
	v_mov_b32_e32 v60, v2
	v_mov_b32_e32 v61, v2
	v_mov_b32_e32 v62, v2
	v_mov_b32_e32 v63, v2
	v_mov_b32_e32 v64, v2
	v_mov_b32_e32 v65, v2
	v_mov_b32_e32 v66, v2
	v_mov_b32_e32 v67, v2
	v_mov_b32_e32 v68, v2
	v_mov_b32_e32 v69, v2
	v_mov_b32_e32 v70, v2
	v_mov_b32_e32 v71, v2
	v_mov_b32_e32 v72, v2
	v_mov_b32_e32 v73, v2
	v_mov_b32_e32 v82, v2
	v_mov_b32_e32 v83, v2
	v_mov_b32_e32 v84, v2
	v_mov_b32_e32 v85, v2
	v_mov_b32_e32 v86, v2
	v_mov_b32_e32 v87, v2
	v_mov_b32_e32 v88, v2
	v_mov_b32_e32 v89, v2
	v_mov_b32_e32 v98, v2
	v_mov_b32_e32 v99, v2
	v_mov_b32_e32 v100, v2
	v_mov_b32_e32 v101, v2
	v_mov_b32_e32 v102, v2
	v_mov_b32_e32 v103, v2
	v_mov_b32_e32 v104, v2
	v_mov_b32_e32 v105, v2
	v_mov_b32_e32 v114, v2
	v_mov_b32_e32 v115, v2
	v_mov_b32_e32 v116, v2
	v_mov_b32_e32 v117, v2
	v_mov_b32_e32 v118, v2
	v_mov_b32_e32 v119, v2
	v_mov_b32_e32 v120, v2
	v_mov_b32_e32 v121, v2
	v_mov_b32_e32 v74, v2
	v_mov_b32_e32 v75, v2
	v_mov_b32_e32 v76, v2
	v_mov_b32_e32 v77, v2
	v_mov_b32_e32 v78, v2
	v_mov_b32_e32 v79, v2
	v_mov_b32_e32 v80, v2
	v_mov_b32_e32 v81, v2
	v_mov_b32_e32 v90, v2
	v_mov_b32_e32 v91, v2
	v_mov_b32_e32 v92, v2
	v_mov_b32_e32 v93, v2
	v_mov_b32_e32 v94, v2
	v_mov_b32_e32 v95, v2
	v_mov_b32_e32 v96, v2
	v_mov_b32_e32 v97, v2
	v_mov_b32_e32 v106, v2
	v_mov_b32_e32 v107, v2
	v_mov_b32_e32 v108, v2
	v_mov_b32_e32 v109, v2
	v_mov_b32_e32 v110, v2
	v_mov_b32_e32 v111, v2
	v_mov_b32_e32 v112, v2
	v_mov_b32_e32 v113, v2
	v_mov_b32_e32 v122, v2
	v_mov_b32_e32 v123, v2
	v_mov_b32_e32 v124, v2
	v_mov_b32_e32 v125, v2
	v_mov_b32_e32 v126, v2
	v_mov_b32_e32 v127, v2
	v_mov_b32_e32 v128, v2
	v_mov_b32_e32 v129, v2
	ds_read_b128 v[154:157], v150
	ds_read_b128 v[158:161], v150 offset:1024
	ds_read_b128 v[162:165], v150 offset:2048
	ds_read_b128 v[166:169], v150 offset:3072
	ds_read_b128 v[174:177], v151
	ds_read_b128 v[178:181], v151 offset:1024
	ds_read_b128 v[182:185], v151 offset:2048
	ds_read_b128 v[186:189], v151 offset:3072
	s_add_u32 s40, s38, 0xfffc0080
	s_addc_u32 s41, s39, -1
	s_cmp_eq_u32 s71, 12
	s_cselect_b32 s43, s29, s41
	s_cselect_b32 s42, s67, s40
	s_cselect_b32 s41, s27, s70
	s_cselect_b32 s40, s68, s69

; #define PG8_STAGE(bufoff, gbase, voff) do { _Pragma("unroll") for (int _i = 0; _i < 2; ++_i) \
;         __builtin_amdgcn_global_load_lds((const unsigned*)((const char*)(gbase) + (voff)[_i]), (PG8_LAS unsigned*)(lds + (bufoff) + ldsw + _i * 8192), 16, 0, 0); } while (0)
; #define PG8_LDA(dst, b, h) do { _Pragma("unroll") for (int m = 0; m < 4; ++m) _Pragma("unroll") for (int k = 0; k < 2; ++k) dst[m][k] = *(const PG8_LAS bf16x8*)(lds + PG8_SA(b, h) + aoff + m * 2048 + k * 1024); } while (0)
; #define PG8_LDB(dst, b, h) do { _Pragma("unroll") for (int n = 0; n < 2; ++n) _Pragma("unroll") for (int k = 0; k < 2; ++k) dst[n][k] = *(const PG8_LAS bf16x8*)(lds + PG8_SB(b, h) + boff + n * 2048 + k * 1024); } while (0)
; #define PG8_MMA(ai, bj, At, Bt) do { __builtin_amdgcn_s_setprio(1); _Pragma("unroll") for (int m = 0; m < 4; ++m) _Pragma("unroll") for (int n = 0; n < 2; ++n) _Pragma("unroll") for (int k = 0; k < 2; ++k) \
;         acc[ai][bj][m][n] = __builtin_amdgcn_mfma_f32_16x16x32_bf16(Bt[n][k], At[m][k], acc[ai][bj][m][n], 0, 0, 0); __builtin_amdgcn_s_setprio(0); } while (0)
; #define PG8_WAIT_V(n) asm volatile("s_waitcnt vmcnt(" #n ")" ::: "memory")
; #define PG8_WAIT_L(n) asm volatile("s_waitcnt lgkmcnt(" #n ")" ::: "memory")
; #define PG8_BAR __builtin_amdgcn_s_barrier()
; #define PG8_SCHED __builtin_amdgcn_sched_barrier(0)
; template <class Epi, class Sched, bool ALIGN_EPI = false, bool SP2 = false>
; __device__ __forceinline__ void gemm_phase(PG8_LAS unsigned char* lds, const Gemm g, const Sched& S, const Epi& E) {
;     ...
;             PG8_LDB(B0, 0, 0); PG8_LDB(B1, 0, 1); PG8_SCHED; PG8_LDA(At, 0, 0); PG8_STAGE(PG8_SA(1, 1), a1 + hstep, voffA);
;             PG8_WAIT_V(8); PG8_WAIT_L(0); PG8_BAR; PG8_MMA(0, 0, At, B0); PG8_MMA(0, 1, At, B1); PG8_BAR; PG8_SCHED;
	v_lshl_add_u64 v[146:147], s[38:39], 0, v[138:139]
	s_add_i32 m0, s55, 0xc000
	ds_read_b128 v[190:193], v152
	ds_read_b128 v[194:197], v152 offset:1024
	ds_read_b128 v[198:201], v152 offset:2048
	ds_read_b128 v[202:205], v152 offset:3072
	ds_read_b128 v[206:209], v152 offset:4096
	ds_read_b128 v[210:213], v152 offset:5120
	ds_read_b128 v[214:217], v152 offset:6144
	ds_read_b128 v[218:221], v152 offset:7168
	global_load_lds_dwordx4 v[146:147], off
	v_lshl_add_u64 v[146:147], s[38:39], 0, v[140:141]
	s_add_i32 m0, s55, 0xe000
	s_nop 0
	global_load_lds_dwordx4 v[146:147], off
	s_waitcnt vmcnt(24)
	s_waitcnt lgkmcnt(0)
	s_barrier
	s_setprio 1
	s_waitcnt lgkmcnt(0)
	v_mfma_f32_16x16x32_bf16 v[126:129], v[154:157], v[190:193], v[126:129]
	v_mfma_f32_16x16x32_bf16 v[122:125], v[162:165], v[190:193], v[122:125]
	v_mfma_f32_16x16x32_bf16 v[110:113], v[154:157], v[198:201], v[110:113]
	v_mfma_f32_16x16x32_bf16 v[106:109], v[162:165], v[198:201], v[106:109]
	v_mfma_f32_16x16x32_bf16 v[94:97], v[154:157], v[206:209], v[94:97]
	v_mfma_f32_16x16x32_bf16 v[90:93], v[162:165], v[206:209], v[90:93]
	v_mfma_f32_16x16x32_bf16 v[78:81], v[154:157], v[214:217], v[78:81]
	v_mfma_f32_16x16x32_bf16 v[74:77], v[162:165], v[214:217], v[74:77]
	v_mfma_f32_16x16x32_bf16 v[126:129], v[158:161], v[194:197], v[126:129]
	v_mfma_f32_16x16x32_bf16 v[122:125], v[166:169], v[194:197], v[122:125]
	v_mfma_f32_16x16x32_bf16 v[110:113], v[158:161], v[202:205], v[110:113]
	v_mfma_f32_16x16x32_bf16 v[106:109], v[166:169], v[202:205], v[106:109]
	v_mfma_f32_16x16x32_bf16 v[94:97], v[158:161], v[210:213], v[94:97]
	v_mfma_f32_16x16x32_bf16 v[90:93], v[166:169], v[210:213], v[90:93]
	v_mfma_f32_16x16x32_bf16 v[78:81], v[158:161], v[218:221], v[78:81]
	v_mfma_f32_16x16x32_bf16 v[74:77], v[166:169], v[218:221], v[74:77]
	s_setprio 0
	s_setprio 1
	v_mfma_f32_16x16x32_bf16 v[118:121], v[174:177], v[190:193], v[118:121]
	v_mfma_f32_16x16x32_bf16 v[114:117], v[182:185], v[190:193], v[114:117]
	v_mfma_f32_16x16x32_bf16 v[102:105], v[174:177], v[198:201], v[102:105]
	v_mfma_f32_16x16x32_bf16 v[98:101], v[182:185], v[198:201], v[98:101]
	v_mfma_f32_16x16x32_bf16 v[86:89], v[174:177], v[206:209], v[86:89]
	v_mfma_f32_16x16x32_bf16 v[82:85], v[182:185], v[206:209], v[82:85]
	v_mfma_f32_16x16x32_bf16 v[70:73], v[174:177], v[214:217], v[70:73]
	v_mfma_f32_16x16x32_bf16 v[66:69], v[182:185], v[214:217], v[66:69]
	v_mfma_f32_16x16x32_bf16 v[118:121], v[178:181], v[194:197], v[118:121]
	v_mfma_f32_16x16x32_bf16 v[114:117], v[186:189], v[194:197], v[114:117]
	v_mfma_f32_16x16x32_bf16 v[102:105], v[178:181], v[202:205], v[102:105]
	v_mfma_f32_16x16x32_bf16 v[98:101], v[186:189], v[202:205], v[98:101]
	v_mfma_f32_16x16x32_bf16 v[86:89], v[178:181], v[210:213], v[86:89]
	v_mfma_f32_16x16x32_bf16 v[82:85], v[186:189], v[210:213], v[82:85]
	v_mfma_f32_16x16x32_bf16 v[70:73], v[178:181], v[218:221], v[70:73]
	v_mfma_f32_16x16x32_bf16 v[66:69], v[186:189], v[218:221], v[66:69]
	s_setprio 0
	s_barrier

; #define PG8_STAGE(bufoff, gbase, voff) do { _Pragma("unroll") for (int _i = 0; _i < 2; ++_i) \
;         __builtin_amdgcn_global_load_lds((const unsigned*)((const char*)(gbase) + (voff)[_i]), (PG8_LAS unsigned*)(lds + (bufoff) + ldsw + _i * 8192), 16, 0, 0); } while (0)
; #define PG8_LDA(dst, b, h) do { _Pragma("unroll") for (int m = 0; m < 4; ++m) _Pragma("unroll") for (int k = 0; k < 2; ++k) dst[m][k] = *(const PG8_LAS bf16x8*)(lds + PG8_SA(b, h) + aoff + m * 2048 + k * 1024); } while (0)
; #define PG8_MMA(ai, bj, At, Bt) do { __builtin_amdgcn_s_setprio(1); _Pragma("unroll") for (int m = 0; m < 4; ++m) _Pragma("unroll") for (int n = 0; n < 2; ++n) _Pragma("unroll") for (int k = 0; k < 2; ++k) \
;         acc[ai][bj][m][n] = __builtin_amdgcn_mfma_f32_16x16x32_bf16(Bt[n][k], At[m][k], acc[ai][bj][m][n], 0, 0, 0); __builtin_amdgcn_s_setprio(0); } while (0)
; #define PG8_WAIT_V(n) asm volatile("s_waitcnt vmcnt(" #n ")" ::: "memory")
; #define PG8_WAIT_L(n) asm volatile("s_waitcnt lgkmcnt(" #n ")" ::: "memory")
; #define PG8_BAR __builtin_amdgcn_s_barrier()
; #define PG8_SCHED __builtin_amdgcn_sched_barrier(0)
; template <class Epi, class Sched, bool ALIGN_EPI = false, bool SP2 = false>
; __device__ __forceinline__ void gemm_phase(PG8_LAS unsigned char* lds, const Gemm g, const Sched& S, const Epi& E) {
;     ...
;             PG8_LDA(At, 0, 1); PG8_STAGE(PG8_SB(0, 0), b2, voffB); PG8_STAGE(PG8_SB(0, 1), b2 + hstep, voffB); PG8_STAGE(PG8_SA(0, 0), a2, voffA);
;             PG8_WAIT_V(8); PG8_WAIT_L(0); PG8_BAR; PG8_MMA(1, 0, At, B0); PG8_MMA(1, 1, At, B1); PG8_BAR; PG8_SCHED;
	s_add_i32 s72, s64, s54
	v_lshl_add_u64 v[146:147], s[40:41], 0, v[132:133]
	s_mov_b32 m0, s72
	ds_read_b128 v[190:193], v152 offset:16384
	ds_read_b128 v[194:197], v152 offset:17408
	ds_read_b128 v[198:201], v152 offset:18432
	ds_read_b128 v[202:205], v152 offset:19456
	ds_read_b128 v[206:209], v152 offset:20480
	ds_read_b128 v[210:213], v152 offset:21504
	ds_read_b128 v[214:217], v152 offset:22528
	ds_read_b128 v[218:221], v152 offset:23552
	global_load_lds_dwordx4 v[146:147], off
	s_add_i32 m0, s72, 0x2000
	s_add_u32 s72, s40, 0x40000
	v_lshl_add_u64 v[170:171], s[40:41], 0, v[136:137]
	s_addc_u32 s73, s41, 0
	s_add_i32 s74, s65, s54
	global_load_lds_dwordx4 v[170:171], off
	v_lshl_add_u64 v[222:223], s[72:73], 0, v[132:133]
	s_mov_b32 m0, s74
	v_lshl_add_u64 v[224:225], s[42:43], 0, v[134:135]
	global_load_lds_dwordx4 v[222:223], off
	v_lshl_add_u64 v[222:223], s[72:73], 0, v[136:137]
	s_add_i32 m0, s74, 0x2000
	s_nop 0
	global_load_lds_dwordx4 v[222:223], off
	v_lshl_add_u64 v[222:223], s[42:43], 0, v[130:131]
	s_mov_b32 m0, s55
	s_nop 0
	global_load_lds_dwordx4 v[222:223], off
	s_mov_b32 m0, s56
	s_nop 0
	global_load_lds_dwordx4 v[224:225], off
	s_waitcnt vmcnt(24)
	s_waitcnt lgkmcnt(0)
	s_barrier
	s_setprio 1
	s_waitcnt lgkmcnt(0)
	v_mfma_f32_16x16x32_bf16 v[62:65], v[154:157], v[190:193], v[62:65]
	v_mfma_f32_16x16x32_bf16 v[58:61], v[162:165], v[190:193], v[58:61]
	v_mfma_f32_16x16x32_bf16 v[46:49], v[154:157], v[198:201], v[46:49]
	v_mfma_f32_16x16x32_bf16 v[42:45], v[162:165], v[198:201], v[42:45]
	v_mfma_f32_16x16x32_bf16 v[30:33], v[154:157], v[206:209], v[30:33]
	v_mfma_f32_16x16x32_bf16 v[26:29], v[162:165], v[206:209], v[26:29]
	v_mfma_f32_16x16x32_bf16 v[14:17], v[154:157], v[214:217], v[14:17]
	v_mfma_f32_16x16x32_bf16 v[10:13], v[162:165], v[214:217], v[10:13]
	v_mfma_f32_16x16x32_bf16 v[62:65], v[158:161], v[194:197], v[62:65]
	v_mfma_f32_16x16x32_bf16 v[58:61], v[166:169], v[194:197], v[58:61]
	v_mfma_f32_16x16x32_bf16 v[46:49], v[158:161], v[202:205], v[46:49]
	v_mfma_f32_16x16x32_bf16 v[42:45], v[166:169], v[202:205], v[42:45]
	v_mfma_f32_16x16x32_bf16 v[30:33], v[158:161], v[210:213], v[30:33]
	v_mfma_f32_16x16x32_bf16 v[26:29], v[166:169], v[210:213], v[26:29]
	v_mfma_f32_16x16x32_bf16 v[14:17], v[158:161], v[218:221], v[14:17]
	v_mfma_f32_16x16x32_bf16 v[10:13], v[166:169], v[218:221], v[10:13]
	s_setprio 0
	s_setprio 1
	v_mfma_f32_16x16x32_bf16 v[54:57], v[174:177], v[190:193], v[54:57]
	v_mfma_f32_16x16x32_bf16 v[50:53], v[182:185], v[190:193], v[50:53]
	v_mfma_f32_16x16x32_bf16 v[38:41], v[174:177], v[198:201], v[38:41]
	v_mfma_f32_16x16x32_bf16 v[34:37], v[182:185], v[198:201], v[34:37]
	v_mfma_f32_16x16x32_bf16 v[22:25], v[174:177], v[206:209], v[22:25]
	v_mfma_f32_16x16x32_bf16 v[18:21], v[182:185], v[206:209], v[18:21]
	v_mfma_f32_16x16x32_bf16 v[6:9], v[174:177], v[214:217], v[6:9]
	v_mfma_f32_16x16x32_bf16 v[2:5], v[182:185], v[214:217], v[2:5]
	v_mfma_f32_16x16x32_bf16 v[54:57], v[178:181], v[194:197], v[54:57]
	v_mfma_f32_16x16x32_bf16 v[50:53], v[186:189], v[194:197], v[50:53]
	v_mfma_f32_16x16x32_bf16 v[38:41], v[178:181], v[202:205], v[38:41]
	v_mfma_f32_16x16x32_bf16 v[34:37], v[186:189], v[202:205], v[34:37]
	v_mfma_f32_16x16x32_bf16 v[22:25], v[178:181], v[210:213], v[22:25]
	v_mfma_f32_16x16x32_bf16 v[18:21], v[186:189], v[210:213], v[18:21]
	v_mfma_f32_16x16x32_bf16 v[6:9], v[178:181], v[218:221], v[6:9]
	v_mfma_f32_16x16x32_bf16 v[2:5], v[186:189], v[218:221], v[2:5]
	s_setprio 0
	s_barrier

; #define PG8_STAGE(bufoff, gbase, voff) do { _Pragma("unroll") for (int _i = 0; _i < 2; ++_i) \
;         __builtin_amdgcn_global_load_lds((const unsigned*)((const char*)(gbase) + (voff)[_i]), (PG8_LAS unsigned*)(lds + (bufoff) + ldsw + _i * 8192), 16, 0, 0); } while (0)
; #define PG8_LDA(dst, b, h) do { _Pragma("unroll") for (int m = 0; m < 4; ++m) _Pragma("unroll") for (int k = 0; k < 2; ++k) dst[m][k] = *(const PG8_LAS bf16x8*)(lds + PG8_SA(b, h) + aoff + m * 2048 + k * 1024); } while (0)
; #define PG8_LDB(dst, b, h) do { _Pragma("unroll") for (int n = 0; n < 2; ++n) _Pragma("unroll") for (int k = 0; k < 2; ++k) dst[n][k] = *(const PG8_LAS bf16x8*)(lds + PG8_SB(b, h) + boff + n * 2048 + k * 1024); } while (0)
; #define PG8_SCHED __builtin_amdgcn_sched_barrier(0)
; template <class Epi, class Sched, bool ALIGN_EPI = false, bool SP2 = false>
; __device__ __forceinline__ void gemm_phase(PG8_LAS unsigned char* lds, const Gemm g, const Sched& S, const Epi& E) {
;     ...
;             PG8_LDB(B0, 1, 0); PG8_LDB(B1, 1, 1); PG8_SCHED; PG8_LDA(At, 1, 0); PG8_STAGE(PG8_SA(0, 1), a2 + hstep, voffA);
	s_add_i32 s72, 0, 0x18000
	v_add_u32_e32 v153, s72, v148
	s_add_i32 s73, 0, 0x1c000
	ds_read_b128 v[154:157], v153
	ds_read_b128 v[158:161], v153 offset:1024
	ds_read_b128 v[162:165], v153 offset:2048
	ds_read_b128 v[166:169], v153 offset:3072
	v_add_u32_e32 v153, s73, v148
	ds_read_b128 v[174:177], v153
	ds_read_b128 v[178:181], v153 offset:1024
	ds_read_b128 v[182:185], v153 offset:2048
	ds_read_b128 v[186:189], v153 offset:3072

; #define PG8_STAGE(bufoff, gbase, voff) do { _Pragma("unroll") for (int _i = 0; _i < 2; ++_i) \
;         __builtin_amdgcn_global_load_lds((const unsigned*)((const char*)(gbase) + (voff)[_i]), (PG8_LAS unsigned*)(lds + (bufoff) + ldsw + _i * 8192), 16, 0, 0); } while (0)
; #define PG8_LDA(dst, b, h) do { _Pragma("unroll") for (int m = 0; m < 4; ++m) _Pragma("unroll") for (int k = 0; k < 2; ++k) dst[m][k] = *(const PG8_LAS bf16x8*)(lds + PG8_SA(b, h) + aoff + m * 2048 + k * 1024); } while (0)
; #define PG8_LDB(dst, b, h) do { _Pragma("unroll") for (int n = 0; n < 2; ++n) _Pragma("unroll") for (int k = 0; k < 2; ++k) dst[n][k] = *(const PG8_LAS bf16x8*)(lds + PG8_SB(b, h) + boff + n * 2048 + k * 1024); } while (0)
; #define PG8_MMA(ai, bj, At, Bt) do { __builtin_amdgcn_s_setprio(1); _Pragma("unroll") for (int m = 0; m < 4; ++m) _Pragma("unroll") for (int n = 0; n < 2; ++n) _Pragma("unroll") for (int k = 0; k < 2; ++k) \
;         acc[ai][bj][m][n] = __builtin_amdgcn_mfma_f32_16x16x32_bf16(Bt[n][k], At[m][k], acc[ai][bj][m][n], 0, 0, 0); __builtin_amdgcn_s_setprio(0); } while (0)
; #define PG8_WAIT_V(n) asm volatile("s_waitcnt vmcnt(" #n ")" ::: "memory")
; #define PG8_WAIT_L(n) asm volatile("s_waitcnt lgkmcnt(" #n ")" ::: "memory")
; #define PG8_BAR __builtin_amdgcn_s_barrier()
; #define PG8_SCHED __builtin_amdgcn_sched_barrier(0)
; template <class Epi, class Sched, bool ALIGN_EPI = false, bool SP2 = false>
; __device__ __forceinline__ void gemm_phase(PG8_LAS unsigned char* lds, const Gemm g, const Sched& S, const Epi& E) {
;     ...
;             PG8_LDB(B0, 1, 0); PG8_LDB(B1, 1, 1); PG8_SCHED; PG8_LDA(At, 1, 0); PG8_STAGE(PG8_SA(0, 1), a2 + hstep, voffA);
;             PG8_WAIT_V(8); PG8_WAIT_L(0); PG8_BAR; PG8_MMA(0, 0, At, B0); PG8_MMA(0, 1, At, B1); PG8_BAR; PG8_SCHED;
	s_add_u32 s42, s42, 0x40000
	s_addc_u32 s43, s43, 0
	s_mov_b32 m0, s57
	v_lshl_add_u64 v[226:227], s[42:43], 0, v[130:131]
	ds_read_b128 v[190:193], v152 offset:32768
	ds_read_b128 v[194:197], v152 offset:33792
	ds_read_b128 v[198:201], v152 offset:34816
	ds_read_b128 v[202:205], v152 offset:35840
	ds_read_b128 v[206:209], v152 offset:36864
	ds_read_b128 v[210:213], v152 offset:37888
	ds_read_b128 v[214:217], v152 offset:38912
	ds_read_b128 v[218:221], v152 offset:39936
	global_load_lds_dwordx4 v[226:227], off
	v_lshl_add_u64 v[226:227], s[42:43], 0, v[134:135]
	s_mov_b32 m0, s58
	s_nop 0
	global_load_lds_dwordx4 v[226:227], off
	s_waitcnt vmcnt(8)
	s_waitcnt lgkmcnt(0)
	s_barrier
	s_setprio 1
	s_waitcnt lgkmcnt(0)
	v_mfma_f32_16x16x32_bf16 v[126:129], v[154:157], v[190:193], v[126:129]
	v_mfma_f32_16x16x32_bf16 v[122:125], v[162:165], v[190:193], v[122:125]
	v_mfma_f32_16x16x32_bf16 v[110:113], v[154:157], v[198:201], v[110:113]
	v_mfma_f32_16x16x32_bf16 v[106:109], v[162:165], v[198:201], v[106:109]
	v_mfma_f32_16x16x32_bf16 v[94:97], v[154:157], v[206:209], v[94:97]
	v_mfma_f32_16x16x32_bf16 v[90:93], v[162:165], v[206:209], v[90:93]
	v_mfma_f32_16x16x32_bf16 v[78:81], v[154:157], v[214:217], v[78:81]
	v_mfma_f32_16x16x32_bf16 v[74:77], v[162:165], v[214:217], v[74:77]
	v_mfma_f32_16x16x32_bf16 v[126:129], v[158:161], v[194:197], v[126:129]
	v_mfma_f32_16x16x32_bf16 v[122:125], v[166:169], v[194:197], v[122:125]
	v_mfma_f32_16x16x32_bf16 v[110:113], v[158:161], v[202:205], v[110:113]
	v_mfma_f32_16x16x32_bf16 v[106:109], v[166:169], v[202:205], v[106:109]
	v_mfma_f32_16x16x32_bf16 v[94:97], v[158:161], v[210:213], v[94:97]
	v_mfma_f32_16x16x32_bf16 v[90:93], v[166:169], v[210:213], v[90:93]
	v_mfma_f32_16x16x32_bf16 v[78:81], v[158:161], v[218:221], v[78:81]
	v_mfma_f32_16x16x32_bf16 v[74:77], v[166:169], v[218:221], v[74:77]
	s_setprio 0
	s_setprio 1
	v_mfma_f32_16x16x32_bf16 v[118:121], v[174:177], v[190:193], v[118:121]
	v_mfma_f32_16x16x32_bf16 v[114:117], v[182:185], v[190:193], v[114:117]
	v_mfma_f32_16x16x32_bf16 v[102:105], v[174:177], v[198:201], v[102:105]
	v_mfma_f32_16x16x32_bf16 v[98:101], v[182:185], v[198:201], v[98:101]
	v_mfma_f32_16x16x32_bf16 v[86:89], v[174:177], v[206:209], v[86:89]
	v_mfma_f32_16x16x32_bf16 v[82:85], v[182:185], v[206:209], v[82:85]
	v_mfma_f32_16x16x32_bf16 v[70:73], v[174:177], v[214:217], v[70:73]
	v_mfma_f32_16x16x32_bf16 v[66:69], v[182:185], v[214:217], v[66:69]
	v_mfma_f32_16x16x32_bf16 v[118:121], v[178:181], v[194:197], v[118:121]
	v_mfma_f32_16x16x32_bf16 v[114:117], v[186:189], v[194:197], v[114:117]
	v_mfma_f32_16x16x32_bf16 v[102:105], v[178:181], v[202:205], v[102:105]
	v_mfma_f32_16x16x32_bf16 v[98:101], v[186:189], v[202:205], v[98:101]
	v_mfma_f32_16x16x32_bf16 v[86:89], v[178:181], v[210:213], v[86:89]
	v_mfma_f32_16x16x32_bf16 v[82:85], v[186:189], v[210:213], v[82:85]
	v_mfma_f32_16x16x32_bf16 v[70:73], v[178:181], v[218:221], v[70:73]
	v_mfma_f32_16x16x32_bf16 v[66:69], v[186:189], v[218:221], v[66:69]
	s_setprio 0
	s_barrier

; #define PG8_STAGE(bufoff, gbase, voff) do { _Pragma("unroll") for (int _i = 0; _i < 2; ++_i) \
;         __builtin_amdgcn_global_load_lds((const unsigned*)((const char*)(gbase) + (voff)[_i]), (PG8_LAS unsigned*)(lds + (bufoff) + ldsw + _i * 8192), 16, 0, 0); } while (0)
; #define PG8_LDA(dst, b, h) do { _Pragma("unroll") for (int m = 0; m < 4; ++m) _Pragma("unroll") for (int k = 0; k < 2; ++k) dst[m][k] = *(const PG8_LAS bf16x8*)(lds + PG8_SA(b, h) + aoff + m * 2048 + k * 1024); } while (0)
; #define PG8_MMA(ai, bj, At, Bt) do { __builtin_amdgcn_s_setprio(1); _Pragma("unroll") for (int m = 0; m < 4; ++m) _Pragma("unroll") for (int n = 0; n < 2; ++n) _Pragma("unroll") for (int k = 0; k < 2; ++k) \
;         acc[ai][bj][m][n] = __builtin_amdgcn_mfma_f32_16x16x32_bf16(Bt[n][k], At[m][k], acc[ai][bj][m][n], 0, 0, 0); __builtin_amdgcn_s_setprio(0); } while (0)
; #define PG8_WAIT_V(n) asm volatile("s_waitcnt vmcnt(" #n ")" ::: "memory")
; #define PG8_WAIT_L(n) asm volatile("s_waitcnt lgkmcnt(" #n ")" ::: "memory")
; #define PG8_BAR __builtin_amdgcn_s_barrier()
; #define PG8_SCHED __builtin_amdgcn_sched_barrier(0)
; template <class Epi, class Sched, bool ALIGN_EPI = false, bool SP2 = false>
; __device__ __forceinline__ void gemm_phase(PG8_LAS unsigned char* lds, const Gemm g, const Sched& S, const Epi& E) {
;     ...
;             PG8_LDA(At, 1, 1); PG8_STAGE(PG8_SB(1, 0), b3, voffB); PG8_STAGE(PG8_SB(1, 1), b3 + hstep, voffB); PG8_STAGE(PG8_SA(1, 0), a3, voffA);
;             PG8_WAIT_V(8); PG8_WAIT_L(0); PG8_BAR; PG8_MMA(1, 0, At, B0); PG8_MMA(1, 1, At, B1); PG8_BAR; PG8_SCHED;
	s_add_i32 s42, s72, s54
	v_lshl_add_u64 v[146:147], v[146:147], 0, s[10:11]
	s_mov_b32 m0, s42
	ds_read_b128 v[190:193], v152 offset:49152
	ds_read_b128 v[194:197], v152 offset:50176
	ds_read_b128 v[198:201], v152 offset:51200
	ds_read_b128 v[202:205], v152 offset:52224
	ds_read_b128 v[206:209], v152 offset:53248
	ds_read_b128 v[210:213], v152 offset:54272
	ds_read_b128 v[214:217], v152 offset:55296
	ds_read_b128 v[218:221], v152 offset:56320
	global_load_lds_dwordx4 v[146:147], off
	s_add_i32 m0, s42, 0x2000
	s_add_u32 s40, s40, 0x40080
	v_lshl_add_u64 v[146:147], v[170:171], 0, s[10:11]
	s_addc_u32 s41, s41, 0
	s_add_i32 s42, s73, s54
	global_load_lds_dwordx4 v[146:147], off
	v_lshl_add_u64 v[146:147], s[40:41], 0, v[132:133]
	s_mov_b32 m0, s42
	s_nop 0
	global_load_lds_dwordx4 v[146:147], off
	v_lshl_add_u64 v[146:147], s[40:41], 0, v[136:137]
	s_add_i32 m0, s42, 0x2000
	s_nop 0
	global_load_lds_dwordx4 v[146:147], off
	v_lshl_add_u64 v[146:147], v[222:223], 0, s[10:11]
	s_mov_b32 m0, s60
	s_nop 0
	global_load_lds_dwordx4 v[146:147], off
	v_lshl_add_u64 v[146:147], v[224:225], 0, s[10:11]
	s_mov_b32 m0, s61
	s_nop 0
	global_load_lds_dwordx4 v[146:147], off
	s_waitcnt vmcnt(8)
	s_waitcnt lgkmcnt(0)
	s_barrier
	s_setprio 1
	s_waitcnt lgkmcnt(0)
	v_mfma_f32_16x16x32_bf16 v[62:65], v[154:157], v[190:193], v[62:65]
	v_mfma_f32_16x16x32_bf16 v[58:61], v[162:165], v[190:193], v[58:61]
	v_mfma_f32_16x16x32_bf16 v[46:49], v[154:157], v[198:201], v[46:49]
	v_mfma_f32_16x16x32_bf16 v[42:45], v[162:165], v[198:201], v[42:45]
	v_mfma_f32_16x16x32_bf16 v[30:33], v[154:157], v[206:209], v[30:33]
	v_mfma_f32_16x16x32_bf16 v[26:29], v[162:165], v[206:209], v[26:29]
	v_mfma_f32_16x16x32_bf16 v[14:17], v[154:157], v[214:217], v[14:17]
	v_mfma_f32_16x16x32_bf16 v[10:13], v[162:165], v[214:217], v[10:13]
	v_mfma_f32_16x16x32_bf16 v[62:65], v[158:161], v[194:197], v[62:65]
	v_mfma_f32_16x16x32_bf16 v[58:61], v[166:169], v[194:197], v[58:61]
	v_mfma_f32_16x16x32_bf16 v[46:49], v[158:161], v[202:205], v[46:49]
	v_mfma_f32_16x16x32_bf16 v[42:45], v[166:169], v[202:205], v[42:45]
	v_mfma_f32_16x16x32_bf16 v[30:33], v[158:161], v[210:213], v[30:33]
	v_mfma_f32_16x16x32_bf16 v[26:29], v[166:169], v[210:213], v[26:29]
	v_mfma_f32_16x16x32_bf16 v[14:17], v[158:161], v[218:221], v[14:17]
	v_mfma_f32_16x16x32_bf16 v[10:13], v[166:169], v[218:221], v[10:13]
	s_setprio 0
	s_setprio 1
	v_mfma_f32_16x16x32_bf16 v[54:57], v[174:177], v[190:193], v[54:57]
	v_mfma_f32_16x16x32_bf16 v[50:53], v[182:185], v[190:193], v[50:53]
	v_mfma_f32_16x16x32_bf16 v[38:41], v[174:177], v[198:201], v[38:41]
	v_mfma_f32_16x16x32_bf16 v[34:37], v[182:185], v[198:201], v[34:37]
	v_mfma_f32_16x16x32_bf16 v[22:25], v[174:177], v[206:209], v[22:25]
	v_mfma_f32_16x16x32_bf16 v[18:21], v[182:185], v[206:209], v[18:21]
	v_mfma_f32_16x16x32_bf16 v[6:9], v[174:177], v[214:217], v[6:9]
	v_mfma_f32_16x16x32_bf16 v[2:5], v[182:185], v[214:217], v[2:5]
	v_mfma_f32_16x16x32_bf16 v[54:57], v[178:181], v[194:197], v[54:57]
	v_mfma_f32_16x16x32_bf16 v[50:53], v[186:189], v[194:197], v[50:53]
	v_mfma_f32_16x16x32_bf16 v[38:41], v[178:181], v[202:205], v[38:41]
	v_mfma_f32_16x16x32_bf16 v[34:37], v[186:189], v[202:205], v[34:37]
	v_mfma_f32_16x16x32_bf16 v[22:25], v[178:181], v[210:213], v[22:25]
	v_mfma_f32_16x16x32_bf16 v[18:21], v[186:189], v[210:213], v[18:21]
	v_mfma_f32_16x16x32_bf16 v[6:9], v[178:181], v[218:221], v[6:9]
	v_mfma_f32_16x16x32_bf16 v[2:5], v[186:189], v[218:221], v[2:5]
	s_setprio 0
	s_barrier

; template <class Epi, class Sched, bool ALIGN_EPI = false, bool SP2 = false>
; __device__ __forceinline__ void gemm_phase(PG8_LAS unsigned char* lds, const Gemm g, const Sched& S, const Epi& E) {
;     ...
;         for (int t = 0; t < nt; t += 2) {
;             const bool last = (t == nt - 2);
;             const char* a1 = cA + (size_t)(t + 1) * kstep;
;             const char* a2 = last ? nA : cA + (size_t)(t + 2) * kstep; const char* b2 = last ? nB : cB + (size_t)(t + 2) * kstep;
;             const char* a3 = a2 + kstep; const char* b3 = b2 + kstep;
	s_add_i32 s71, s71, 2
	s_add_u32 s38, s38, 0x100
	s_addc_u32 s39, s39, 0
	s_add_u32 s69, s69, 0x100
	s_addc_u32 s70, s70, 0

; #define PG8_STAGE(bufoff, gbase, voff) do { _Pragma("unroll") for (int _i = 0; _i < 2; ++_i) \
;         __builtin_amdgcn_global_load_lds((const unsigned*)((const char*)(gbase) + (voff)[_i]), (PG8_LAS unsigned*)(lds + (bufoff) + ldsw + _i * 8192), 16, 0, 0); } while (0)
; #define PG8_LDA(dst, b, h) do { _Pragma("unroll") for (int m = 0; m < 4; ++m) _Pragma("unroll") for (int k = 0; k < 2; ++k) dst[m][k] = *(const PG8_LAS bf16x8*)(lds + PG8_SA(b, h) + aoff + m * 2048 + k * 1024); } while (0)
; #define PG8_LDB(dst, b, h) do { _Pragma("unroll") for (int n = 0; n < 2; ++n) _Pragma("unroll") for (int k = 0; k < 2; ++k) dst[n][k] = *(const PG8_LAS bf16x8*)(lds + PG8_SB(b, h) + boff + n * 2048 + k * 1024); } while (0)
; #define PG8_SCHED __builtin_amdgcn_sched_barrier(0)
; template <class Epi, class Sched, bool ALIGN_EPI = false, bool SP2 = false>
; __device__ __forceinline__ void gemm_phase(PG8_LAS unsigned char* lds, const Gemm g, const Sched& S, const Epi& E) {
;     ...
;         const bool has_next = S.next(ui + 1, nxt);
;         const char* nA = has_next ? (const char*)g.A + (size_t)nxt.pm * tstep : cA; const char* nB = has_next ? (const char*)g.Bt + (size_t)nxt.pn * tstep : cB;
; #pragma nounroll
;         for (int t = 0; t < nt; t += 2) {
;             const bool last = (t == nt - 2);
;             const char* a1 = cA + (size_t)(t + 1) * kstep;
;             const char* a2 = last ? nA : cA + (size_t)(t + 2) * kstep; const char* b2 = last ? nB : cB + (size_t)(t + 2) * kstep;
;             const char* a3 = a2 + kstep; const char* b3 = b2 + kstep;
;             if (last && has_next) S.a_ready(nxt);
;             if constexpr (SP2) {
;             PG8_LDB(B0, 0, 0); PG8_LDB(B1, 0, 1); PG8_SCHED; PG8_LDA(At, 0, 0); PG8_STAGE(PG8_SA(1, 1), a1 + hstep, voffA);
;     ...
; #pragma unroll
;         for (int a = 0; a < 2; ++a)
; #pragma unroll
;             for (int b = 0; b < 2; ++b)
; #pragma unroll
;                 for (int m = 0; m < 4; ++m)
; #pragma unroll
;                     for (int n = 0; n < 2; ++n) acc[a][b][m][n] = (f32x4){0.f, 0.f, 0.f, 0.f};
;         cur = nxt; cA = nA; cB = nB; ++ui;
.LBB0_1431:
	s_ashr_i32 s21, s20, 31
	s_lshl_b64 s[22:23], s[20:21], 19
	s_add_u32 s22, s38, s22
	s_addc_u32 s23, s39, s23
	s_and_b64 s[24:25], s[2:3], exec
	s_cselect_b32 s21, s23, s29
	s_cselect_b32 s64, s22, s28
	s_ashr_i32 s19, s18, 31
	s_lshl_b64 s[24:25], s[18:19], 19
	s_add_u32 s24, s40, s24
	s_addc_u32 s25, s41, s25
	s_and_b64 s[34:35], s[2:3], exec
	s_cselect_b32 s19, s25, s31
	s_cselect_b32 s65, s24, s30
	s_add_u32 s28, s28, 0x40080
	s_addc_u32 s29, s29, 0
	s_add_u32 s66, s30, 0x100
	v_mov_b32_e32 v2, 0
	s_addc_u32 s67, s31, 0
	s_mov_b32 s68, -2
	v_mov_b32_e32 v3, v2
	v_mov_b32_e32 v4, v2
	v_mov_b32_e32 v5, v2
	v_mov_b32_e32 v6, v2
	v_mov_b32_e32 v7, v2
	v_mov_b32_e32 v8, v2
	v_mov_b32_e32 v9, v2
	v_mov_b32_e32 v10, v2
	v_mov_b32_e32 v11, v2
	v_mov_b32_e32 v12, v2
	v_mov_b32_e32 v13, v2
	v_mov_b32_e32 v18, v2
	v_mov_b32_e32 v19, v2
	v_mov_b32_e32 v20, v2
	v_mov_b32_e32 v21, v2
	v_mov_b32_e32 v26, v2
	v_mov_b32_e32 v27, v2
	v_mov_b32_e32 v28, v2
	v_mov_b32_e32 v29, v2
	v_mov_b32_e32 v34, v2
	v_mov_b32_e32 v35, v2
	v_mov_b32_e32 v36, v2
	v_mov_b32_e32 v37, v2
	v_mov_b32_e32 v42, v2
	v_mov_b32_e32 v43, v2
	v_mov_b32_e32 v44, v2
	v_mov_b32_e32 v45, v2
	v_mov_b32_e32 v50, v2
	v_mov_b32_e32 v51, v2
	v_mov_b32_e32 v52, v2
	v_mov_b32_e32 v53, v2
	v_mov_b32_e32 v14, v2
	v_mov_b32_e32 v15, v2
	v_mov_b32_e32 v16, v2
	v_mov_b32_e32 v17, v2
	v_mov_b32_e32 v22, v2
	v_mov_b32_e32 v23, v2
	v_mov_b32_e32 v24, v2
	v_mov_b32_e32 v25, v2
	v_mov_b32_e32 v30, v2
	v_mov_b32_e32 v31, v2
	v_mov_b32_e32 v32, v2
	v_mov_b32_e32 v33, v2
	v_mov_b32_e32 v38, v2
	v_mov_b32_e32 v39, v2
	v_mov_b32_e32 v40, v2
	v_mov_b32_e32 v41, v2
	v_mov_b32_e32 v46, v2
	v_mov_b32_e32 v47, v2
	v_mov_b32_e32 v48, v2
	v_mov_b32_e32 v49, v2
	v_mov_b32_e32 v54, v2
	v_mov_b32_e32 v55, v2
	v_mov_b32_e32 v56, v2
	v_mov_b32_e32 v57, v2
	v_mov_b32_e32 v58, v2
	v_mov_b32_e32 v59, v2
	v_mov_b32_e32 v60, v2
	v_mov_b32_e32 v61, v2
	v_mov_b32_e32 v62, v2
	v_mov_b32_e32 v63, v2
	v_mov_b32_e32 v64, v2
	v_mov_b32_e32 v65, v2
	v_mov_b32_e32 v66, v2
	v_mov_b32_e32 v67, v2
	v_mov_b32_e32 v68, v2
	v_mov_b32_e32 v69, v2
	v_mov_b32_e32 v70, v2
	v_mov_b32_e32 v71, v2
	v_mov_b32_e32 v72, v2
	v_mov_b32_e32 v73, v2
	v_mov_b32_e32 v74, v2
	v_mov_b32_e32 v75, v2
	v_mov_b32_e32 v76, v2
	v_mov_b32_e32 v77, v2
	v_mov_b32_e32 v82, v2
	v_mov_b32_e32 v83, v2
	v_mov_b32_e32 v84, v2
	v_mov_b32_e32 v85, v2
	v_mov_b32_e32 v90, v2
	v_mov_b32_e32 v91, v2
	v_mov_b32_e32 v92, v2
	v_mov_b32_e32 v93, v2
	v_mov_b32_e32 v98, v2
	v_mov_b32_e32 v99, v2
	v_mov_b32_e32 v100, v2
	v_mov_b32_e32 v101, v2
	v_mov_b32_e32 v106, v2
	v_mov_b32_e32 v107, v2
	v_mov_b32_e32 v108, v2
	v_mov_b32_e32 v109, v2
	v_mov_b32_e32 v114, v2
	v_mov_b32_e32 v115, v2
	v_mov_b32_e32 v116, v2
	v_mov_b32_e32 v117, v2
	v_mov_b32_e32 v78, v2
	v_mov_b32_e32 v79, v2
	v_mov_b32_e32 v80, v2
	v_mov_b32_e32 v81, v2
	v_mov_b32_e32 v86, v2
	v_mov_b32_e32 v87, v2
	v_mov_b32_e32 v88, v2
	v_mov_b32_e32 v89, v2
	v_mov_b32_e32 v94, v2
	v_mov_b32_e32 v95, v2
	v_mov_b32_e32 v96, v2
	v_mov_b32_e32 v97, v2
	v_mov_b32_e32 v102, v2
	v_mov_b32_e32 v103, v2
	v_mov_b32_e32 v104, v2
	v_mov_b32_e32 v105, v2
	v_mov_b32_e32 v110, v2
	v_mov_b32_e32 v111, v2
	v_mov_b32_e32 v112, v2
	v_mov_b32_e32 v113, v2
	v_mov_b32_e32 v118, v2
	v_mov_b32_e32 v119, v2
	v_mov_b32_e32 v120, v2
	v_mov_b32_e32 v121, v2
	v_mov_b32_e32 v122, v2
	v_mov_b32_e32 v123, v2
	v_mov_b32_e32 v124, v2
	v_mov_b32_e32 v125, v2
	v_mov_b32_e32 v126, v2
	v_mov_b32_e32 v127, v2
	v_mov_b32_e32 v128, v2
	v_mov_b32_e32 v129, v2
	ds_read_b128 v[154:157], v150
	ds_read_b128 v[158:161], v150 offset:1024
	ds_read_b128 v[162:165], v150 offset:2048
	ds_read_b128 v[166:169], v150 offset:3072
	ds_read_b128 v[174:177], v151
	ds_read_b128 v[178:181], v151 offset:1024
	ds_read_b128 v[182:185], v151 offset:2048
	ds_read_b128 v[186:189], v151 offset:3072
	s_add_u32 s30, s28, 0xfffc0080
	s_addc_u32 s31, s29, -1
	s_cmp_eq_u32 s68, 12
	s_cselect_b32 s35, s21, s31
	s_cselect_b32 s34, s64, s30
	s_cselect_b32 s31, s19, s67
	s_cselect_b32 s30, s65, s66

; #define PG8_STAGE(bufoff, gbase, voff) do { _Pragma("unroll") for (int _i = 0; _i < 2; ++_i) \
;         __builtin_amdgcn_global_load_lds((const unsigned*)((const char*)(gbase) + (voff)[_i]), (PG8_LAS unsigned*)(lds + (bufoff) + ldsw + _i * 8192), 16, 0, 0); } while (0)
; #define PG8_LDA(dst, b, h) do { _Pragma("unroll") for (int m = 0; m < 4; ++m) _Pragma("unroll") for (int k = 0; k < 2; ++k) dst[m][k] = *(const PG8_LAS bf16x8*)(lds + PG8_SA(b, h) + aoff + m * 2048 + k * 1024); } while (0)
; #define PG8_LDB(dst, b, h) do { _Pragma("unroll") for (int n = 0; n < 2; ++n) _Pragma("unroll") for (int k = 0; k < 2; ++k) dst[n][k] = *(const PG8_LAS bf16x8*)(lds + PG8_SB(b, h) + boff + n * 2048 + k * 1024); } while (0)
; #define PG8_MMA(ai, bj, At, Bt) do { __builtin_amdgcn_s_setprio(1); _Pragma("unroll") for (int m = 0; m < 4; ++m) _Pragma("unroll") for (int n = 0; n < 2; ++n) _Pragma("unroll") for (int k = 0; k < 2; ++k) \
;         acc[ai][bj][m][n] = __builtin_amdgcn_mfma_f32_16x16x32_bf16(Bt[n][k], At[m][k], acc[ai][bj][m][n], 0, 0, 0); __builtin_amdgcn_s_setprio(0); } while (0)
; #define PG8_WAIT_V(n) asm volatile("s_waitcnt vmcnt(" #n ")" ::: "memory")
; #define PG8_WAIT_L(n) asm volatile("s_waitcnt lgkmcnt(" #n ")" ::: "memory")
; #define PG8_BAR __builtin_amdgcn_s_barrier()
; #define PG8_SCHED __builtin_amdgcn_sched_barrier(0)
; template <class Epi, class Sched, bool ALIGN_EPI = false, bool SP2 = false>
; __device__ __forceinline__ void gemm_phase(PG8_LAS unsigned char* lds, const Gemm g, const Sched& S, const Epi& E) {
;     ...
;             PG8_LDB(B0, 0, 0); PG8_LDB(B1, 0, 1); PG8_SCHED; PG8_LDA(At, 0, 0); PG8_STAGE(PG8_SA(1, 1), a1 + hstep, voffA);
;             PG8_WAIT_V(8); PG8_WAIT_L(0); PG8_BAR; PG8_MMA(0, 0, At, B0); PG8_MMA(0, 1, At, B1); PG8_BAR; PG8_SCHED;
	v_lshl_add_u64 v[146:147], s[28:29], 0, v[138:139]
	s_add_i32 m0, s27, 0xc000
	ds_read_b128 v[190:193], v152
	ds_read_b128 v[194:197], v152 offset:1024
	ds_read_b128 v[198:201], v152 offset:2048
	ds_read_b128 v[202:205], v152 offset:3072
	ds_read_b128 v[206:209], v152 offset:4096
	ds_read_b128 v[210:213], v152 offset:5120
	ds_read_b128 v[214:217], v152 offset:6144
	ds_read_b128 v[218:221], v152 offset:7168
	global_load_lds_dwordx4 v[146:147], off
	v_lshl_add_u64 v[146:147], s[28:29], 0, v[140:141]
	s_add_i32 m0, s27, 0xe000
	s_nop 0
	global_load_lds_dwordx4 v[146:147], off
	s_waitcnt vmcnt(24)
	s_waitcnt lgkmcnt(0)
	s_barrier
	s_setprio 1
	s_waitcnt lgkmcnt(0)
	v_mfma_f32_16x16x32_bf16 v[126:129], v[154:157], v[190:193], v[126:129]
	v_mfma_f32_16x16x32_bf16 v[122:125], v[162:165], v[190:193], v[122:125]
	v_mfma_f32_16x16x32_bf16 v[118:121], v[154:157], v[198:201], v[118:121]
	v_mfma_f32_16x16x32_bf16 v[110:113], v[162:165], v[198:201], v[110:113]
	v_mfma_f32_16x16x32_bf16 v[102:105], v[154:157], v[206:209], v[102:105]
	v_mfma_f32_16x16x32_bf16 v[94:97], v[162:165], v[206:209], v[94:97]
	v_mfma_f32_16x16x32_bf16 v[86:89], v[154:157], v[214:217], v[86:89]
	v_mfma_f32_16x16x32_bf16 v[78:81], v[162:165], v[214:217], v[78:81]
	v_mfma_f32_16x16x32_bf16 v[126:129], v[158:161], v[194:197], v[126:129]
	v_mfma_f32_16x16x32_bf16 v[122:125], v[166:169], v[194:197], v[122:125]
	v_mfma_f32_16x16x32_bf16 v[118:121], v[158:161], v[202:205], v[118:121]
	v_mfma_f32_16x16x32_bf16 v[110:113], v[166:169], v[202:205], v[110:113]
	v_mfma_f32_16x16x32_bf16 v[102:105], v[158:161], v[210:213], v[102:105]
	v_mfma_f32_16x16x32_bf16 v[94:97], v[166:169], v[210:213], v[94:97]
	v_mfma_f32_16x16x32_bf16 v[86:89], v[158:161], v[218:221], v[86:89]
	v_mfma_f32_16x16x32_bf16 v[78:81], v[166:169], v[218:221], v[78:81]
	s_setprio 0
	s_setprio 1
	v_mfma_f32_16x16x32_bf16 v[114:117], v[174:177], v[190:193], v[114:117]
	v_mfma_f32_16x16x32_bf16 v[106:109], v[182:185], v[190:193], v[106:109]
	v_mfma_f32_16x16x32_bf16 v[98:101], v[174:177], v[198:201], v[98:101]
	v_mfma_f32_16x16x32_bf16 v[90:93], v[182:185], v[198:201], v[90:93]
	v_mfma_f32_16x16x32_bf16 v[82:85], v[174:177], v[206:209], v[82:85]
	v_mfma_f32_16x16x32_bf16 v[74:77], v[182:185], v[206:209], v[74:77]
	v_mfma_f32_16x16x32_bf16 v[70:73], v[174:177], v[214:217], v[70:73]
	v_mfma_f32_16x16x32_bf16 v[66:69], v[182:185], v[214:217], v[66:69]
	v_mfma_f32_16x16x32_bf16 v[114:117], v[178:181], v[194:197], v[114:117]
	v_mfma_f32_16x16x32_bf16 v[106:109], v[186:189], v[194:197], v[106:109]
	v_mfma_f32_16x16x32_bf16 v[98:101], v[178:181], v[202:205], v[98:101]
	v_mfma_f32_16x16x32_bf16 v[90:93], v[186:189], v[202:205], v[90:93]
	v_mfma_f32_16x16x32_bf16 v[82:85], v[178:181], v[210:213], v[82:85]
	v_mfma_f32_16x16x32_bf16 v[74:77], v[186:189], v[210:213], v[74:77]
	v_mfma_f32_16x16x32_bf16 v[70:73], v[178:181], v[218:221], v[70:73]
	v_mfma_f32_16x16x32_bf16 v[66:69], v[186:189], v[218:221], v[66:69]
	s_setprio 0
	s_barrier

; #define PG8_STAGE(bufoff, gbase, voff) do { _Pragma("unroll") for (int _i = 0; _i < 2; ++_i) \
;         __builtin_amdgcn_global_load_lds((const unsigned*)((const char*)(gbase) + (voff)[_i]), (PG8_LAS unsigned*)(lds + (bufoff) + ldsw + _i * 8192), 16, 0, 0); } while (0)
; #define PG8_LDA(dst, b, h) do { _Pragma("unroll") for (int m = 0; m < 4; ++m) _Pragma("unroll") for (int k = 0; k < 2; ++k) dst[m][k] = *(const PG8_LAS bf16x8*)(lds + PG8_SA(b, h) + aoff + m * 2048 + k * 1024); } while (0)
; #define PG8_MMA(ai, bj, At, Bt) do { __builtin_amdgcn_s_setprio(1); _Pragma("unroll") for (int m = 0; m < 4; ++m) _Pragma("unroll") for (int n = 0; n < 2; ++n) _Pragma("unroll") for (int k = 0; k < 2; ++k) \
;         acc[ai][bj][m][n] = __builtin_amdgcn_mfma_f32_16x16x32_bf16(Bt[n][k], At[m][k], acc[ai][bj][m][n], 0, 0, 0); __builtin_amdgcn_s_setprio(0); } while (0)
; #define PG8_WAIT_V(n) asm volatile("s_waitcnt vmcnt(" #n ")" ::: "memory")
; #define PG8_WAIT_L(n) asm volatile("s_waitcnt lgkmcnt(" #n ")" ::: "memory")
; #define PG8_BAR __builtin_amdgcn_s_barrier()
; #define PG8_SCHED __builtin_amdgcn_sched_barrier(0)
; template <class Epi, class Sched, bool ALIGN_EPI = false, bool SP2 = false>
; __device__ __forceinline__ void gemm_phase(PG8_LAS unsigned char* lds, const Gemm g, const Sched& S, const Epi& E) {
;     ...
;             PG8_LDA(At, 0, 1); PG8_STAGE(PG8_SB(0, 0), b2, voffB); PG8_STAGE(PG8_SB(0, 1), b2 + hstep, voffB); PG8_STAGE(PG8_SA(0, 0), a2, voffA);
;             PG8_WAIT_V(8); PG8_WAIT_L(0); PG8_BAR; PG8_MMA(1, 0, At, B0); PG8_MMA(1, 1, At, B1); PG8_BAR; PG8_SCHED;
	s_add_i32 s69, s57, s42
	v_lshl_add_u64 v[146:147], s[30:31], 0, v[132:133]
	s_mov_b32 m0, s69
	ds_read_b128 v[190:193], v152 offset:16384
	ds_read_b128 v[194:197], v152 offset:17408
	ds_read_b128 v[198:201], v152 offset:18432
	ds_read_b128 v[202:205], v152 offset:19456
	ds_read_b128 v[206:209], v152 offset:20480
	ds_read_b128 v[210:213], v152 offset:21504
	ds_read_b128 v[214:217], v152 offset:22528
	ds_read_b128 v[218:221], v152 offset:23552
	global_load_lds_dwordx4 v[146:147], off
	s_add_i32 m0, s69, 0x2000
	s_add_u32 s70, s30, 0x40000
	v_lshl_add_u64 v[170:171], s[30:31], 0, v[136:137]
	s_addc_u32 s71, s31, 0
	s_add_i32 s69, s58, s42
	global_load_lds_dwordx4 v[170:171], off
	v_lshl_add_u64 v[222:223], s[70:71], 0, v[132:133]
	s_mov_b32 m0, s69
	v_lshl_add_u64 v[224:225], s[34:35], 0, v[134:135]
	global_load_lds_dwordx4 v[222:223], off
	v_lshl_add_u64 v[222:223], s[70:71], 0, v[136:137]
	s_add_i32 m0, s69, 0x2000
	s_nop 0
	global_load_lds_dwordx4 v[222:223], off
	v_lshl_add_u64 v[222:223], s[34:35], 0, v[130:131]
	s_mov_b32 m0, s27
	s_nop 0
	global_load_lds_dwordx4 v[222:223], off
	s_mov_b32 m0, s43
	s_nop 0
	global_load_lds_dwordx4 v[224:225], off
	s_waitcnt vmcnt(24)
	s_waitcnt lgkmcnt(0)
	s_barrier
	s_setprio 1
	s_waitcnt lgkmcnt(0)
	v_mfma_f32_16x16x32_bf16 v[62:65], v[154:157], v[190:193], v[62:65]
	v_mfma_f32_16x16x32_bf16 v[58:61], v[162:165], v[190:193], v[58:61]
	v_mfma_f32_16x16x32_bf16 v[54:57], v[154:157], v[198:201], v[54:57]
	v_mfma_f32_16x16x32_bf16 v[46:49], v[162:165], v[198:201], v[46:49]
	v_mfma_f32_16x16x32_bf16 v[38:41], v[154:157], v[206:209], v[38:41]
	v_mfma_f32_16x16x32_bf16 v[30:33], v[162:165], v[206:209], v[30:33]
	v_mfma_f32_16x16x32_bf16 v[22:25], v[154:157], v[214:217], v[22:25]
	v_mfma_f32_16x16x32_bf16 v[14:17], v[162:165], v[214:217], v[14:17]
	v_mfma_f32_16x16x32_bf16 v[62:65], v[158:161], v[194:197], v[62:65]
	v_mfma_f32_16x16x32_bf16 v[58:61], v[166:169], v[194:197], v[58:61]
	v_mfma_f32_16x16x32_bf16 v[54:57], v[158:161], v[202:205], v[54:57]
	v_mfma_f32_16x16x32_bf16 v[46:49], v[166:169], v[202:205], v[46:49]
	v_mfma_f32_16x16x32_bf16 v[38:41], v[158:161], v[210:213], v[38:41]
	v_mfma_f32_16x16x32_bf16 v[30:33], v[166:169], v[210:213], v[30:33]
	v_mfma_f32_16x16x32_bf16 v[22:25], v[158:161], v[218:221], v[22:25]
	v_mfma_f32_16x16x32_bf16 v[14:17], v[166:169], v[218:221], v[14:17]
	s_setprio 0
	s_setprio 1
	v_mfma_f32_16x16x32_bf16 v[50:53], v[174:177], v[190:193], v[50:53]
	v_mfma_f32_16x16x32_bf16 v[42:45], v[182:185], v[190:193], v[42:45]
	v_mfma_f32_16x16x32_bf16 v[34:37], v[174:177], v[198:201], v[34:37]
	v_mfma_f32_16x16x32_bf16 v[26:29], v[182:185], v[198:201], v[26:29]
	v_mfma_f32_16x16x32_bf16 v[18:21], v[174:177], v[206:209], v[18:21]
	v_mfma_f32_16x16x32_bf16 v[10:13], v[182:185], v[206:209], v[10:13]
	v_mfma_f32_16x16x32_bf16 v[6:9], v[174:177], v[214:217], v[6:9]
	v_mfma_f32_16x16x32_bf16 v[2:5], v[182:185], v[214:217], v[2:5]
	v_mfma_f32_16x16x32_bf16 v[50:53], v[178:181], v[194:197], v[50:53]
	v_mfma_f32_16x16x32_bf16 v[42:45], v[186:189], v[194:197], v[42:45]
	v_mfma_f32_16x16x32_bf16 v[34:37], v[178:181], v[202:205], v[34:37]
	v_mfma_f32_16x16x32_bf16 v[26:29], v[186:189], v[202:205], v[26:29]
	v_mfma_f32_16x16x32_bf16 v[18:21], v[178:181], v[210:213], v[18:21]
	v_mfma_f32_16x16x32_bf16 v[10:13], v[186:189], v[210:213], v[10:13]
	v_mfma_f32_16x16x32_bf16 v[6:9], v[178:181], v[218:221], v[6:9]
	v_mfma_f32_16x16x32_bf16 v[2:5], v[186:189], v[218:221], v[2:5]
	s_setprio 0
	s_barrier

; #define PG8_STAGE(bufoff, gbase, voff) do { _Pragma("unroll") for (int _i = 0; _i < 2; ++_i) \
;         __builtin_amdgcn_global_load_lds((const unsigned*)((const char*)(gbase) + (voff)[_i]), (PG8_LAS unsigned*)(lds + (bufoff) + ldsw + _i * 8192), 16, 0, 0); } while (0)
; #define PG8_LDA(dst, b, h) do { _Pragma("unroll") for (int m = 0; m < 4; ++m) _Pragma("unroll") for (int k = 0; k < 2; ++k) dst[m][k] = *(const PG8_LAS bf16x8*)(lds + PG8_SA(b, h) + aoff + m * 2048 + k * 1024); } while (0)
; #define PG8_LDB(dst, b, h) do { _Pragma("unroll") for (int n = 0; n < 2; ++n) _Pragma("unroll") for (int k = 0; k < 2; ++k) dst[n][k] = *(const PG8_LAS bf16x8*)(lds + PG8_SB(b, h) + boff + n * 2048 + k * 1024); } while (0)
; #define PG8_SCHED __builtin_amdgcn_sched_barrier(0)
; template <class Epi, class Sched, bool ALIGN_EPI = false, bool SP2 = false>
; __device__ __forceinline__ void gemm_phase(PG8_LAS unsigned char* lds, const Gemm g, const Sched& S, const Epi& E) {
;     ...
;             PG8_LDB(B0, 1, 0); PG8_LDB(B1, 1, 1); PG8_SCHED; PG8_LDA(At, 1, 0); PG8_STAGE(PG8_SA(0, 1), a2 + hstep, voffA);
	s_add_i32 s69, 0, 0x18000
	v_add_u32_e32 v153, s69, v148
	s_add_i32 s70, 0, 0x1c000
	ds_read_b128 v[154:157], v153
	ds_read_b128 v[158:161], v153 offset:1024
	ds_read_b128 v[162:165], v153 offset:2048
	ds_read_b128 v[166:169], v153 offset:3072
	v_add_u32_e32 v153, s70, v148
	ds_read_b128 v[174:177], v153
	ds_read_b128 v[178:181], v153 offset:1024
	ds_read_b128 v[182:185], v153 offset:2048
	ds_read_b128 v[186:189], v153 offset:3072

; #define PG8_STAGE(bufoff, gbase, voff) do { _Pragma("unroll") for (int _i = 0; _i < 2; ++_i) \
;         __builtin_amdgcn_global_load_lds((const unsigned*)((const char*)(gbase) + (voff)[_i]), (PG8_LAS unsigned*)(lds + (bufoff) + ldsw + _i * 8192), 16, 0, 0); } while (0)
; #define PG8_LDA(dst, b, h) do { _Pragma("unroll") for (int m = 0; m < 4; ++m) _Pragma("unroll") for (int k = 0; k < 2; ++k) dst[m][k] = *(const PG8_LAS bf16x8*)(lds + PG8_SA(b, h) + aoff + m * 2048 + k * 1024); } while (0)
; #define PG8_LDB(dst, b, h) do { _Pragma("unroll") for (int n = 0; n < 2; ++n) _Pragma("unroll") for (int k = 0; k < 2; ++k) dst[n][k] = *(const PG8_LAS bf16x8*)(lds + PG8_SB(b, h) + boff + n * 2048 + k * 1024); } while (0)
; #define PG8_MMA(ai, bj, At, Bt) do { __builtin_amdgcn_s_setprio(1); _Pragma("unroll") for (int m = 0; m < 4; ++m) _Pragma("unroll") for (int n = 0; n < 2; ++n) _Pragma("unroll") for (int k = 0; k < 2; ++k) \
;         acc[ai][bj][m][n] = __builtin_amdgcn_mfma_f32_16x16x32_bf16(Bt[n][k], At[m][k], acc[ai][bj][m][n], 0, 0, 0); __builtin_amdgcn_s_setprio(0); } while (0)
; #define PG8_WAIT_V(n) asm volatile("s_waitcnt vmcnt(" #n ")" ::: "memory")
; #define PG8_WAIT_L(n) asm volatile("s_waitcnt lgkmcnt(" #n ")" ::: "memory")
; #define PG8_BAR __builtin_amdgcn_s_barrier()
; #define PG8_SCHED __builtin_amdgcn_sched_barrier(0)
; template <class Epi, class Sched, bool ALIGN_EPI = false, bool SP2 = false>
; __device__ __forceinline__ void gemm_phase(PG8_LAS unsigned char* lds, const Gemm g, const Sched& S, const Epi& E) {
;     ...
;             PG8_LDB(B0, 1, 0); PG8_LDB(B1, 1, 1); PG8_SCHED; PG8_LDA(At, 1, 0); PG8_STAGE(PG8_SA(0, 1), a2 + hstep, voffA);
;             PG8_WAIT_V(8); PG8_WAIT_L(0); PG8_BAR; PG8_MMA(0, 0, At, B0); PG8_MMA(0, 1, At, B1); PG8_BAR; PG8_SCHED;
	s_add_u32 s34, s34, 0x40000
	s_addc_u32 s35, s35, 0
	s_mov_b32 m0, s44
	v_lshl_add_u64 v[226:227], s[34:35], 0, v[130:131]
	ds_read_b128 v[190:193], v152 offset:32768
	ds_read_b128 v[194:197], v152 offset:33792
	ds_read_b128 v[198:201], v152 offset:34816
	ds_read_b128 v[202:205], v152 offset:35840
	ds_read_b128 v[206:209], v152 offset:36864
	ds_read_b128 v[210:213], v152 offset:37888
	ds_read_b128 v[214:217], v152 offset:38912
	ds_read_b128 v[218:221], v152 offset:39936
	global_load_lds_dwordx4 v[226:227], off
	v_lshl_add_u64 v[226:227], s[34:35], 0, v[134:135]
	s_mov_b32 m0, s45
	s_nop 0
	global_load_lds_dwordx4 v[226:227], off
	s_waitcnt vmcnt(8)
	s_waitcnt lgkmcnt(0)
	s_barrier
	s_setprio 1
	s_waitcnt lgkmcnt(0)
	v_mfma_f32_16x16x32_bf16 v[126:129], v[154:157], v[190:193], v[126:129]
	v_mfma_f32_16x16x32_bf16 v[122:125], v[162:165], v[190:193], v[122:125]
	v_mfma_f32_16x16x32_bf16 v[118:121], v[154:157], v[198:201], v[118:121]
	v_mfma_f32_16x16x32_bf16 v[110:113], v[162:165], v[198:201], v[110:113]
	v_mfma_f32_16x16x32_bf16 v[102:105], v[154:157], v[206:209], v[102:105]
	v_mfma_f32_16x16x32_bf16 v[94:97], v[162:165], v[206:209], v[94:97]
	v_mfma_f32_16x16x32_bf16 v[86:89], v[154:157], v[214:217], v[86:89]
	v_mfma_f32_16x16x32_bf16 v[78:81], v[162:165], v[214:217], v[78:81]
	v_mfma_f32_16x16x32_bf16 v[126:129], v[158:161], v[194:197], v[126:129]
	v_mfma_f32_16x16x32_bf16 v[122:125], v[166:169], v[194:197], v[122:125]
	v_mfma_f32_16x16x32_bf16 v[118:121], v[158:161], v[202:205], v[118:121]
	v_mfma_f32_16x16x32_bf16 v[110:113], v[166:169], v[202:205], v[110:113]
	v_mfma_f32_16x16x32_bf16 v[102:105], v[158:161], v[210:213], v[102:105]
	v_mfma_f32_16x16x32_bf16 v[94:97], v[166:169], v[210:213], v[94:97]
	v_mfma_f32_16x16x32_bf16 v[86:89], v[158:161], v[218:221], v[86:89]
	v_mfma_f32_16x16x32_bf16 v[78:81], v[166:169], v[218:221], v[78:81]
	s_setprio 0
	s_setprio 1
	v_mfma_f32_16x16x32_bf16 v[114:117], v[174:177], v[190:193], v[114:117]
	v_mfma_f32_16x16x32_bf16 v[106:109], v[182:185], v[190:193], v[106:109]
	v_mfma_f32_16x16x32_bf16 v[98:101], v[174:177], v[198:201], v[98:101]
	v_mfma_f32_16x16x32_bf16 v[90:93], v[182:185], v[198:201], v[90:93]
	v_mfma_f32_16x16x32_bf16 v[82:85], v[174:177], v[206:209], v[82:85]
	v_mfma_f32_16x16x32_bf16 v[74:77], v[182:185], v[206:209], v[74:77]
	v_mfma_f32_16x16x32_bf16 v[70:73], v[174:177], v[214:217], v[70:73]
	v_mfma_f32_16x16x32_bf16 v[66:69], v[182:185], v[214:217], v[66:69]
	v_mfma_f32_16x16x32_bf16 v[114:117], v[178:181], v[194:197], v[114:117]
	v_mfma_f32_16x16x32_bf16 v[106:109], v[186:189], v[194:197], v[106:109]
	v_mfma_f32_16x16x32_bf16 v[98:101], v[178:181], v[202:205], v[98:101]
	v_mfma_f32_16x16x32_bf16 v[90:93], v[186:189], v[202:205], v[90:93]
	v_mfma_f32_16x16x32_bf16 v[82:85], v[178:181], v[210:213], v[82:85]
	v_mfma_f32_16x16x32_bf16 v[74:77], v[186:189], v[210:213], v[74:77]
	v_mfma_f32_16x16x32_bf16 v[70:73], v[178:181], v[218:221], v[70:73]
	v_mfma_f32_16x16x32_bf16 v[66:69], v[186:189], v[218:221], v[66:69]
	s_setprio 0
	s_barrier

; #define PG8_STAGE(bufoff, gbase, voff) do { _Pragma("unroll") for (int _i = 0; _i < 2; ++_i) \
;         __builtin_amdgcn_global_load_lds((const unsigned*)((const char*)(gbase) + (voff)[_i]), (PG8_LAS unsigned*)(lds + (bufoff) + ldsw + _i * 8192), 16, 0, 0); } while (0)
; #define PG8_LDA(dst, b, h) do { _Pragma("unroll") for (int m = 0; m < 4; ++m) _Pragma("unroll") for (int k = 0; k < 2; ++k) dst[m][k] = *(const PG8_LAS bf16x8*)(lds + PG8_SA(b, h) + aoff + m * 2048 + k * 1024); } while (0)
; #define PG8_MMA(ai, bj, At, Bt) do { __builtin_amdgcn_s_setprio(1); _Pragma("unroll") for (int m = 0; m < 4; ++m) _Pragma("unroll") for (int n = 0; n < 2; ++n) _Pragma("unroll") for (int k = 0; k < 2; ++k) \
;         acc[ai][bj][m][n] = __builtin_amdgcn_mfma_f32_16x16x32_bf16(Bt[n][k], At[m][k], acc[ai][bj][m][n], 0, 0, 0); __builtin_amdgcn_s_setprio(0); } while (0)
; #define PG8_WAIT_V(n) asm volatile("s_waitcnt vmcnt(" #n ")" ::: "memory")
; #define PG8_WAIT_L(n) asm volatile("s_waitcnt lgkmcnt(" #n ")" ::: "memory")
; #define PG8_BAR __builtin_amdgcn_s_barrier()
; #define PG8_SCHED __builtin_amdgcn_sched_barrier(0)
; template <class Epi, class Sched, bool ALIGN_EPI = false, bool SP2 = false>
; __device__ __forceinline__ void gemm_phase(PG8_LAS unsigned char* lds, const Gemm g, const Sched& S, const Epi& E) {
;     ...
;             PG8_LDA(At, 1, 1); PG8_STAGE(PG8_SB(1, 0), b3, voffB); PG8_STAGE(PG8_SB(1, 1), b3 + hstep, voffB); PG8_STAGE(PG8_SA(1, 0), a3, voffA);
;             PG8_WAIT_V(8); PG8_WAIT_L(0); PG8_BAR; PG8_MMA(1, 0, At, B0); PG8_MMA(1, 1, At, B1); PG8_BAR; PG8_SCHED;
	s_add_i32 s34, s69, s42
	v_lshl_add_u64 v[146:147], v[146:147], 0, s[8:9]
	s_mov_b32 m0, s34
	ds_read_b128 v[190:193], v152 offset:49152
	ds_read_b128 v[194:197], v152 offset:50176
	ds_read_b128 v[198:201], v152 offset:51200
	ds_read_b128 v[202:205], v152 offset:52224
	ds_read_b128 v[206:209], v152 offset:53248
	ds_read_b128 v[210:213], v152 offset:54272
	ds_read_b128 v[214:217], v152 offset:55296
	ds_read_b128 v[218:221], v152 offset:56320
	global_load_lds_dwordx4 v[146:147], off
	s_add_i32 m0, s34, 0x2000
	s_add_u32 s30, s30, 0x40080
	v_lshl_add_u64 v[146:147], v[170:171], 0, s[8:9]
	s_addc_u32 s31, s31, 0
	s_add_i32 s34, s70, s42
	global_load_lds_dwordx4 v[146:147], off
	v_lshl_add_u64 v[146:147], s[30:31], 0, v[132:133]
	s_mov_b32 m0, s34
	s_nop 0
	global_load_lds_dwordx4 v[146:147], off
	v_lshl_add_u64 v[146:147], s[30:31], 0, v[136:137]
	s_add_i32 m0, s34, 0x2000
	s_nop 0
	global_load_lds_dwordx4 v[146:147], off
	v_lshl_add_u64 v[146:147], v[222:223], 0, s[8:9]
	s_mov_b32 m0, s53
	s_nop 0
	global_load_lds_dwordx4 v[146:147], off
	v_lshl_add_u64 v[146:147], v[224:225], 0, s[8:9]
	s_mov_b32 m0, s54
	s_nop 0
	global_load_lds_dwordx4 v[146:147], off
	s_waitcnt vmcnt(8)
	s_waitcnt lgkmcnt(0)
	s_barrier
	s_setprio 1
	s_waitcnt lgkmcnt(0)
	v_mfma_f32_16x16x32_bf16 v[62:65], v[154:157], v[190:193], v[62:65]
	v_mfma_f32_16x16x32_bf16 v[58:61], v[162:165], v[190:193], v[58:61]
	v_mfma_f32_16x16x32_bf16 v[54:57], v[154:157], v[198:201], v[54:57]
	v_mfma_f32_16x16x32_bf16 v[46:49], v[162:165], v[198:201], v[46:49]
	v_mfma_f32_16x16x32_bf16 v[38:41], v[154:157], v[206:209], v[38:41]
	v_mfma_f32_16x16x32_bf16 v[30:33], v[162:165], v[206:209], v[30:33]
	v_mfma_f32_16x16x32_bf16 v[22:25], v[154:157], v[214:217], v[22:25]
	v_mfma_f32_16x16x32_bf16 v[14:17], v[162:165], v[214:217], v[14:17]
	v_mfma_f32_16x16x32_bf16 v[62:65], v[158:161], v[194:197], v[62:65]
	v_mfma_f32_16x16x32_bf16 v[58:61], v[166:169], v[194:197], v[58:61]
	v_mfma_f32_16x16x32_bf16 v[54:57], v[158:161], v[202:205], v[54:57]
	v_mfma_f32_16x16x32_bf16 v[46:49], v[166:169], v[202:205], v[46:49]
	v_mfma_f32_16x16x32_bf16 v[38:41], v[158:161], v[210:213], v[38:41]
	v_mfma_f32_16x16x32_bf16 v[30:33], v[166:169], v[210:213], v[30:33]
	v_mfma_f32_16x16x32_bf16 v[22:25], v[158:161], v[218:221], v[22:25]
	v_mfma_f32_16x16x32_bf16 v[14:17], v[166:169], v[218:221], v[14:17]
	s_setprio 0
	s_setprio 1
	v_mfma_f32_16x16x32_bf16 v[50:53], v[174:177], v[190:193], v[50:53]
	v_mfma_f32_16x16x32_bf16 v[42:45], v[182:185], v[190:193], v[42:45]
	v_mfma_f32_16x16x32_bf16 v[34:37], v[174:177], v[198:201], v[34:37]
	v_mfma_f32_16x16x32_bf16 v[26:29], v[182:185], v[198:201], v[26:29]
	v_mfma_f32_16x16x32_bf16 v[18:21], v[174:177], v[206:209], v[18:21]
	v_mfma_f32_16x16x32_bf16 v[10:13], v[182:185], v[206:209], v[10:13]
	v_mfma_f32_16x16x32_bf16 v[6:9], v[174:177], v[214:217], v[6:9]
	v_mfma_f32_16x16x32_bf16 v[2:5], v[182:185], v[214:217], v[2:5]
	v_mfma_f32_16x16x32_bf16 v[50:53], v[178:181], v[194:197], v[50:53]
	v_mfma_f32_16x16x32_bf16 v[42:45], v[186:189], v[194:197], v[42:45]
	v_mfma_f32_16x16x32_bf16 v[34:37], v[178:181], v[202:205], v[34:37]
	v_mfma_f32_16x16x32_bf16 v[26:29], v[186:189], v[202:205], v[26:29]
	v_mfma_f32_16x16x32_bf16 v[18:21], v[178:181], v[210:213], v[18:21]
	v_mfma_f32_16x16x32_bf16 v[10:13], v[186:189], v[210:213], v[10:13]
	v_mfma_f32_16x16x32_bf16 v[6:9], v[178:181], v[218:221], v[6:9]
	v_mfma_f32_16x16x32_bf16 v[2:5], v[186:189], v[218:221], v[2:5]
	s_setprio 0
	s_barrier

; template <class Epi, class Sched, bool ALIGN_EPI = false, bool SP2 = false>
; __device__ __forceinline__ void gemm_phase(PG8_LAS unsigned char* lds, const Gemm g, const Sched& S, const Epi& E) {
;     ...
;         for (int t = 0; t < nt; t += 2) {
;             const bool last = (t == nt - 2);
;             const char* a1 = cA + (size_t)(t + 1) * kstep;
;             const char* a2 = last ? nA : cA + (size_t)(t + 2) * kstep; const char* b2 = last ? nB : cB + (size_t)(t + 2) * kstep;
;             const char* a3 = a2 + kstep; const char* b3 = b2 + kstep;
	s_add_i32 s68, s68, 2
	s_add_u32 s28, s28, 0x100
	s_addc_u32 s29, s29, 0
	s_add_u32 s66, s66, 0x100
	s_addc_u32 s67, s67, 0

; #define PG8_STAGE(bufoff, gbase, voff) do { _Pragma("unroll") for (int _i = 0; _i < 2; ++_i) \
;         __builtin_amdgcn_global_load_lds((const unsigned*)((const char*)(gbase) + (voff)[_i]), (PG8_LAS unsigned*)(lds + (bufoff) + ldsw + _i * 8192), 16, 0, 0); } while (0)
; #define PG8_LDA(dst, b, h) do { _Pragma("unroll") for (int m = 0; m < 4; ++m) _Pragma("unroll") for (int k = 0; k < 2; ++k) dst[m][k] = *(const PG8_LAS bf16x8*)(lds + PG8_SA(b, h) + aoff + m * 2048 + k * 1024); } while (0)
; #define PG8_LDB(dst, b, h) do { _Pragma("unroll") for (int n = 0; n < 2; ++n) _Pragma("unroll") for (int k = 0; k < 2; ++k) dst[n][k] = *(const PG8_LAS bf16x8*)(lds + PG8_SB(b, h) + boff + n * 2048 + k * 1024); } while (0)
; #define PG8_SCHED __builtin_amdgcn_sched_barrier(0)
; template <class Epi, class Sched, bool ALIGN_EPI = false, bool SP2 = false>
; __device__ __forceinline__ void gemm_phase(PG8_LAS unsigned char* lds, const Gemm g, const Sched& S, const Epi& E) {
;     ...
;         const bool has_next = S.next(ui + 1, nxt);
;         const char* nA = has_next ? (const char*)g.A + (size_t)nxt.pm * tstep : cA; const char* nB = has_next ? (const char*)g.Bt + (size_t)nxt.pn * tstep : cB;
; #pragma nounroll
;         for (int t = 0; t < nt; t += 2) {
;             const bool last = (t == nt - 2);
;             const char* a1 = cA + (size_t)(t + 1) * kstep;
;             const char* a2 = last ? nA : cA + (size_t)(t + 2) * kstep; const char* b2 = last ? nB : cB + (size_t)(t + 2) * kstep;
;             const char* a3 = a2 + kstep; const char* b3 = b2 + kstep;
;             if (last && has_next) S.a_ready(nxt);
;             if constexpr (SP2) {
;             PG8_LDB(B0, 0, 0); PG8_LDB(B1, 0, 1); PG8_SCHED; PG8_LDA(At, 0, 0); PG8_STAGE(PG8_SA(1, 1), a1 + hstep, voffA);
;     ...
; #pragma unroll
;         for (int a = 0; a < 2; ++a)
; #pragma unroll
;             for (int b = 0; b < 2; ++b)
; #pragma unroll
;                 for (int m = 0; m < 4; ++m)
; #pragma unroll
;                     for (int n = 0; n < 2; ++n) acc[a][b][m][n] = (f32x4){0.f, 0.f, 0.f, 0.f};
;         cur = nxt; cA = nA; cB = nB; ++ui;
.LBB0_1590:
	s_ashr_i32 s13, s12, 31
	s_lshl_b64 s[14:15], s[12:13], 19
	s_add_u32 s14, s26, s14
	s_addc_u32 s15, s27, s15
	s_and_b64 s[16:17], s[2:3], exec
	s_cselect_b32 s13, s15, s21
	s_cselect_b32 s52, s14, s20
	s_ashr_i32 s11, s10, 31
	s_lshl_b64 s[16:17], s[10:11], 19
	s_add_u32 s16, s28, s16
	s_addc_u32 s17, s29, s17
	s_and_b64 s[24:25], s[2:3], exec
	s_cselect_b32 s11, s17, s23
	s_cselect_b32 s53, s16, s22
	s_add_u32 s20, s20, 0x40080
	s_addc_u32 s21, s21, 0
	s_add_u32 s54, s22, 0x100
	v_mov_b32_e32 v2, 0
	s_addc_u32 s55, s23, 0
	s_mov_b32 s56, -2
	v_mov_b32_e32 v3, v2
	v_mov_b32_e32 v4, v2
	v_mov_b32_e32 v5, v2
	v_mov_b32_e32 v6, v2
	v_mov_b32_e32 v7, v2
	v_mov_b32_e32 v8, v2
	v_mov_b32_e32 v9, v2
	v_mov_b32_e32 v18, v2
	v_mov_b32_e32 v19, v2
	v_mov_b32_e32 v20, v2
	v_mov_b32_e32 v21, v2
	v_mov_b32_e32 v22, v2
	v_mov_b32_e32 v23, v2
	v_mov_b32_e32 v24, v2
	v_mov_b32_e32 v25, v2
	v_mov_b32_e32 v34, v2
	v_mov_b32_e32 v35, v2
	v_mov_b32_e32 v36, v2
	v_mov_b32_e32 v37, v2
	v_mov_b32_e32 v38, v2
	v_mov_b32_e32 v39, v2
	v_mov_b32_e32 v40, v2
	v_mov_b32_e32 v41, v2
	v_mov_b32_e32 v50, v2
	v_mov_b32_e32 v51, v2
	v_mov_b32_e32 v52, v2
	v_mov_b32_e32 v53, v2
	v_mov_b32_e32 v54, v2
	v_mov_b32_e32 v55, v2
	v_mov_b32_e32 v56, v2
	v_mov_b32_e32 v57, v2
	v_mov_b32_e32 v10, v2
	v_mov_b32_e32 v11, v2
	v_mov_b32_e32 v12, v2
	v_mov_b32_e32 v13, v2
	v_mov_b32_e32 v14, v2
	v_mov_b32_e32 v15, v2
	v_mov_b32_e32 v16, v2
	v_mov_b32_e32 v17, v2
	v_mov_b32_e32 v26, v2
	v_mov_b32_e32 v27, v2
	v_mov_b32_e32 v28, v2
	v_mov_b32_e32 v29, v2
	v_mov_b32_e32 v30, v2
	v_mov_b32_e32 v31, v2
	v_mov_b32_e32 v32, v2
	v_mov_b32_e32 v33, v2
	v_mov_b32_e32 v42, v2
	v_mov_b32_e32 v43, v2
	v_mov_b32_e32 v44, v2
	v_mov_b32_e32 v45, v2
	v_mov_b32_e32 v46, v2
	v_mov_b32_e32 v47, v2
	v_mov_b32_e32 v48, v2
	v_mov_b32_e32 v49, v2
	v_mov_b32_e32 v58, v2
	v_mov_b32_e32 v59, v2
	v_mov_b32_e32 v60, v2
	v_mov_b32_e32 v61, v2
	v_mov_b32_e32 v62, v2
	v_mov_b32_e32 v63, v2
	v_mov_b32_e32 v64, v2
	v_mov_b32_e32 v65, v2
	v_mov_b32_e32 v66, v2
	v_mov_b32_e32 v67, v2
	v_mov_b32_e32 v68, v2
	v_mov_b32_e32 v69, v2
	v_mov_b32_e32 v70, v2
	v_mov_b32_e32 v71, v2
	v_mov_b32_e32 v72, v2
	v_mov_b32_e32 v73, v2
	v_mov_b32_e32 v82, v2
	v_mov_b32_e32 v83, v2
	v_mov_b32_e32 v84, v2
	v_mov_b32_e32 v85, v2
	v_mov_b32_e32 v86, v2
	v_mov_b32_e32 v87, v2
	v_mov_b32_e32 v88, v2
	v_mov_b32_e32 v89, v2
	v_mov_b32_e32 v98, v2
	v_mov_b32_e32 v99, v2
	v_mov_b32_e32 v100, v2
	v_mov_b32_e32 v101, v2
	v_mov_b32_e32 v102, v2
	v_mov_b32_e32 v103, v2
	v_mov_b32_e32 v104, v2
	v_mov_b32_e32 v105, v2
	v_mov_b32_e32 v114, v2
	v_mov_b32_e32 v115, v2
	v_mov_b32_e32 v116, v2
	v_mov_b32_e32 v117, v2
	v_mov_b32_e32 v118, v2
	v_mov_b32_e32 v119, v2
	v_mov_b32_e32 v120, v2
	v_mov_b32_e32 v121, v2
	v_mov_b32_e32 v74, v2
	v_mov_b32_e32 v75, v2
	v_mov_b32_e32 v76, v2
	v_mov_b32_e32 v77, v2
	v_mov_b32_e32 v78, v2
	v_mov_b32_e32 v79, v2
	v_mov_b32_e32 v80, v2
	v_mov_b32_e32 v81, v2
	v_mov_b32_e32 v90, v2
	v_mov_b32_e32 v91, v2
	v_mov_b32_e32 v92, v2
	v_mov_b32_e32 v93, v2
	v_mov_b32_e32 v94, v2
	v_mov_b32_e32 v95, v2
	v_mov_b32_e32 v96, v2
	v_mov_b32_e32 v97, v2
	v_mov_b32_e32 v106, v2
	v_mov_b32_e32 v107, v2
	v_mov_b32_e32 v108, v2
	v_mov_b32_e32 v109, v2
	v_mov_b32_e32 v110, v2
	v_mov_b32_e32 v111, v2
	v_mov_b32_e32 v112, v2
	v_mov_b32_e32 v113, v2
	v_mov_b32_e32 v122, v2
	v_mov_b32_e32 v123, v2
	v_mov_b32_e32 v124, v2
	v_mov_b32_e32 v125, v2
	v_mov_b32_e32 v126, v2
	v_mov_b32_e32 v127, v2
	v_mov_b32_e32 v128, v2
	v_mov_b32_e32 v129, v2
	ds_read_b128 v[152:155], v149
	ds_read_b128 v[156:159], v149 offset:1024
	ds_read_b128 v[160:163], v149 offset:2048
	ds_read_b128 v[164:167], v149 offset:3072
	ds_read_b128 v[168:171], v150
	ds_read_b128 v[174:177], v150 offset:1024
	ds_read_b128 v[178:181], v150 offset:2048
	ds_read_b128 v[182:185], v150 offset:3072
	s_add_u32 s22, s20, 0xfffc0080
	s_addc_u32 s23, s21, -1
	s_cmp_eq_u32 s56, 12
	s_cselect_b32 s25, s13, s23
	s_cselect_b32 s24, s52, s22
	s_cselect_b32 s23, s11, s55
	s_cselect_b32 s22, s53, s54

; #define PG8_STAGE(bufoff, gbase, voff) do { _Pragma("unroll") for (int _i = 0; _i < 2; ++_i) \
;         __builtin_amdgcn_global_load_lds((const unsigned*)((const char*)(gbase) + (voff)[_i]), (PG8_LAS unsigned*)(lds + (bufoff) + ldsw + _i * 8192), 16, 0, 0); } while (0)
; #define PG8_LDA(dst, b, h) do { _Pragma("unroll") for (int m = 0; m < 4; ++m) _Pragma("unroll") for (int k = 0; k < 2; ++k) dst[m][k] = *(const PG8_LAS bf16x8*)(lds + PG8_SA(b, h) + aoff + m * 2048 + k * 1024); } while (0)
; #define PG8_LDB(dst, b, h) do { _Pragma("unroll") for (int n = 0; n < 2; ++n) _Pragma("unroll") for (int k = 0; k < 2; ++k) dst[n][k] = *(const PG8_LAS bf16x8*)(lds + PG8_SB(b, h) + boff + n * 2048 + k * 1024); } while (0)
; #define PG8_MMA(ai, bj, At, Bt) do { __builtin_amdgcn_s_setprio(1); _Pragma("unroll") for (int m = 0; m < 4; ++m) _Pragma("unroll") for (int n = 0; n < 2; ++n) _Pragma("unroll") for (int k = 0; k < 2; ++k) \
;         acc[ai][bj][m][n] = __builtin_amdgcn_mfma_f32_16x16x32_bf16(Bt[n][k], At[m][k], acc[ai][bj][m][n], 0, 0, 0); __builtin_amdgcn_s_setprio(0); } while (0)
; #define PG8_WAIT_V(n) asm volatile("s_waitcnt vmcnt(" #n ")" ::: "memory")
; #define PG8_WAIT_L(n) asm volatile("s_waitcnt lgkmcnt(" #n ")" ::: "memory")
; #define PG8_BAR __builtin_amdgcn_s_barrier()
; #define PG8_SCHED __builtin_amdgcn_sched_barrier(0)
; template <class Epi, class Sched, bool ALIGN_EPI = false, bool SP2 = false>
; __device__ __forceinline__ void gemm_phase(PG8_LAS unsigned char* lds, const Gemm g, const Sched& S, const Epi& E) {
;     ...
;             PG8_LDB(B0, 0, 0); PG8_LDB(B1, 0, 1); PG8_SCHED; PG8_LDA(At, 0, 0); PG8_STAGE(PG8_SA(1, 1), a1 + hstep, voffA);
;             PG8_WAIT_V(8); PG8_WAIT_L(0); PG8_BAR; PG8_MMA(0, 0, At, B0); PG8_MMA(0, 1, At, B1); PG8_BAR; PG8_SCHED;
	v_lshl_add_u64 v[218:219], s[20:21], 0, v[140:141]
	s_add_i32 m0, s34, 0xc000
	ds_read_b128 v[186:189], v151
	ds_read_b128 v[190:193], v151 offset:1024
	ds_read_b128 v[194:197], v151 offset:2048
	ds_read_b128 v[198:201], v151 offset:3072
	ds_read_b128 v[202:205], v151 offset:4096
	ds_read_b128 v[206:209], v151 offset:5120
	ds_read_b128 v[210:213], v151 offset:6144
	ds_read_b128 v[214:217], v151 offset:7168
	global_load_lds_dwordx4 v[218:219], off
	v_lshl_add_u64 v[218:219], s[20:21], 0, v[142:143]
	s_add_i32 m0, s34, 0xe000
	s_nop 0
	global_load_lds_dwordx4 v[218:219], off
	s_waitcnt vmcnt(16)
	s_waitcnt lgkmcnt(0)
	s_barrier
	s_setprio 1
	s_waitcnt lgkmcnt(0)
	v_mfma_f32_16x16x32_bf16 v[126:129], v[152:155], v[186:189], v[126:129]
	v_mfma_f32_16x16x32_bf16 v[122:125], v[160:163], v[186:189], v[122:125]
	v_mfma_f32_16x16x32_bf16 v[110:113], v[152:155], v[194:197], v[110:113]
	v_mfma_f32_16x16x32_bf16 v[106:109], v[160:163], v[194:197], v[106:109]
	v_mfma_f32_16x16x32_bf16 v[94:97], v[152:155], v[202:205], v[94:97]
	v_mfma_f32_16x16x32_bf16 v[90:93], v[160:163], v[202:205], v[90:93]
	v_mfma_f32_16x16x32_bf16 v[78:81], v[152:155], v[210:213], v[78:81]
	v_mfma_f32_16x16x32_bf16 v[74:77], v[160:163], v[210:213], v[74:77]
	v_mfma_f32_16x16x32_bf16 v[126:129], v[156:159], v[190:193], v[126:129]
	v_mfma_f32_16x16x32_bf16 v[122:125], v[164:167], v[190:193], v[122:125]
	v_mfma_f32_16x16x32_bf16 v[110:113], v[156:159], v[198:201], v[110:113]
	v_mfma_f32_16x16x32_bf16 v[106:109], v[164:167], v[198:201], v[106:109]
	v_mfma_f32_16x16x32_bf16 v[94:97], v[156:159], v[206:209], v[94:97]
	v_mfma_f32_16x16x32_bf16 v[90:93], v[164:167], v[206:209], v[90:93]
	v_mfma_f32_16x16x32_bf16 v[78:81], v[156:159], v[214:217], v[78:81]
	v_mfma_f32_16x16x32_bf16 v[74:77], v[164:167], v[214:217], v[74:77]
	s_setprio 0
	s_setprio 1
	v_mfma_f32_16x16x32_bf16 v[118:121], v[168:171], v[186:189], v[118:121]
	v_mfma_f32_16x16x32_bf16 v[114:117], v[178:181], v[186:189], v[114:117]
	v_mfma_f32_16x16x32_bf16 v[102:105], v[168:171], v[194:197], v[102:105]
	v_mfma_f32_16x16x32_bf16 v[98:101], v[178:181], v[194:197], v[98:101]
	v_mfma_f32_16x16x32_bf16 v[86:89], v[168:171], v[202:205], v[86:89]
	v_mfma_f32_16x16x32_bf16 v[82:85], v[178:181], v[202:205], v[82:85]
	v_mfma_f32_16x16x32_bf16 v[70:73], v[168:171], v[210:213], v[70:73]
	v_mfma_f32_16x16x32_bf16 v[66:69], v[178:181], v[210:213], v[66:69]
	v_mfma_f32_16x16x32_bf16 v[118:121], v[174:177], v[190:193], v[118:121]
	v_mfma_f32_16x16x32_bf16 v[114:117], v[182:185], v[190:193], v[114:117]
	v_mfma_f32_16x16x32_bf16 v[102:105], v[174:177], v[198:201], v[102:105]
	v_mfma_f32_16x16x32_bf16 v[98:101], v[182:185], v[198:201], v[98:101]
	v_mfma_f32_16x16x32_bf16 v[86:89], v[174:177], v[206:209], v[86:89]
	v_mfma_f32_16x16x32_bf16 v[82:85], v[182:185], v[206:209], v[82:85]
	v_mfma_f32_16x16x32_bf16 v[70:73], v[174:177], v[214:217], v[70:73]
	v_mfma_f32_16x16x32_bf16 v[66:69], v[182:185], v[214:217], v[66:69]
	s_setprio 0
	s_barrier

; #define PG8_STAGE(bufoff, gbase, voff) do { _Pragma("unroll") for (int _i = 0; _i < 2; ++_i) \
;         __builtin_amdgcn_global_load_lds((const unsigned*)((const char*)(gbase) + (voff)[_i]), (PG8_LAS unsigned*)(lds + (bufoff) + ldsw + _i * 8192), 16, 0, 0); } while (0)
; #define PG8_LDA(dst, b, h) do { _Pragma("unroll") for (int m = 0; m < 4; ++m) _Pragma("unroll") for (int k = 0; k < 2; ++k) dst[m][k] = *(const PG8_LAS bf16x8*)(lds + PG8_SA(b, h) + aoff + m * 2048 + k * 1024); } while (0)
; #define PG8_MMA(ai, bj, At, Bt) do { __builtin_amdgcn_s_setprio(1); _Pragma("unroll") for (int m = 0; m < 4; ++m) _Pragma("unroll") for (int n = 0; n < 2; ++n) _Pragma("unroll") for (int k = 0; k < 2; ++k) \
;         acc[ai][bj][m][n] = __builtin_amdgcn_mfma_f32_16x16x32_bf16(Bt[n][k], At[m][k], acc[ai][bj][m][n], 0, 0, 0); __builtin_amdgcn_s_setprio(0); } while (0)
; #define PG8_WAIT_V(n) asm volatile("s_waitcnt vmcnt(" #n ")" ::: "memory")
; #define PG8_WAIT_L(n) asm volatile("s_waitcnt lgkmcnt(" #n ")" ::: "memory")
; #define PG8_BAR __builtin_amdgcn_s_barrier()
; #define PG8_SCHED __builtin_amdgcn_sched_barrier(0)
; template <class Epi, class Sched, bool ALIGN_EPI = false, bool SP2 = false>
; __device__ __forceinline__ void gemm_phase(PG8_LAS unsigned char* lds, const Gemm g, const Sched& S, const Epi& E) {
;     ...
;             PG8_LDA(At, 0, 1); PG8_STAGE(PG8_SB(0, 0), b2, voffB); PG8_STAGE(PG8_SB(0, 1), b2 + hstep, voffB); PG8_STAGE(PG8_SA(0, 0), a2, voffA);
;             PG8_WAIT_V(8); PG8_WAIT_L(0); PG8_BAR; PG8_MMA(1, 0, At, B0); PG8_MMA(1, 1, At, B1); PG8_BAR; PG8_SCHED;
	s_add_i32 s57, s45, s30
	v_lshl_add_u64 v[218:219], s[22:23], 0, v[134:135]
	s_mov_b32 m0, s57
	ds_read_b128 v[186:189], v151 offset:16384
	ds_read_b128 v[190:193], v151 offset:17408
	ds_read_b128 v[194:197], v151 offset:18432
	ds_read_b128 v[198:201], v151 offset:19456
	ds_read_b128 v[202:205], v151 offset:20480
	ds_read_b128 v[206:209], v151 offset:21504
	ds_read_b128 v[210:213], v151 offset:22528
	ds_read_b128 v[214:217], v151 offset:23552
	global_load_lds_dwordx4 v[218:219], off
	s_add_i32 m0, s57, 0x2000
	s_add_u32 s58, s22, 0x40000
	v_lshl_add_u64 v[220:221], s[22:23], 0, v[130:131]
	s_addc_u32 s59, s23, 0
	s_add_i32 s57, s48, s30
	global_load_lds_dwordx4 v[220:221], off
	v_lshl_add_u64 v[222:223], s[58:59], 0, v[134:135]
	s_mov_b32 m0, s57
	v_lshl_add_u64 v[224:225], s[24:25], 0, v[132:133]
	global_load_lds_dwordx4 v[222:223], off
	v_lshl_add_u64 v[222:223], s[58:59], 0, v[130:131]
	s_add_i32 m0, s57, 0x2000
	s_nop 0
	global_load_lds_dwordx4 v[222:223], off
	v_lshl_add_u64 v[222:223], s[24:25], 0, v[136:137]
	s_mov_b32 m0, s34
	s_nop 0
	global_load_lds_dwordx4 v[222:223], off
	s_mov_b32 m0, s35
	s_nop 0
	global_load_lds_dwordx4 v[224:225], off
	s_waitcnt vmcnt(16)
	s_waitcnt lgkmcnt(0)
	s_barrier
	s_setprio 1
	s_waitcnt lgkmcnt(0)
	v_mfma_f32_16x16x32_bf16 v[62:65], v[152:155], v[186:189], v[62:65]
	v_mfma_f32_16x16x32_bf16 v[58:61], v[160:163], v[186:189], v[58:61]
	v_mfma_f32_16x16x32_bf16 v[46:49], v[152:155], v[194:197], v[46:49]
	v_mfma_f32_16x16x32_bf16 v[42:45], v[160:163], v[194:197], v[42:45]
	v_mfma_f32_16x16x32_bf16 v[30:33], v[152:155], v[202:205], v[30:33]
	v_mfma_f32_16x16x32_bf16 v[26:29], v[160:163], v[202:205], v[26:29]
	v_mfma_f32_16x16x32_bf16 v[14:17], v[152:155], v[210:213], v[14:17]
	v_mfma_f32_16x16x32_bf16 v[10:13], v[160:163], v[210:213], v[10:13]
	v_mfma_f32_16x16x32_bf16 v[62:65], v[156:159], v[190:193], v[62:65]
	v_mfma_f32_16x16x32_bf16 v[58:61], v[164:167], v[190:193], v[58:61]
	v_mfma_f32_16x16x32_bf16 v[46:49], v[156:159], v[198:201], v[46:49]
	v_mfma_f32_16x16x32_bf16 v[42:45], v[164:167], v[198:201], v[42:45]
	v_mfma_f32_16x16x32_bf16 v[30:33], v[156:159], v[206:209], v[30:33]
	v_mfma_f32_16x16x32_bf16 v[26:29], v[164:167], v[206:209], v[26:29]
	v_mfma_f32_16x16x32_bf16 v[14:17], v[156:159], v[214:217], v[14:17]
	v_mfma_f32_16x16x32_bf16 v[10:13], v[164:167], v[214:217], v[10:13]
	s_setprio 0
	s_setprio 1
	v_mfma_f32_16x16x32_bf16 v[54:57], v[168:171], v[186:189], v[54:57]
	v_mfma_f32_16x16x32_bf16 v[50:53], v[178:181], v[186:189], v[50:53]
	v_mfma_f32_16x16x32_bf16 v[38:41], v[168:171], v[194:197], v[38:41]
	v_mfma_f32_16x16x32_bf16 v[34:37], v[178:181], v[194:197], v[34:37]
	v_mfma_f32_16x16x32_bf16 v[22:25], v[168:171], v[202:205], v[22:25]
	v_mfma_f32_16x16x32_bf16 v[18:21], v[178:181], v[202:205], v[18:21]
	v_mfma_f32_16x16x32_bf16 v[6:9], v[168:171], v[210:213], v[6:9]
	v_mfma_f32_16x16x32_bf16 v[2:5], v[178:181], v[210:213], v[2:5]
	v_mfma_f32_16x16x32_bf16 v[54:57], v[174:177], v[190:193], v[54:57]
	v_mfma_f32_16x16x32_bf16 v[50:53], v[182:185], v[190:193], v[50:53]
	v_mfma_f32_16x16x32_bf16 v[38:41], v[174:177], v[198:201], v[38:41]
	v_mfma_f32_16x16x32_bf16 v[34:37], v[182:185], v[198:201], v[34:37]
	v_mfma_f32_16x16x32_bf16 v[22:25], v[174:177], v[206:209], v[22:25]
	v_mfma_f32_16x16x32_bf16 v[18:21], v[182:185], v[206:209], v[18:21]
	v_mfma_f32_16x16x32_bf16 v[6:9], v[174:177], v[214:217], v[6:9]
	v_mfma_f32_16x16x32_bf16 v[2:5], v[182:185], v[214:217], v[2:5]
	s_setprio 0
	s_barrier

; #define PG8_STAGE(bufoff, gbase, voff) do { _Pragma("unroll") for (int _i = 0; _i < 2; ++_i) \
;         __builtin_amdgcn_global_load_lds((const unsigned*)((const char*)(gbase) + (voff)[_i]), (PG8_LAS unsigned*)(lds + (bufoff) + ldsw + _i * 8192), 16, 0, 0); } while (0)
; #define PG8_LDA(dst, b, h) do { _Pragma("unroll") for (int m = 0; m < 4; ++m) _Pragma("unroll") for (int k = 0; k < 2; ++k) dst[m][k] = *(const PG8_LAS bf16x8*)(lds + PG8_SA(b, h) + aoff + m * 2048 + k * 1024); } while (0)
; #define PG8_LDB(dst, b, h) do { _Pragma("unroll") for (int n = 0; n < 2; ++n) _Pragma("unroll") for (int k = 0; k < 2; ++k) dst[n][k] = *(const PG8_LAS bf16x8*)(lds + PG8_SB(b, h) + boff + n * 2048 + k * 1024); } while (0)
; #define PG8_SCHED __builtin_amdgcn_sched_barrier(0)
; template <class Epi, class Sched, bool ALIGN_EPI = false, bool SP2 = false>
; __device__ __forceinline__ void gemm_phase(PG8_LAS unsigned char* lds, const Gemm g, const Sched& S, const Epi& E) {
;     ...
;             PG8_LDB(B0, 1, 0); PG8_LDB(B1, 1, 1); PG8_SCHED; PG8_LDA(At, 1, 0); PG8_STAGE(PG8_SA(0, 1), a2 + hstep, voffA);
	s_add_i32 s57, 0, 0x18000
	s_add_i32 s58, 0, 0x1c000
	v_add_u32_e32 v164, s57, v148
	v_add_u32_e32 v182, s58, v148
	ds_read_b128 v[152:155], v164
	ds_read_b128 v[156:159], v164 offset:1024
	ds_read_b128 v[160:163], v164 offset:2048
	ds_read_b128 v[164:167], v164 offset:3072
	ds_read_b128 v[168:171], v182
	ds_read_b128 v[174:177], v182 offset:1024
	ds_read_b128 v[178:181], v182 offset:2048
	ds_read_b128 v[182:185], v182 offset:3072

; #define PG8_STAGE(bufoff, gbase, voff) do { _Pragma("unroll") for (int _i = 0; _i < 2; ++_i) \
;         __builtin_amdgcn_global_load_lds((const unsigned*)((const char*)(gbase) + (voff)[_i]), (PG8_LAS unsigned*)(lds + (bufoff) + ldsw + _i * 8192), 16, 0, 0); } while (0)
; #define PG8_LDA(dst, b, h) do { _Pragma("unroll") for (int m = 0; m < 4; ++m) _Pragma("unroll") for (int k = 0; k < 2; ++k) dst[m][k] = *(const PG8_LAS bf16x8*)(lds + PG8_SA(b, h) + aoff + m * 2048 + k * 1024); } while (0)
; #define PG8_LDB(dst, b, h) do { _Pragma("unroll") for (int n = 0; n < 2; ++n) _Pragma("unroll") for (int k = 0; k < 2; ++k) dst[n][k] = *(const PG8_LAS bf16x8*)(lds + PG8_SB(b, h) + boff + n * 2048 + k * 1024); } while (0)
; #define PG8_MMA(ai, bj, At, Bt) do { __builtin_amdgcn_s_setprio(1); _Pragma("unroll") for (int m = 0; m < 4; ++m) _Pragma("unroll") for (int n = 0; n < 2; ++n) _Pragma("unroll") for (int k = 0; k < 2; ++k) \
;         acc[ai][bj][m][n] = __builtin_amdgcn_mfma_f32_16x16x32_bf16(Bt[n][k], At[m][k], acc[ai][bj][m][n], 0, 0, 0); __builtin_amdgcn_s_setprio(0); } while (0)
; #define PG8_WAIT_V(n) asm volatile("s_waitcnt vmcnt(" #n ")" ::: "memory")
; #define PG8_WAIT_L(n) asm volatile("s_waitcnt lgkmcnt(" #n ")" ::: "memory")
; #define PG8_BAR __builtin_amdgcn_s_barrier()
; #define PG8_SCHED __builtin_amdgcn_sched_barrier(0)
; template <class Epi, class Sched, bool ALIGN_EPI = false, bool SP2 = false>
; __device__ __forceinline__ void gemm_phase(PG8_LAS unsigned char* lds, const Gemm g, const Sched& S, const Epi& E) {
;     ...
;             PG8_LDB(B0, 1, 0); PG8_LDB(B1, 1, 1); PG8_SCHED; PG8_LDA(At, 1, 0); PG8_STAGE(PG8_SA(0, 1), a2 + hstep, voffA);
;             PG8_WAIT_V(8); PG8_WAIT_L(0); PG8_BAR; PG8_MMA(0, 0, At, B0); PG8_MMA(0, 1, At, B1); PG8_BAR; PG8_SCHED;
	s_add_u32 s24, s24, 0x40000
	s_addc_u32 s25, s25, 0
	s_mov_b32 m0, s38
	v_lshl_add_u64 v[226:227], s[24:25], 0, v[136:137]
	ds_read_b128 v[186:189], v151 offset:32768
	ds_read_b128 v[190:193], v151 offset:33792
	ds_read_b128 v[194:197], v151 offset:34816
	ds_read_b128 v[198:201], v151 offset:35840
	ds_read_b128 v[202:205], v151 offset:36864
	ds_read_b128 v[206:209], v151 offset:37888
	ds_read_b128 v[210:213], v151 offset:38912
	ds_read_b128 v[214:217], v151 offset:39936
	global_load_lds_dwordx4 v[226:227], off
	v_lshl_add_u64 v[226:227], s[24:25], 0, v[132:133]
	s_mov_b32 m0, s39
	s_nop 0
	global_load_lds_dwordx4 v[226:227], off
	s_waitcnt vmcnt(8)
	s_waitcnt lgkmcnt(0)
	s_barrier
	s_setprio 1
	s_waitcnt lgkmcnt(0)
	v_mfma_f32_16x16x32_bf16 v[126:129], v[152:155], v[186:189], v[126:129]
	v_mfma_f32_16x16x32_bf16 v[122:125], v[160:163], v[186:189], v[122:125]
	v_mfma_f32_16x16x32_bf16 v[110:113], v[152:155], v[194:197], v[110:113]
	v_mfma_f32_16x16x32_bf16 v[106:109], v[160:163], v[194:197], v[106:109]
	v_mfma_f32_16x16x32_bf16 v[94:97], v[152:155], v[202:205], v[94:97]
	v_mfma_f32_16x16x32_bf16 v[90:93], v[160:163], v[202:205], v[90:93]
	v_mfma_f32_16x16x32_bf16 v[78:81], v[152:155], v[210:213], v[78:81]
	v_mfma_f32_16x16x32_bf16 v[74:77], v[160:163], v[210:213], v[74:77]
	v_mfma_f32_16x16x32_bf16 v[126:129], v[156:159], v[190:193], v[126:129]
	v_mfma_f32_16x16x32_bf16 v[122:125], v[164:167], v[190:193], v[122:125]
	v_mfma_f32_16x16x32_bf16 v[110:113], v[156:159], v[198:201], v[110:113]
	v_mfma_f32_16x16x32_bf16 v[106:109], v[164:167], v[198:201], v[106:109]
	v_mfma_f32_16x16x32_bf16 v[94:97], v[156:159], v[206:209], v[94:97]
	v_mfma_f32_16x16x32_bf16 v[90:93], v[164:167], v[206:209], v[90:93]
	v_mfma_f32_16x16x32_bf16 v[78:81], v[156:159], v[214:217], v[78:81]
	v_mfma_f32_16x16x32_bf16 v[74:77], v[164:167], v[214:217], v[74:77]
	s_setprio 0
	s_setprio 1
	v_mfma_f32_16x16x32_bf16 v[118:121], v[168:171], v[186:189], v[118:121]
	v_mfma_f32_16x16x32_bf16 v[114:117], v[178:181], v[186:189], v[114:117]
	v_mfma_f32_16x16x32_bf16 v[102:105], v[168:171], v[194:197], v[102:105]
	v_mfma_f32_16x16x32_bf16 v[98:101], v[178:181], v[194:197], v[98:101]
	v_mfma_f32_16x16x32_bf16 v[86:89], v[168:171], v[202:205], v[86:89]
	v_mfma_f32_16x16x32_bf16 v[82:85], v[178:181], v[202:205], v[82:85]
	v_mfma_f32_16x16x32_bf16 v[70:73], v[168:171], v[210:213], v[70:73]
	v_mfma_f32_16x16x32_bf16 v[66:69], v[178:181], v[210:213], v[66:69]
	v_mfma_f32_16x16x32_bf16 v[118:121], v[174:177], v[190:193], v[118:121]
	v_mfma_f32_16x16x32_bf16 v[114:117], v[182:185], v[190:193], v[114:117]
	v_mfma_f32_16x16x32_bf16 v[102:105], v[174:177], v[198:201], v[102:105]
	v_mfma_f32_16x16x32_bf16 v[98:101], v[182:185], v[198:201], v[98:101]
	v_mfma_f32_16x16x32_bf16 v[86:89], v[174:177], v[206:209], v[86:89]
	v_mfma_f32_16x16x32_bf16 v[82:85], v[182:185], v[206:209], v[82:85]
	v_mfma_f32_16x16x32_bf16 v[70:73], v[174:177], v[214:217], v[70:73]
	v_mfma_f32_16x16x32_bf16 v[66:69], v[182:185], v[214:217], v[66:69]
	s_setprio 0
	s_barrier

; #define PG8_STAGE(bufoff, gbase, voff) do { _Pragma("unroll") for (int _i = 0; _i < 2; ++_i) \
;         __builtin_amdgcn_global_load_lds((const unsigned*)((const char*)(gbase) + (voff)[_i]), (PG8_LAS unsigned*)(lds + (bufoff) + ldsw + _i * 8192), 16, 0, 0); } while (0)
; #define PG8_LDA(dst, b, h) do { _Pragma("unroll") for (int m = 0; m < 4; ++m) _Pragma("unroll") for (int k = 0; k < 2; ++k) dst[m][k] = *(const PG8_LAS bf16x8*)(lds + PG8_SA(b, h) + aoff + m * 2048 + k * 1024); } while (0)
; #define PG8_MMA(ai, bj, At, Bt) do { __builtin_amdgcn_s_setprio(1); _Pragma("unroll") for (int m = 0; m < 4; ++m) _Pragma("unroll") for (int n = 0; n < 2; ++n) _Pragma("unroll") for (int k = 0; k < 2; ++k) \
;         acc[ai][bj][m][n] = __builtin_amdgcn_mfma_f32_16x16x32_bf16(Bt[n][k], At[m][k], acc[ai][bj][m][n], 0, 0, 0); __builtin_amdgcn_s_setprio(0); } while (0)
; #define PG8_WAIT_V(n) asm volatile("s_waitcnt vmcnt(" #n ")" ::: "memory")
; #define PG8_WAIT_L(n) asm volatile("s_waitcnt lgkmcnt(" #n ")" ::: "memory")
; #define PG8_BAR __builtin_amdgcn_s_barrier()
; #define PG8_SCHED __builtin_amdgcn_sched_barrier(0)
; template <class Epi, class Sched, bool ALIGN_EPI = false, bool SP2 = false>
; __device__ __forceinline__ void gemm_phase(PG8_LAS unsigned char* lds, const Gemm g, const Sched& S, const Epi& E) {
;     ...
;             PG8_LDA(At, 1, 1); PG8_STAGE(PG8_SB(1, 0), b3, voffB); PG8_STAGE(PG8_SB(1, 1), b3 + hstep, voffB); PG8_STAGE(PG8_SA(1, 0), a3, voffA);
;             PG8_WAIT_V(8); PG8_WAIT_L(0); PG8_BAR; PG8_MMA(1, 0, At, B0); PG8_MMA(1, 1, At, B1); PG8_BAR; PG8_SCHED;
	s_add_i32 s24, s57, s30
	v_lshl_add_u64 v[218:219], v[218:219], 0, s[6:7]
	s_mov_b32 m0, s24
	ds_read_b128 v[186:189], v151 offset:49152
	ds_read_b128 v[190:193], v151 offset:50176
	ds_read_b128 v[194:197], v151 offset:51200
	ds_read_b128 v[198:201], v151 offset:52224
	ds_read_b128 v[202:205], v151 offset:53248
	ds_read_b128 v[206:209], v151 offset:54272
	ds_read_b128 v[210:213], v151 offset:55296
	ds_read_b128 v[214:217], v151 offset:56320
	global_load_lds_dwordx4 v[218:219], off
	s_add_i32 m0, s24, 0x2000
	s_add_u32 s22, s22, 0x40080
	v_lshl_add_u64 v[218:219], v[220:221], 0, s[6:7]
	s_addc_u32 s23, s23, 0
	s_add_i32 s24, s58, s30
	global_load_lds_dwordx4 v[218:219], off
	v_lshl_add_u64 v[218:219], s[22:23], 0, v[134:135]
	s_mov_b32 m0, s24
	s_nop 0
	global_load_lds_dwordx4 v[218:219], off
	v_lshl_add_u64 v[218:219], s[22:23], 0, v[130:131]
	s_add_i32 m0, s24, 0x2000
	s_nop 0
	global_load_lds_dwordx4 v[218:219], off
	v_lshl_add_u64 v[218:219], v[222:223], 0, s[6:7]
	s_mov_b32 m0, s41
	s_nop 0
	global_load_lds_dwordx4 v[218:219], off
	v_lshl_add_u64 v[218:219], v[224:225], 0, s[6:7]
	s_mov_b32 m0, s42
	s_nop 0
	global_load_lds_dwordx4 v[218:219], off
	s_waitcnt vmcnt(8)
	s_waitcnt lgkmcnt(0)
	s_barrier
	s_setprio 1
	s_waitcnt lgkmcnt(0)
	v_mfma_f32_16x16x32_bf16 v[62:65], v[152:155], v[186:189], v[62:65]
	v_mfma_f32_16x16x32_bf16 v[58:61], v[160:163], v[186:189], v[58:61]
	v_mfma_f32_16x16x32_bf16 v[46:49], v[152:155], v[194:197], v[46:49]
	v_mfma_f32_16x16x32_bf16 v[42:45], v[160:163], v[194:197], v[42:45]
	v_mfma_f32_16x16x32_bf16 v[30:33], v[152:155], v[202:205], v[30:33]
	v_mfma_f32_16x16x32_bf16 v[26:29], v[160:163], v[202:205], v[26:29]
	v_mfma_f32_16x16x32_bf16 v[14:17], v[152:155], v[210:213], v[14:17]
	v_mfma_f32_16x16x32_bf16 v[10:13], v[160:163], v[210:213], v[10:13]
	v_mfma_f32_16x16x32_bf16 v[62:65], v[156:159], v[190:193], v[62:65]
	v_mfma_f32_16x16x32_bf16 v[58:61], v[164:167], v[190:193], v[58:61]
	v_mfma_f32_16x16x32_bf16 v[46:49], v[156:159], v[198:201], v[46:49]
	v_mfma_f32_16x16x32_bf16 v[42:45], v[164:167], v[198:201], v[42:45]
	v_mfma_f32_16x16x32_bf16 v[30:33], v[156:159], v[206:209], v[30:33]
	v_mfma_f32_16x16x32_bf16 v[26:29], v[164:167], v[206:209], v[26:29]
	v_mfma_f32_16x16x32_bf16 v[14:17], v[156:159], v[214:217], v[14:17]
	v_mfma_f32_16x16x32_bf16 v[10:13], v[164:167], v[214:217], v[10:13]
	s_setprio 0
	s_setprio 1
	v_mfma_f32_16x16x32_bf16 v[54:57], v[168:171], v[186:189], v[54:57]
	v_mfma_f32_16x16x32_bf16 v[50:53], v[178:181], v[186:189], v[50:53]
	v_mfma_f32_16x16x32_bf16 v[38:41], v[168:171], v[194:197], v[38:41]
	v_mfma_f32_16x16x32_bf16 v[34:37], v[178:181], v[194:197], v[34:37]
	v_mfma_f32_16x16x32_bf16 v[22:25], v[168:171], v[202:205], v[22:25]
	v_mfma_f32_16x16x32_bf16 v[18:21], v[178:181], v[202:205], v[18:21]
	v_mfma_f32_16x16x32_bf16 v[6:9], v[168:171], v[210:213], v[6:9]
	v_mfma_f32_16x16x32_bf16 v[2:5], v[178:181], v[210:213], v[2:5]
	v_mfma_f32_16x16x32_bf16 v[54:57], v[174:177], v[190:193], v[54:57]
	v_mfma_f32_16x16x32_bf16 v[50:53], v[182:185], v[190:193], v[50:53]
	v_mfma_f32_16x16x32_bf16 v[38:41], v[174:177], v[198:201], v[38:41]
	v_mfma_f32_16x16x32_bf16 v[34:37], v[182:185], v[198:201], v[34:37]
	v_mfma_f32_16x16x32_bf16 v[22:25], v[174:177], v[206:209], v[22:25]
	v_mfma_f32_16x16x32_bf16 v[18:21], v[182:185], v[206:209], v[18:21]
	v_mfma_f32_16x16x32_bf16 v[6:9], v[174:177], v[214:217], v[6:9]
	v_mfma_f32_16x16x32_bf16 v[2:5], v[182:185], v[214:217], v[2:5]
	s_setprio 0
	s_barrier

; template <class Epi, class Sched, bool ALIGN_EPI = false, bool SP2 = false>
; __device__ __forceinline__ void gemm_phase(PG8_LAS unsigned char* lds, const Gemm g, const Sched& S, const Epi& E) {
;     ...
;         for (int t = 0; t < nt; t += 2) {
;             const bool last = (t == nt - 2);
;             const char* a1 = cA + (size_t)(t + 1) * kstep;
;             const char* a2 = last ? nA : cA + (size_t)(t + 2) * kstep; const char* b2 = last ? nB : cB + (size_t)(t + 2) * kstep;
;             const char* a3 = a2 + kstep; const char* b3 = b2 + kstep;
	s_add_i32 s56, s56, 2
	s_add_u32 s20, s20, 0x100
	s_addc_u32 s21, s21, 0
	s_add_u32 s54, s54, 0x100
	s_addc_u32 s55, s55, 0

; #define PG8_STAGE(bufoff, gbase, voff) do { _Pragma("unroll") for (int _i = 0; _i < 2; ++_i) \
;         __builtin_amdgcn_global_load_lds((const unsigned*)((const char*)(gbase) + (voff)[_i]), (PG8_LAS unsigned*)(lds + (bufoff) + ldsw + _i * 8192), 16, 0, 0); } while (0)
; #define PG8_LDA(dst, b, h) do { _Pragma("unroll") for (int m = 0; m < 4; ++m) _Pragma("unroll") for (int k = 0; k < 2; ++k) dst[m][k] = *(const PG8_LAS bf16x8*)(lds + PG8_SA(b, h) + aoff + m * 2048 + k * 1024); } while (0)
; #define PG8_LDB(dst, b, h) do { _Pragma("unroll") for (int n = 0; n < 2; ++n) _Pragma("unroll") for (int k = 0; k < 2; ++k) dst[n][k] = *(const PG8_LAS bf16x8*)(lds + PG8_SB(b, h) + boff + n * 2048 + k * 1024); } while (0)
; #define PG8_SCHED __builtin_amdgcn_sched_barrier(0)
; template <class Epi, class Sched, bool ALIGN_EPI = false, bool SP2 = false>
; __device__ __forceinline__ void gemm_phase(PG8_LAS unsigned char* lds, const Gemm g, const Sched& S, const Epi& E) {
;     ...
;         const bool has_next = S.next(ui + 1, nxt);
;         const char* nA = has_next ? (const char*)g.A + (size_t)nxt.pm * tstep : cA; const char* nB = has_next ? (const char*)g.Bt + (size_t)nxt.pn * tstep : cB;
; #pragma nounroll
;         for (int t = 0; t < nt; t += 2) {
;             const bool last = (t == nt - 2);
;             const char* a1 = cA + (size_t)(t + 1) * kstep;
;             const char* a2 = last ? nA : cA + (size_t)(t + 2) * kstep; const char* b2 = last ? nB : cB + (size_t)(t + 2) * kstep;
;             const char* a3 = a2 + kstep; const char* b3 = b2 + kstep;
;             if (last && has_next) S.a_ready(nxt);
;             if constexpr (SP2) {
;             PG8_LDB(B0, 0, 0); PG8_LDB(B1, 0, 1); PG8_SCHED; PG8_LDA(At, 0, 0); PG8_STAGE(PG8_SA(1, 1), a1 + hstep, voffA);
;     ...
; #pragma unroll
;         for (int a = 0; a < 2; ++a)
; #pragma unroll
;             for (int b = 0; b < 2; ++b)
; #pragma unroll
;                 for (int m = 0; m < 4; ++m)
; #pragma unroll
;                     for (int n = 0; n < 2; ++n) acc[a][b][m][n] = (f32x4){0.f, 0.f, 0.f, 0.f};
;         cur = nxt; cA = nA; cB = nB; ++ui;
.LBB0_1687:
	s_add_u32 s22, s22, 0xb0080
	s_addc_u32 s23, s23, 0
	s_add_u32 s60, s24, 0x100
	v_mov_b32_e32 v2, 0
	s_addc_u32 s61, s25, 0
	s_mov_b32 s62, -2
	v_mov_b32_e32 v3, v2
	v_mov_b32_e32 v4, v2
	v_mov_b32_e32 v5, v2
	v_mov_b32_e32 v6, v2
	v_mov_b32_e32 v7, v2
	v_mov_b32_e32 v8, v2
	v_mov_b32_e32 v9, v2
	v_mov_b32_e32 v10, v2
	v_mov_b32_e32 v11, v2
	v_mov_b32_e32 v12, v2
	v_mov_b32_e32 v13, v2
	v_mov_b32_e32 v18, v2
	v_mov_b32_e32 v19, v2
	v_mov_b32_e32 v20, v2
	v_mov_b32_e32 v21, v2
	v_mov_b32_e32 v26, v2
	v_mov_b32_e32 v27, v2
	v_mov_b32_e32 v28, v2
	v_mov_b32_e32 v29, v2
	v_mov_b32_e32 v34, v2
	v_mov_b32_e32 v35, v2
	v_mov_b32_e32 v36, v2
	v_mov_b32_e32 v37, v2
	v_mov_b32_e32 v42, v2
	v_mov_b32_e32 v43, v2
	v_mov_b32_e32 v44, v2
	v_mov_b32_e32 v45, v2
	v_mov_b32_e32 v50, v2
	v_mov_b32_e32 v51, v2
	v_mov_b32_e32 v52, v2
	v_mov_b32_e32 v53, v2
	v_mov_b32_e32 v14, v2
	v_mov_b32_e32 v15, v2
	v_mov_b32_e32 v16, v2
	v_mov_b32_e32 v17, v2
	v_mov_b32_e32 v22, v2
	v_mov_b32_e32 v23, v2
	v_mov_b32_e32 v24, v2
	v_mov_b32_e32 v25, v2
	v_mov_b32_e32 v30, v2
	v_mov_b32_e32 v31, v2
	v_mov_b32_e32 v32, v2
	v_mov_b32_e32 v33, v2
	v_mov_b32_e32 v38, v2
	v_mov_b32_e32 v39, v2
	v_mov_b32_e32 v40, v2
	v_mov_b32_e32 v41, v2
	v_mov_b32_e32 v46, v2
	v_mov_b32_e32 v47, v2
	v_mov_b32_e32 v48, v2
	v_mov_b32_e32 v49, v2
	v_mov_b32_e32 v54, v2
	v_mov_b32_e32 v55, v2
	v_mov_b32_e32 v56, v2
	v_mov_b32_e32 v57, v2
	v_mov_b32_e32 v58, v2
	v_mov_b32_e32 v59, v2
	v_mov_b32_e32 v60, v2
	v_mov_b32_e32 v61, v2
	v_mov_b32_e32 v62, v2
	v_mov_b32_e32 v63, v2
	v_mov_b32_e32 v64, v2
	v_mov_b32_e32 v65, v2
	v_mov_b32_e32 v66, v2
	v_mov_b32_e32 v67, v2
	v_mov_b32_e32 v68, v2
	v_mov_b32_e32 v69, v2
	v_mov_b32_e32 v70, v2
	v_mov_b32_e32 v71, v2
	v_mov_b32_e32 v72, v2
	v_mov_b32_e32 v73, v2
	v_mov_b32_e32 v74, v2
	v_mov_b32_e32 v75, v2
	v_mov_b32_e32 v76, v2
	v_mov_b32_e32 v77, v2
	v_mov_b32_e32 v82, v2
	v_mov_b32_e32 v83, v2
	v_mov_b32_e32 v84, v2
	v_mov_b32_e32 v85, v2
	v_mov_b32_e32 v90, v2
	v_mov_b32_e32 v91, v2
	v_mov_b32_e32 v92, v2
	v_mov_b32_e32 v93, v2
	v_mov_b32_e32 v98, v2
	v_mov_b32_e32 v99, v2
	v_mov_b32_e32 v100, v2
	v_mov_b32_e32 v101, v2
	v_mov_b32_e32 v106, v2
	v_mov_b32_e32 v107, v2
	v_mov_b32_e32 v108, v2
	v_mov_b32_e32 v109, v2
	v_mov_b32_e32 v114, v2
	v_mov_b32_e32 v115, v2
	v_mov_b32_e32 v116, v2
	v_mov_b32_e32 v117, v2
	v_mov_b32_e32 v78, v2
	v_mov_b32_e32 v79, v2
	v_mov_b32_e32 v80, v2
	v_mov_b32_e32 v81, v2
	v_mov_b32_e32 v86, v2
	v_mov_b32_e32 v87, v2
	v_mov_b32_e32 v88, v2
	v_mov_b32_e32 v89, v2
	v_mov_b32_e32 v94, v2
	v_mov_b32_e32 v95, v2
	v_mov_b32_e32 v96, v2
	v_mov_b32_e32 v97, v2
	v_mov_b32_e32 v102, v2
	v_mov_b32_e32 v103, v2
	v_mov_b32_e32 v104, v2
	v_mov_b32_e32 v105, v2
	v_mov_b32_e32 v110, v2
	v_mov_b32_e32 v111, v2
	v_mov_b32_e32 v112, v2
	v_mov_b32_e32 v113, v2
	v_mov_b32_e32 v118, v2
	v_mov_b32_e32 v119, v2
	v_mov_b32_e32 v120, v2
	v_mov_b32_e32 v121, v2
	v_mov_b32_e32 v122, v2
	v_mov_b32_e32 v123, v2
	v_mov_b32_e32 v124, v2
	v_mov_b32_e32 v125, v2
	v_mov_b32_e32 v126, v2
	v_mov_b32_e32 v127, v2
	v_mov_b32_e32 v128, v2
	v_mov_b32_e32 v129, v2
	ds_read_b128 v[154:157], v150
	ds_read_b128 v[158:161], v150 offset:1024
	ds_read_b128 v[162:165], v150 offset:2048
	ds_read_b128 v[166:169], v150 offset:3072
	ds_read_b128 v[174:177], v151
	ds_read_b128 v[178:181], v151 offset:1024
	ds_read_b128 v[182:185], v151 offset:2048
	ds_read_b128 v[186:189], v151 offset:3072
	s_add_u32 s24, s22, 0xfff50080
	s_addc_u32 s25, s23, -1
	s_cmp_eq_u32 s62, 40
	s_cselect_b32 s27, s5, s25
	s_cselect_b32 s26, s4, s24
	s_cselect_b32 s25, s21, s61
	s_cselect_b32 s24, s20, s60

; #define PG8_STAGE(bufoff, gbase, voff) do { _Pragma("unroll") for (int _i = 0; _i < 2; ++_i) \
;         __builtin_amdgcn_global_load_lds((const unsigned*)((const char*)(gbase) + (voff)[_i]), (PG8_LAS unsigned*)(lds + (bufoff) + ldsw + _i * 8192), 16, 0, 0); } while (0)
; #define PG8_LDA(dst, b, h) do { _Pragma("unroll") for (int m = 0; m < 4; ++m) _Pragma("unroll") for (int k = 0; k < 2; ++k) dst[m][k] = *(const PG8_LAS bf16x8*)(lds + PG8_SA(b, h) + aoff + m * 2048 + k * 1024); } while (0)
; #define PG8_LDB(dst, b, h) do { _Pragma("unroll") for (int n = 0; n < 2; ++n) _Pragma("unroll") for (int k = 0; k < 2; ++k) dst[n][k] = *(const PG8_LAS bf16x8*)(lds + PG8_SB(b, h) + boff + n * 2048 + k * 1024); } while (0)
; #define PG8_MMA(ai, bj, At, Bt) do { __builtin_amdgcn_s_setprio(1); _Pragma("unroll") for (int m = 0; m < 4; ++m) _Pragma("unroll") for (int n = 0; n < 2; ++n) _Pragma("unroll") for (int k = 0; k < 2; ++k) \
;         acc[ai][bj][m][n] = __builtin_amdgcn_mfma_f32_16x16x32_bf16(Bt[n][k], At[m][k], acc[ai][bj][m][n], 0, 0, 0); __builtin_amdgcn_s_setprio(0); } while (0)
; #define PG8_WAIT_V(n) asm volatile("s_waitcnt vmcnt(" #n ")" ::: "memory")
; #define PG8_WAIT_L(n) asm volatile("s_waitcnt lgkmcnt(" #n ")" ::: "memory")
; #define PG8_BAR __builtin_amdgcn_s_barrier()
; #define PG8_SCHED __builtin_amdgcn_sched_barrier(0)
; template <class Epi, class Sched, bool ALIGN_EPI = false, bool SP2 = false>
; __device__ __forceinline__ void gemm_phase(PG8_LAS unsigned char* lds, const Gemm g, const Sched& S, const Epi& E) {
;     ...
;             PG8_LDB(B0, 0, 0); PG8_LDB(B1, 0, 1); PG8_SCHED; PG8_LDA(At, 0, 0); PG8_STAGE(PG8_SA(1, 1), a1 + hstep, voffA);
;             PG8_WAIT_V(8); PG8_WAIT_L(0); PG8_BAR; PG8_MMA(0, 0, At, B0); PG8_MMA(0, 1, At, B1); PG8_BAR; PG8_SCHED;
	v_lshl_add_u64 v[146:147], s[22:23], 0, v[138:139]
	s_add_i32 m0, s35, 0xc000
	ds_read_b128 v[190:193], v152
	ds_read_b128 v[194:197], v152 offset:1024
	ds_read_b128 v[198:201], v152 offset:2048
	ds_read_b128 v[202:205], v152 offset:3072
	ds_read_b128 v[206:209], v152 offset:4096
	ds_read_b128 v[210:213], v152 offset:5120
	ds_read_b128 v[214:217], v152 offset:6144
	ds_read_b128 v[218:221], v152 offset:7168
	global_load_lds_dwordx4 v[146:147], off
	v_lshl_add_u64 v[146:147], s[22:23], 0, v[140:141]
	s_add_i32 m0, s35, 0xe000
	s_nop 0
	global_load_lds_dwordx4 v[146:147], off
	s_waitcnt vmcnt(24)
	s_waitcnt lgkmcnt(0)
	s_barrier
	s_setprio 1
	s_waitcnt lgkmcnt(0)
	v_mfma_f32_16x16x32_bf16 v[126:129], v[154:157], v[190:193], v[126:129]
	v_mfma_f32_16x16x32_bf16 v[122:125], v[162:165], v[190:193], v[122:125]
	v_mfma_f32_16x16x32_bf16 v[118:121], v[154:157], v[198:201], v[118:121]
	v_mfma_f32_16x16x32_bf16 v[110:113], v[162:165], v[198:201], v[110:113]
	v_mfma_f32_16x16x32_bf16 v[102:105], v[154:157], v[206:209], v[102:105]
	v_mfma_f32_16x16x32_bf16 v[94:97], v[162:165], v[206:209], v[94:97]
	v_mfma_f32_16x16x32_bf16 v[86:89], v[154:157], v[214:217], v[86:89]
	v_mfma_f32_16x16x32_bf16 v[78:81], v[162:165], v[214:217], v[78:81]
	v_mfma_f32_16x16x32_bf16 v[126:129], v[158:161], v[194:197], v[126:129]
	v_mfma_f32_16x16x32_bf16 v[122:125], v[166:169], v[194:197], v[122:125]
	v_mfma_f32_16x16x32_bf16 v[118:121], v[158:161], v[202:205], v[118:121]
	v_mfma_f32_16x16x32_bf16 v[110:113], v[166:169], v[202:205], v[110:113]
	v_mfma_f32_16x16x32_bf16 v[102:105], v[158:161], v[210:213], v[102:105]
	v_mfma_f32_16x16x32_bf16 v[94:97], v[166:169], v[210:213], v[94:97]
	v_mfma_f32_16x16x32_bf16 v[86:89], v[158:161], v[218:221], v[86:89]
	v_mfma_f32_16x16x32_bf16 v[78:81], v[166:169], v[218:221], v[78:81]
	s_setprio 0
	s_setprio 1
	v_mfma_f32_16x16x32_bf16 v[114:117], v[174:177], v[190:193], v[114:117]
	v_mfma_f32_16x16x32_bf16 v[106:109], v[182:185], v[190:193], v[106:109]
	v_mfma_f32_16x16x32_bf16 v[98:101], v[174:177], v[198:201], v[98:101]
	v_mfma_f32_16x16x32_bf16 v[90:93], v[182:185], v[198:201], v[90:93]
	v_mfma_f32_16x16x32_bf16 v[82:85], v[174:177], v[206:209], v[82:85]
	v_mfma_f32_16x16x32_bf16 v[74:77], v[182:185], v[206:209], v[74:77]
	v_mfma_f32_16x16x32_bf16 v[70:73], v[174:177], v[214:217], v[70:73]
	v_mfma_f32_16x16x32_bf16 v[66:69], v[182:185], v[214:217], v[66:69]
	v_mfma_f32_16x16x32_bf16 v[114:117], v[178:181], v[194:197], v[114:117]
	v_mfma_f32_16x16x32_bf16 v[106:109], v[186:189], v[194:197], v[106:109]
	v_mfma_f32_16x16x32_bf16 v[98:101], v[178:181], v[202:205], v[98:101]
	v_mfma_f32_16x16x32_bf16 v[90:93], v[186:189], v[202:205], v[90:93]
	v_mfma_f32_16x16x32_bf16 v[82:85], v[178:181], v[210:213], v[82:85]
	v_mfma_f32_16x16x32_bf16 v[74:77], v[186:189], v[210:213], v[74:77]
	v_mfma_f32_16x16x32_bf16 v[70:73], v[178:181], v[218:221], v[70:73]
	v_mfma_f32_16x16x32_bf16 v[66:69], v[186:189], v[218:221], v[66:69]
	s_setprio 0
	s_barrier

; #define PG8_STAGE(bufoff, gbase, voff) do { _Pragma("unroll") for (int _i = 0; _i < 2; ++_i) \
;         __builtin_amdgcn_global_load_lds((const unsigned*)((const char*)(gbase) + (voff)[_i]), (PG8_LAS unsigned*)(lds + (bufoff) + ldsw + _i * 8192), 16, 0, 0); } while (0)
; #define PG8_LDA(dst, b, h) do { _Pragma("unroll") for (int m = 0; m < 4; ++m) _Pragma("unroll") for (int k = 0; k < 2; ++k) dst[m][k] = *(const PG8_LAS bf16x8*)(lds + PG8_SA(b, h) + aoff + m * 2048 + k * 1024); } while (0)
; #define PG8_MMA(ai, bj, At, Bt) do { __builtin_amdgcn_s_setprio(1); _Pragma("unroll") for (int m = 0; m < 4; ++m) _Pragma("unroll") for (int n = 0; n < 2; ++n) _Pragma("unroll") for (int k = 0; k < 2; ++k) \
;         acc[ai][bj][m][n] = __builtin_amdgcn_mfma_f32_16x16x32_bf16(Bt[n][k], At[m][k], acc[ai][bj][m][n], 0, 0, 0); __builtin_amdgcn_s_setprio(0); } while (0)
; #define PG8_WAIT_V(n) asm volatile("s_waitcnt vmcnt(" #n ")" ::: "memory")
; #define PG8_WAIT_L(n) asm volatile("s_waitcnt lgkmcnt(" #n ")" ::: "memory")
; #define PG8_BAR __builtin_amdgcn_s_barrier()
; #define PG8_SCHED __builtin_amdgcn_sched_barrier(0)
; template <class Epi, class Sched, bool ALIGN_EPI = false, bool SP2 = false>
; __device__ __forceinline__ void gemm_phase(PG8_LAS unsigned char* lds, const Gemm g, const Sched& S, const Epi& E) {
;     ...
;             PG8_LDA(At, 0, 1); PG8_STAGE(PG8_SB(0, 0), b2, voffB); PG8_STAGE(PG8_SB(0, 1), b2 + hstep, voffB); PG8_STAGE(PG8_SA(0, 0), a2, voffA);
;             PG8_WAIT_V(8); PG8_WAIT_L(0); PG8_BAR; PG8_MMA(1, 0, At, B0); PG8_MMA(1, 1, At, B1); PG8_BAR; PG8_SCHED;
	s_add_i32 s63, s48, s34
	v_lshl_add_u64 v[146:147], s[24:25], 0, v[132:133]
	s_mov_b32 m0, s63
	ds_read_b128 v[190:193], v152 offset:16384
	ds_read_b128 v[194:197], v152 offset:17408
	ds_read_b128 v[198:201], v152 offset:18432
	ds_read_b128 v[202:205], v152 offset:19456
	ds_read_b128 v[206:209], v152 offset:20480
	ds_read_b128 v[210:213], v152 offset:21504
	ds_read_b128 v[214:217], v152 offset:22528
	ds_read_b128 v[218:221], v152 offset:23552
	global_load_lds_dwordx4 v[146:147], off
	s_add_i32 m0, s63, 0x2000
	s_add_u32 s64, s24, 0xb0000
	v_lshl_add_u64 v[170:171], s[24:25], 0, v[136:137]
	s_addc_u32 s65, s25, 0
	s_add_i32 s63, s49, s34
	global_load_lds_dwordx4 v[170:171], off
	v_lshl_add_u64 v[222:223], s[64:65], 0, v[132:133]
	s_mov_b32 m0, s63
	v_lshl_add_u64 v[224:225], s[26:27], 0, v[134:135]
	global_load_lds_dwordx4 v[222:223], off
	v_lshl_add_u64 v[222:223], s[64:65], 0, v[136:137]
	s_add_i32 m0, s63, 0x2000
	s_nop 0
	global_load_lds_dwordx4 v[222:223], off
	v_lshl_add_u64 v[222:223], s[26:27], 0, v[130:131]
	s_mov_b32 m0, s35
	s_nop 0
	global_load_lds_dwordx4 v[222:223], off
	s_mov_b32 m0, s38
	s_nop 0
	global_load_lds_dwordx4 v[224:225], off
	s_waitcnt vmcnt(24)
	s_waitcnt lgkmcnt(0)
	s_barrier
	s_setprio 1
	s_waitcnt lgkmcnt(0)
	v_mfma_f32_16x16x32_bf16 v[62:65], v[154:157], v[190:193], v[62:65]
	v_mfma_f32_16x16x32_bf16 v[58:61], v[162:165], v[190:193], v[58:61]
	v_mfma_f32_16x16x32_bf16 v[54:57], v[154:157], v[198:201], v[54:57]
	v_mfma_f32_16x16x32_bf16 v[46:49], v[162:165], v[198:201], v[46:49]
	v_mfma_f32_16x16x32_bf16 v[38:41], v[154:157], v[206:209], v[38:41]
	v_mfma_f32_16x16x32_bf16 v[30:33], v[162:165], v[206:209], v[30:33]
	v_mfma_f32_16x16x32_bf16 v[22:25], v[154:157], v[214:217], v[22:25]
	v_mfma_f32_16x16x32_bf16 v[14:17], v[162:165], v[214:217], v[14:17]
	v_mfma_f32_16x16x32_bf16 v[62:65], v[158:161], v[194:197], v[62:65]
	v_mfma_f32_16x16x32_bf16 v[58:61], v[166:169], v[194:197], v[58:61]
	v_mfma_f32_16x16x32_bf16 v[54:57], v[158:161], v[202:205], v[54:57]
	v_mfma_f32_16x16x32_bf16 v[46:49], v[166:169], v[202:205], v[46:49]
	v_mfma_f32_16x16x32_bf16 v[38:41], v[158:161], v[210:213], v[38:41]
	v_mfma_f32_16x16x32_bf16 v[30:33], v[166:169], v[210:213], v[30:33]
	v_mfma_f32_16x16x32_bf16 v[22:25], v[158:161], v[218:221], v[22:25]
	v_mfma_f32_16x16x32_bf16 v[14:17], v[166:169], v[218:221], v[14:17]
	s_setprio 0
	s_setprio 1
	v_mfma_f32_16x16x32_bf16 v[50:53], v[174:177], v[190:193], v[50:53]
	v_mfma_f32_16x16x32_bf16 v[42:45], v[182:185], v[190:193], v[42:45]
	v_mfma_f32_16x16x32_bf16 v[34:37], v[174:177], v[198:201], v[34:37]
	v_mfma_f32_16x16x32_bf16 v[26:29], v[182:185], v[198:201], v[26:29]
	v_mfma_f32_16x16x32_bf16 v[18:21], v[174:177], v[206:209], v[18:21]
	v_mfma_f32_16x16x32_bf16 v[10:13], v[182:185], v[206:209], v[10:13]
	v_mfma_f32_16x16x32_bf16 v[6:9], v[174:177], v[214:217], v[6:9]
	v_mfma_f32_16x16x32_bf16 v[2:5], v[182:185], v[214:217], v[2:5]
	v_mfma_f32_16x16x32_bf16 v[50:53], v[178:181], v[194:197], v[50:53]
	v_mfma_f32_16x16x32_bf16 v[42:45], v[186:189], v[194:197], v[42:45]
	v_mfma_f32_16x16x32_bf16 v[34:37], v[178:181], v[202:205], v[34:37]
	v_mfma_f32_16x16x32_bf16 v[26:29], v[186:189], v[202:205], v[26:29]
	v_mfma_f32_16x16x32_bf16 v[18:21], v[178:181], v[210:213], v[18:21]
	v_mfma_f32_16x16x32_bf16 v[10:13], v[186:189], v[210:213], v[10:13]
	v_mfma_f32_16x16x32_bf16 v[6:9], v[178:181], v[218:221], v[6:9]
	v_mfma_f32_16x16x32_bf16 v[2:5], v[186:189], v[218:221], v[2:5]
	s_setprio 0
	s_barrier

; #define PG8_STAGE(bufoff, gbase, voff) do { _Pragma("unroll") for (int _i = 0; _i < 2; ++_i) \
;         __builtin_amdgcn_global_load_lds((const unsigned*)((const char*)(gbase) + (voff)[_i]), (PG8_LAS unsigned*)(lds + (bufoff) + ldsw + _i * 8192), 16, 0, 0); } while (0)
; #define PG8_LDA(dst, b, h) do { _Pragma("unroll") for (int m = 0; m < 4; ++m) _Pragma("unroll") for (int k = 0; k < 2; ++k) dst[m][k] = *(const PG8_LAS bf16x8*)(lds + PG8_SA(b, h) + aoff + m * 2048 + k * 1024); } while (0)
; #define PG8_LDB(dst, b, h) do { _Pragma("unroll") for (int n = 0; n < 2; ++n) _Pragma("unroll") for (int k = 0; k < 2; ++k) dst[n][k] = *(const PG8_LAS bf16x8*)(lds + PG8_SB(b, h) + boff + n * 2048 + k * 1024); } while (0)
; #define PG8_SCHED __builtin_amdgcn_sched_barrier(0)
; template <class Epi, class Sched, bool ALIGN_EPI = false, bool SP2 = false>
; __device__ __forceinline__ void gemm_phase(PG8_LAS unsigned char* lds, const Gemm g, const Sched& S, const Epi& E) {
;     ...
;             PG8_LDB(B0, 1, 0); PG8_LDB(B1, 1, 1); PG8_SCHED; PG8_LDA(At, 1, 0); PG8_STAGE(PG8_SA(0, 1), a2 + hstep, voffA);
	s_add_i32 s63, 0, 0x18000
	v_add_u32_e32 v153, s63, v148
	s_add_i32 s64, 0, 0x1c000
	ds_read_b128 v[154:157], v153
	ds_read_b128 v[158:161], v153 offset:1024
	ds_read_b128 v[162:165], v153 offset:2048
	ds_read_b128 v[166:169], v153 offset:3072
	v_add_u32_e32 v153, s64, v148
	ds_read_b128 v[174:177], v153
	ds_read_b128 v[178:181], v153 offset:1024
	ds_read_b128 v[182:185], v153 offset:2048
	ds_read_b128 v[186:189], v153 offset:3072

; #define PG8_STAGE(bufoff, gbase, voff) do { _Pragma("unroll") for (int _i = 0; _i < 2; ++_i) \
;         __builtin_amdgcn_global_load_lds((const unsigned*)((const char*)(gbase) + (voff)[_i]), (PG8_LAS unsigned*)(lds + (bufoff) + ldsw + _i * 8192), 16, 0, 0); } while (0)
; #define PG8_LDA(dst, b, h) do { _Pragma("unroll") for (int m = 0; m < 4; ++m) _Pragma("unroll") for (int k = 0; k < 2; ++k) dst[m][k] = *(const PG8_LAS bf16x8*)(lds + PG8_SA(b, h) + aoff + m * 2048 + k * 1024); } while (0)
; #define PG8_LDB(dst, b, h) do { _Pragma("unroll") for (int n = 0; n < 2; ++n) _Pragma("unroll") for (int k = 0; k < 2; ++k) dst[n][k] = *(const PG8_LAS bf16x8*)(lds + PG8_SB(b, h) + boff + n * 2048 + k * 1024); } while (0)
; #define PG8_MMA(ai, bj, At, Bt) do { __builtin_amdgcn_s_setprio(1); _Pragma("unroll") for (int m = 0; m < 4; ++m) _Pragma("unroll") for (int n = 0; n < 2; ++n) _Pragma("unroll") for (int k = 0; k < 2; ++k) \
;         acc[ai][bj][m][n] = __builtin_amdgcn_mfma_f32_16x16x32_bf16(Bt[n][k], At[m][k], acc[ai][bj][m][n], 0, 0, 0); __builtin_amdgcn_s_setprio(0); } while (0)
; #define PG8_WAIT_V(n) asm volatile("s_waitcnt vmcnt(" #n ")" ::: "memory")
; #define PG8_WAIT_L(n) asm volatile("s_waitcnt lgkmcnt(" #n ")" ::: "memory")
; #define PG8_BAR __builtin_amdgcn_s_barrier()
; #define PG8_SCHED __builtin_amdgcn_sched_barrier(0)
; template <class Epi, class Sched, bool ALIGN_EPI = false, bool SP2 = false>
; __device__ __forceinline__ void gemm_phase(PG8_LAS unsigned char* lds, const Gemm g, const Sched& S, const Epi& E) {
;     ...
;             PG8_LDB(B0, 1, 0); PG8_LDB(B1, 1, 1); PG8_SCHED; PG8_LDA(At, 1, 0); PG8_STAGE(PG8_SA(0, 1), a2 + hstep, voffA);
;             PG8_WAIT_V(8); PG8_WAIT_L(0); PG8_BAR; PG8_MMA(0, 0, At, B0); PG8_MMA(0, 1, At, B1); PG8_BAR; PG8_SCHED;
	s_add_u32 s26, s26, 0xb0000
	s_addc_u32 s27, s27, 0
	s_mov_b32 m0, s39
	v_lshl_add_u64 v[226:227], s[26:27], 0, v[130:131]
	ds_read_b128 v[190:193], v152 offset:32768
	ds_read_b128 v[194:197], v152 offset:33792
	ds_read_b128 v[198:201], v152 offset:34816
	ds_read_b128 v[202:205], v152 offset:35840
	ds_read_b128 v[206:209], v152 offset:36864
	ds_read_b128 v[210:213], v152 offset:37888
	ds_read_b128 v[214:217], v152 offset:38912
	ds_read_b128 v[218:221], v152 offset:39936
	global_load_lds_dwordx4 v[226:227], off
	v_lshl_add_u64 v[226:227], s[26:27], 0, v[134:135]
	s_mov_b32 m0, s40
	s_nop 0
	global_load_lds_dwordx4 v[226:227], off
	s_waitcnt vmcnt(8)
	s_waitcnt lgkmcnt(0)
	s_barrier
	s_setprio 1
	s_waitcnt lgkmcnt(0)
	v_mfma_f32_16x16x32_bf16 v[126:129], v[154:157], v[190:193], v[126:129]
	v_mfma_f32_16x16x32_bf16 v[122:125], v[162:165], v[190:193], v[122:125]
	v_mfma_f32_16x16x32_bf16 v[118:121], v[154:157], v[198:201], v[118:121]
	v_mfma_f32_16x16x32_bf16 v[110:113], v[162:165], v[198:201], v[110:113]
	v_mfma_f32_16x16x32_bf16 v[102:105], v[154:157], v[206:209], v[102:105]
	v_mfma_f32_16x16x32_bf16 v[94:97], v[162:165], v[206:209], v[94:97]
	v_mfma_f32_16x16x32_bf16 v[86:89], v[154:157], v[214:217], v[86:89]
	v_mfma_f32_16x16x32_bf16 v[78:81], v[162:165], v[214:217], v[78:81]
	v_mfma_f32_16x16x32_bf16 v[126:129], v[158:161], v[194:197], v[126:129]
	v_mfma_f32_16x16x32_bf16 v[122:125], v[166:169], v[194:197], v[122:125]
	v_mfma_f32_16x16x32_bf16 v[118:121], v[158:161], v[202:205], v[118:121]
	v_mfma_f32_16x16x32_bf16 v[110:113], v[166:169], v[202:205], v[110:113]
	v_mfma_f32_16x16x32_bf16 v[102:105], v[158:161], v[210:213], v[102:105]
	v_mfma_f32_16x16x32_bf16 v[94:97], v[166:169], v[210:213], v[94:97]
	v_mfma_f32_16x16x32_bf16 v[86:89], v[158:161], v[218:221], v[86:89]
	v_mfma_f32_16x16x32_bf16 v[78:81], v[166:169], v[218:221], v[78:81]
	s_setprio 0
	s_setprio 1
	v_mfma_f32_16x16x32_bf16 v[114:117], v[174:177], v[190:193], v[114:117]
	v_mfma_f32_16x16x32_bf16 v[106:109], v[182:185], v[190:193], v[106:109]
	v_mfma_f32_16x16x32_bf16 v[98:101], v[174:177], v[198:201], v[98:101]
	v_mfma_f32_16x16x32_bf16 v[90:93], v[182:185], v[198:201], v[90:93]
	v_mfma_f32_16x16x32_bf16 v[82:85], v[174:177], v[206:209], v[82:85]
	v_mfma_f32_16x16x32_bf16 v[74:77], v[182:185], v[206:209], v[74:77]
	v_mfma_f32_16x16x32_bf16 v[70:73], v[174:177], v[214:217], v[70:73]
	v_mfma_f32_16x16x32_bf16 v[66:69], v[182:185], v[214:217], v[66:69]
	v_mfma_f32_16x16x32_bf16 v[114:117], v[178:181], v[194:197], v[114:117]
	v_mfma_f32_16x16x32_bf16 v[106:109], v[186:189], v[194:197], v[106:109]
	v_mfma_f32_16x16x32_bf16 v[98:101], v[178:181], v[202:205], v[98:101]
	v_mfma_f32_16x16x32_bf16 v[90:93], v[186:189], v[202:205], v[90:93]
	v_mfma_f32_16x16x32_bf16 v[82:85], v[178:181], v[210:213], v[82:85]
	v_mfma_f32_16x16x32_bf16 v[74:77], v[186:189], v[210:213], v[74:77]
	v_mfma_f32_16x16x32_bf16 v[70:73], v[178:181], v[218:221], v[70:73]
	v_mfma_f32_16x16x32_bf16 v[66:69], v[186:189], v[218:221], v[66:69]
	s_setprio 0
	s_barrier

; #define PG8_STAGE(bufoff, gbase, voff) do { _Pragma("unroll") for (int _i = 0; _i < 2; ++_i) \
;         __builtin_amdgcn_global_load_lds((const unsigned*)((const char*)(gbase) + (voff)[_i]), (PG8_LAS unsigned*)(lds + (bufoff) + ldsw + _i * 8192), 16, 0, 0); } while (0)
; #define PG8_LDA(dst, b, h) do { _Pragma("unroll") for (int m = 0; m < 4; ++m) _Pragma("unroll") for (int k = 0; k < 2; ++k) dst[m][k] = *(const PG8_LAS bf16x8*)(lds + PG8_SA(b, h) + aoff + m * 2048 + k * 1024); } while (0)
; #define PG8_MMA(ai, bj, At, Bt) do { __builtin_amdgcn_s_setprio(1); _Pragma("unroll") for (int m = 0; m < 4; ++m) _Pragma("unroll") for (int n = 0; n < 2; ++n) _Pragma("unroll") for (int k = 0; k < 2; ++k) \
;         acc[ai][bj][m][n] = __builtin_amdgcn_mfma_f32_16x16x32_bf16(Bt[n][k], At[m][k], acc[ai][bj][m][n], 0, 0, 0); __builtin_amdgcn_s_setprio(0); } while (0)
; #define PG8_WAIT_V(n) asm volatile("s_waitcnt vmcnt(" #n ")" ::: "memory")
; #define PG8_WAIT_L(n) asm volatile("s_waitcnt lgkmcnt(" #n ")" ::: "memory")
; #define PG8_BAR __builtin_amdgcn_s_barrier()
; #define PG8_SCHED __builtin_amdgcn_sched_barrier(0)
; template <class Epi, class Sched, bool ALIGN_EPI = false, bool SP2 = false>
; __device__ __forceinline__ void gemm_phase(PG8_LAS unsigned char* lds, const Gemm g, const Sched& S, const Epi& E) {
;     ...
;             PG8_LDA(At, 1, 1); PG8_STAGE(PG8_SB(1, 0), b3, voffB); PG8_STAGE(PG8_SB(1, 1), b3 + hstep, voffB); PG8_STAGE(PG8_SA(1, 0), a3, voffA);
;             PG8_WAIT_V(8); PG8_WAIT_L(0); PG8_BAR; PG8_MMA(1, 0, At, B0); PG8_MMA(1, 1, At, B1); PG8_BAR; PG8_SCHED;
	s_add_i32 s26, s63, s34
	v_lshl_add_u64 v[146:147], v[146:147], 0, s[8:9]
	s_mov_b32 m0, s26
	ds_read_b128 v[190:193], v152 offset:49152
	ds_read_b128 v[194:197], v152 offset:50176
	ds_read_b128 v[198:201], v152 offset:51200
	ds_read_b128 v[202:205], v152 offset:52224
	ds_read_b128 v[206:209], v152 offset:53248
	ds_read_b128 v[210:213], v152 offset:54272
	ds_read_b128 v[214:217], v152 offset:55296
	ds_read_b128 v[218:221], v152 offset:56320
	global_load_lds_dwordx4 v[146:147], off
	s_add_i32 m0, s26, 0x2000
	s_add_u32 s24, s24, 0xb0080
	v_lshl_add_u64 v[146:147], v[170:171], 0, s[8:9]
	s_addc_u32 s25, s25, 0
	s_add_i32 s26, s64, s34
	global_load_lds_dwordx4 v[146:147], off
	v_lshl_add_u64 v[146:147], s[24:25], 0, v[132:133]
	s_mov_b32 m0, s26
	s_nop 0
	global_load_lds_dwordx4 v[146:147], off
	v_lshl_add_u64 v[146:147], s[24:25], 0, v[136:137]
	s_add_i32 m0, s26, 0x2000
	s_nop 0
	global_load_lds_dwordx4 v[146:147], off
	v_lshl_add_u64 v[146:147], v[222:223], 0, s[8:9]
	s_mov_b32 m0, s42
	s_nop 0
	global_load_lds_dwordx4 v[146:147], off
	v_lshl_add_u64 v[146:147], v[224:225], 0, s[8:9]
	s_mov_b32 m0, s43
	s_nop 0
	global_load_lds_dwordx4 v[146:147], off
	s_waitcnt vmcnt(8)
	s_waitcnt lgkmcnt(0)
	s_barrier
	s_setprio 1
	s_waitcnt lgkmcnt(0)
	v_mfma_f32_16x16x32_bf16 v[62:65], v[154:157], v[190:193], v[62:65]
	v_mfma_f32_16x16x32_bf16 v[58:61], v[162:165], v[190:193], v[58:61]
	v_mfma_f32_16x16x32_bf16 v[54:57], v[154:157], v[198:201], v[54:57]
	v_mfma_f32_16x16x32_bf16 v[46:49], v[162:165], v[198:201], v[46:49]
	v_mfma_f32_16x16x32_bf16 v[38:41], v[154:157], v[206:209], v[38:41]
	v_mfma_f32_16x16x32_bf16 v[30:33], v[162:165], v[206:209], v[30:33]
	v_mfma_f32_16x16x32_bf16 v[22:25], v[154:157], v[214:217], v[22:25]
	v_mfma_f32_16x16x32_bf16 v[14:17], v[162:165], v[214:217], v[14:17]
	v_mfma_f32_16x16x32_bf16 v[62:65], v[158:161], v[194:197], v[62:65]
	v_mfma_f32_16x16x32_bf16 v[58:61], v[166:169], v[194:197], v[58:61]
	v_mfma_f32_16x16x32_bf16 v[54:57], v[158:161], v[202:205], v[54:57]
	v_mfma_f32_16x16x32_bf16 v[46:49], v[166:169], v[202:205], v[46:49]
	v_mfma_f32_16x16x32_bf16 v[38:41], v[158:161], v[210:213], v[38:41]
	v_mfma_f32_16x16x32_bf16 v[30:33], v[166:169], v[210:213], v[30:33]
	v_mfma_f32_16x16x32_bf16 v[22:25], v[158:161], v[218:221], v[22:25]
	v_mfma_f32_16x16x32_bf16 v[14:17], v[166:169], v[218:221], v[14:17]
	s_setprio 0
	s_setprio 1
	v_mfma_f32_16x16x32_bf16 v[50:53], v[174:177], v[190:193], v[50:53]
	v_mfma_f32_16x16x32_bf16 v[42:45], v[182:185], v[190:193], v[42:45]
	v_mfma_f32_16x16x32_bf16 v[34:37], v[174:177], v[198:201], v[34:37]
	v_mfma_f32_16x16x32_bf16 v[26:29], v[182:185], v[198:201], v[26:29]
	v_mfma_f32_16x16x32_bf16 v[18:21], v[174:177], v[206:209], v[18:21]
	v_mfma_f32_16x16x32_bf16 v[10:13], v[182:185], v[206:209], v[10:13]
	v_mfma_f32_16x16x32_bf16 v[6:9], v[174:177], v[214:217], v[6:9]
	v_mfma_f32_16x16x32_bf16 v[2:5], v[182:185], v[214:217], v[2:5]
	v_mfma_f32_16x16x32_bf16 v[50:53], v[178:181], v[194:197], v[50:53]
	v_mfma_f32_16x16x32_bf16 v[42:45], v[186:189], v[194:197], v[42:45]
	v_mfma_f32_16x16x32_bf16 v[34:37], v[178:181], v[202:205], v[34:37]
	v_mfma_f32_16x16x32_bf16 v[26:29], v[186:189], v[202:205], v[26:29]
	v_mfma_f32_16x16x32_bf16 v[18:21], v[178:181], v[210:213], v[18:21]
	v_mfma_f32_16x16x32_bf16 v[10:13], v[186:189], v[210:213], v[10:13]
	v_mfma_f32_16x16x32_bf16 v[6:9], v[178:181], v[218:221], v[6:9]
	v_mfma_f32_16x16x32_bf16 v[2:5], v[186:189], v[218:221], v[2:5]
	s_setprio 0
	s_barrier

; template <class Epi, class Sched, bool ALIGN_EPI = false, bool SP2 = false>
; __device__ __forceinline__ void gemm_phase(PG8_LAS unsigned char* lds, const Gemm g, const Sched& S, const Epi& E) {
;     ...
;         for (int t = 0; t < nt; t += 2) {
;             const bool last = (t == nt - 2);
;             const char* a1 = cA + (size_t)(t + 1) * kstep;
;             const char* a2 = last ? nA : cA + (size_t)(t + 2) * kstep; const char* b2 = last ? nB : cB + (size_t)(t + 2) * kstep;
;             const char* a3 = a2 + kstep; const char* b3 = b2 + kstep;
	s_add_i32 s62, s62, 2
	s_add_u32 s22, s22, 0x100
	s_addc_u32 s23, s23, 0
	s_add_u32 s60, s60, 0x100
	s_addc_u32 s61, s61, 0
